# grid barrier: non-leader workgroups poll the cross-XCD release generation directly instead of waiting for their XCD leader's relay (same generation value); out-proj fusion kept
# speedup vs baseline: 1.0627x; 1.0055x over previous
.LBB0_384:
	s_or_b64 exec, exec, s[4:5]
	v_cvt_f32_u32_e32 v5, v3
	s_waitcnt vmcnt(0)
	v_readfirstlane_b32 s2, v4
	v_sub_u32_e32 v4, 0, v3
	v_rcp_iflag_f32_e32 v5, v5
	v_add_u32_e32 v6, s2, v2
	v_mul_f32_e32 v5, 0x4f7ffffe, v5
	v_cvt_u32_f32_e32 v5, v5
	v_mul_lo_u32 v2, v4, v5
	v_mul_hi_u32 v2, v5, v2
	v_add_u32_e32 v2, v5, v2
	v_mul_hi_u32 v2, v6, v2
	v_mul_lo_u32 v4, v2, v3
	v_sub_u32_e32 v4, v6, v4
	v_add_u32_e32 v5, 1, v2
	v_cmp_ge_u32_e32 vcc, v4, v3
	s_nop 1
	v_cndmask_b32_e32 v2, v2, v5, vcc
	v_sub_u32_e32 v5, v4, v3
	v_cndmask_b32_e32 v4, v4, v5, vcc
	v_add_u32_e32 v5, 1, v2
	v_cmp_ge_u32_e32 vcc, v4, v3
	v_add_u32_e32 v4, 1, v6
	s_nop 0
	v_cndmask_b32_e32 v2, v2, v5, vcc
	v_mul_lo_u32 v5, v3, v2
	v_add_u32_e32 v3, v5, v3
	v_cmp_ne_u32_e32 vcc, v4, v3
	s_and_saveexec_b64 s[2:3], vcc
	s_xor_b64 s[2:3], exec, s[2:3]
	s_cbranch_execz .LBB0_398
	s_add_i32 s4, s20, 0x900
	s_mov_b32 s5, 0
	s_lshl_b64 s[4:5], s[4:5], 2
	s_add_u32 s8, s62, 0xf71d500
	s_addc_u32 s9, s63, 0
	s_waitcnt lgkmcnt(0)
	v_mov_b32_e32 v1, 0
	global_load_dword v3, v1, s[8:9] sc1
	s_waitcnt vmcnt(0)
	v_cmp_eq_u32_e32 vcc, v3, v2
	s_and_saveexec_b64 s[4:5], vcc
	s_cbranch_execz .LBB0_397
	s_add_u32 s6, s62, 0xf71a200
	s_addc_u32 s7, s63, 0
	s_mov_b32 s21, 1
	s_mov_b64 s[10:11], 0
	s_branch .LBB0_388

.LBB0_644:
	s_or_b64 exec, exec, s[4:5]
	v_cvt_f32_u32_e32 v5, v3
	s_waitcnt vmcnt(0)
	v_readfirstlane_b32 s2, v4
	v_sub_u32_e32 v4, 0, v3
	v_rcp_iflag_f32_e32 v5, v5
	v_add_u32_e32 v6, s2, v1
	v_mul_f32_e32 v5, 0x4f7ffffe, v5
	v_cvt_u32_f32_e32 v5, v5
	v_mul_lo_u32 v1, v4, v5
	v_mul_hi_u32 v1, v5, v1
	v_add_u32_e32 v1, v5, v1
	v_mul_hi_u32 v1, v6, v1
	v_mul_lo_u32 v4, v1, v3
	v_sub_u32_e32 v4, v6, v4
	v_add_u32_e32 v5, 1, v1
	v_cmp_ge_u32_e32 vcc, v4, v3
	s_nop 1
	v_cndmask_b32_e32 v1, v1, v5, vcc
	v_sub_u32_e32 v5, v4, v3
	v_cndmask_b32_e32 v4, v4, v5, vcc
	v_add_u32_e32 v5, 1, v1
	v_cmp_ge_u32_e32 vcc, v4, v3
	v_add_u32_e32 v4, 1, v6
	s_nop 0
	v_cndmask_b32_e32 v1, v1, v5, vcc
	v_mul_lo_u32 v5, v3, v1
	v_add_u32_e32 v3, v5, v3
	v_cmp_ne_u32_e32 vcc, v4, v3
	s_and_saveexec_b64 s[2:3], vcc
	s_xor_b64 s[2:3], exec, s[2:3]
	s_cbranch_execz .LBB0_658
	s_add_i32 s4, s18, 0x900
	s_mov_b32 s5, 0
	s_lshl_b64 s[4:5], s[4:5], 2
	v_readlane_b32 s6, v253, 55
	v_readlane_b32 s7, v253, 56
	s_add_u32 s6, s62, 0xf71d500
	s_addc_u32 s7, s63, 0
	s_waitcnt lgkmcnt(0)
	v_mov_b32_e32 v2, 0
	s_nop 0
	global_load_dword v3, v2, s[6:7] sc1
	s_waitcnt vmcnt(0)
	v_cmp_eq_u32_e32 vcc, v3, v1
	s_and_saveexec_b64 s[4:5], vcc
	s_cbranch_execz .LBB0_657
	s_mov_b32 s19, 1
	s_mov_b64 s[8:9], 0
	s_branch .LBB0_648

.LBB0_743:
	s_or_b64 exec, exec, s[4:5]
	v_cvt_f32_u32_e32 v5, v3
	s_waitcnt vmcnt(0)
	v_readfirstlane_b32 s2, v4
	v_sub_u32_e32 v4, 0, v3
	v_rcp_iflag_f32_e32 v5, v5
	v_add_u32_e32 v6, s2, v1
	v_mul_f32_e32 v5, 0x4f7ffffe, v5
	v_cvt_u32_f32_e32 v5, v5
	v_mul_lo_u32 v1, v4, v5
	v_mul_hi_u32 v1, v5, v1
	v_add_u32_e32 v1, v5, v1
	v_mul_hi_u32 v1, v6, v1
	v_mul_lo_u32 v4, v1, v3
	v_sub_u32_e32 v4, v6, v4
	v_add_u32_e32 v5, 1, v1
	v_cmp_ge_u32_e32 vcc, v4, v3
	s_nop 1
	v_cndmask_b32_e32 v1, v1, v5, vcc
	v_sub_u32_e32 v5, v4, v3
	v_cndmask_b32_e32 v4, v4, v5, vcc
	v_add_u32_e32 v5, 1, v1
	v_cmp_ge_u32_e32 vcc, v4, v3
	v_add_u32_e32 v4, 1, v6
	s_nop 0
	v_cndmask_b32_e32 v1, v1, v5, vcc
	v_mul_lo_u32 v5, v3, v1
	v_add_u32_e32 v3, v5, v3
	v_cmp_ne_u32_e32 vcc, v4, v3
	s_and_saveexec_b64 s[2:3], vcc
	s_xor_b64 s[2:3], exec, s[2:3]
	s_cbranch_execz .LBB0_757
	s_add_i32 s4, s20, 0x900
	s_mov_b32 s5, 0
	s_lshl_b64 s[4:5], s[4:5], 2
	v_readlane_b32 s6, v253, 55
	v_readlane_b32 s7, v253, 56
	s_add_u32 s6, s62, 0xf71d500
	s_addc_u32 s7, s63, 0
	s_waitcnt lgkmcnt(0)
	v_mov_b32_e32 v2, 0
	s_nop 0
	global_load_dword v3, v2, s[6:7] sc1
	s_waitcnt vmcnt(0)
	v_cmp_eq_u32_e32 vcc, v3, v1
	s_and_saveexec_b64 s[4:5], vcc
	s_cbranch_execz .LBB0_756
	s_mov_b32 s21, 1
	s_mov_b64 s[8:9], 0
	s_branch .LBB0_747

.LBB0_780:
	s_movk_i32 s6, 0x7ff
	v_cmp_lt_i32_e32 vcc, s6, v66
	s_and_saveexec_b64 s[6:7], vcc
	s_xor_b64 s[6:7], exec, s[6:7]
	s_cbranch_execz .LBB0_782
	s_movk_i32 s11, 0x80
	v_add_u32_e32 v2, 0xfffff800, v66
	v_bfe_u32 v86, v66, 1, 2
	v_and_or_b32 v67, v77, s11, v1
	v_lshrrev_b32_e32 v87, 3, v2
	v_lshlrev_b32_e32 v2, 6, v67
	v_lshlrev_b32_e32 v3, 14, v86
	v_or3_b32 v89, v3, v2, v68
	v_lshlrev_b32_e32 v90, 4, v87
	v_lshl_or_b32 v88, v86, 13, v68
	v_add_u32_e32 v70, v89, v90
	v_lshlrev_b64 v[2:3], 9, v[70:71]
	v_add_u32_e32 v70, v88, v90
	v_lshlrev_b64 v[6:7], 9, v[70:71]
	v_lshl_add_u64 v[2:3], v[72:73], 0, v[2:3]
	v_lshl_add_u64 v[6:7], v[74:75], 0, v[6:7]
	s_mov_b64 vcc, 0x1000
	v_lshl_add_u64 v[100:101], v[2:3], 0, vcc
	s_mov_b64 vcc, 0x1000
	v_lshl_add_u64 v[102:103], v[6:7], 0, vcc
	s_mov_b64 vcc, 0x101000
	v_lshl_add_u64 v[104:105], v[6:7], 0, vcc
	s_mov_b64 vcc, 0x201000
	v_lshl_add_u64 v[106:107], v[6:7], 0, vcc
	s_mov_b64 vcc, 0x301000
	v_lshl_add_u64 v[108:109], v[6:7], 0, vcc
	global_load_dwordx4 v[112:115], v[100:101], off offset:-4096
	global_load_dwordx4 v[116:119], v[100:101], off offset:-3072
	global_load_dwordx4 v[144:147], v[102:103], off offset:-4096
	global_load_dwordx4 v[148:151], v[104:105], off offset:-4096
	global_load_dwordx4 v[152:155], v[106:107], off offset:-4096
	global_load_dwordx4 v[156:159], v[108:109], off offset:-4096
	global_load_dwordx4 v[120:123], v[100:101], off offset:-2048
	global_load_dwordx4 v[124:127], v[100:101], off offset:-1024
	global_load_dwordx4 v[128:131], v[100:101], off
	global_load_dwordx4 v[132:135], v[100:101], off offset:1024
	global_load_dwordx4 v[136:139], v[100:101], off offset:2048
	global_load_dwordx4 v[140:143], v[100:101], off offset:3072
	global_load_dwordx4 v[160:163], v[102:103], off offset:-3072
	global_load_dwordx4 v[164:167], v[104:105], off offset:-3072
	global_load_dwordx4 v[168:171], v[106:107], off offset:-3072
	global_load_dwordx4 v[172:175], v[108:109], off offset:-3072
	global_load_dwordx4 v[176:179], v[102:103], off offset:-2048
	global_load_dwordx4 v[180:183], v[104:105], off offset:-2048
	global_load_dwordx4 v[184:187], v[106:107], off offset:-2048
	global_load_dwordx4 v[188:191], v[108:109], off offset:-2048
	s_waitcnt vmcnt(17)
	v_mfma_f32_32x32x16_bf16 v[50:65], v[144:147], v[112:115], 0
	global_load_dwordx4 v[144:147], v[102:103], off offset:-1024
	s_waitcnt vmcnt(17)
	v_mfma_f32_32x32x16_bf16 v[34:49], v[148:151], v[112:115], 0
	global_load_dwordx4 v[148:151], v[104:105], off offset:-1024
	s_waitcnt vmcnt(17)
	v_mfma_f32_32x32x16_bf16 v[18:33], v[152:155], v[112:115], 0
	global_load_dwordx4 v[152:155], v[106:107], off offset:-1024
	s_waitcnt vmcnt(17)
	v_mfma_f32_32x32x16_bf16 v[2:17], v[156:159], v[112:115], 0
	global_load_dwordx4 v[156:159], v[108:109], off offset:-1024
	s_waitcnt vmcnt(11)
	v_mfma_f32_32x32x16_bf16 v[50:65], v[160:163], v[116:119], v[50:65]
	global_load_dwordx4 v[160:163], v[102:103], off
	s_waitcnt vmcnt(11)
	v_mfma_f32_32x32x16_bf16 v[34:49], v[164:167], v[116:119], v[34:49]
	global_load_dwordx4 v[164:167], v[104:105], off
	s_waitcnt vmcnt(11)
	v_mfma_f32_32x32x16_bf16 v[18:33], v[168:171], v[116:119], v[18:33]
	global_load_dwordx4 v[168:171], v[106:107], off
	s_waitcnt vmcnt(11)
	v_mfma_f32_32x32x16_bf16 v[2:17], v[172:175], v[116:119], v[2:17]
	global_load_dwordx4 v[172:175], v[108:109], off
	s_waitcnt vmcnt(11)
	v_mfma_f32_32x32x16_bf16 v[50:65], v[176:179], v[120:123], v[50:65]
	global_load_dwordx4 v[176:179], v[102:103], off offset:1024
	s_waitcnt vmcnt(11)
	v_mfma_f32_32x32x16_bf16 v[34:49], v[180:183], v[120:123], v[34:49]
	global_load_dwordx4 v[180:183], v[104:105], off offset:1024
	s_waitcnt vmcnt(11)
	v_mfma_f32_32x32x16_bf16 v[18:33], v[184:187], v[120:123], v[18:33]
	global_load_dwordx4 v[184:187], v[106:107], off offset:1024
	s_waitcnt vmcnt(11)
	v_mfma_f32_32x32x16_bf16 v[2:17], v[188:191], v[120:123], v[2:17]
	global_load_dwordx4 v[188:191], v[108:109], off offset:1024
	s_waitcnt vmcnt(11)
	v_mfma_f32_32x32x16_bf16 v[50:65], v[144:147], v[124:127], v[50:65]
	global_load_dwordx4 v[144:147], v[102:103], off offset:2048
	s_waitcnt vmcnt(11)
	v_mfma_f32_32x32x16_bf16 v[34:49], v[148:151], v[124:127], v[34:49]
	global_load_dwordx4 v[148:151], v[104:105], off offset:2048
	s_waitcnt vmcnt(11)
	v_mfma_f32_32x32x16_bf16 v[18:33], v[152:155], v[124:127], v[18:33]
	global_load_dwordx4 v[152:155], v[106:107], off offset:2048
	s_waitcnt vmcnt(11)
	v_mfma_f32_32x32x16_bf16 v[2:17], v[156:159], v[124:127], v[2:17]
	global_load_dwordx4 v[156:159], v[108:109], off offset:2048
	s_waitcnt vmcnt(11)
	v_mfma_f32_32x32x16_bf16 v[50:65], v[160:163], v[128:131], v[50:65]
	global_load_dwordx4 v[160:163], v[102:103], off offset:3072
	s_waitcnt vmcnt(11)
	v_mfma_f32_32x32x16_bf16 v[34:49], v[164:167], v[128:131], v[34:49]
	global_load_dwordx4 v[164:167], v[104:105], off offset:3072
	s_waitcnt vmcnt(11)
	v_mfma_f32_32x32x16_bf16 v[18:33], v[168:171], v[128:131], v[18:33]
	global_load_dwordx4 v[168:171], v[106:107], off offset:3072
	s_waitcnt vmcnt(11)
	v_mfma_f32_32x32x16_bf16 v[2:17], v[172:175], v[128:131], v[2:17]
	global_load_dwordx4 v[172:175], v[108:109], off offset:3072
	s_waitcnt vmcnt(11)
	v_mfma_f32_32x32x16_bf16 v[50:65], v[176:179], v[132:135], v[50:65]
	s_waitcnt vmcnt(10)
	v_mfma_f32_32x32x16_bf16 v[34:49], v[180:183], v[132:135], v[34:49]
	s_waitcnt vmcnt(9)
	v_mfma_f32_32x32x16_bf16 v[18:33], v[184:187], v[132:135], v[18:33]
	s_waitcnt vmcnt(8)
	v_mfma_f32_32x32x16_bf16 v[2:17], v[188:191], v[132:135], v[2:17]
	s_waitcnt vmcnt(7)
	v_mfma_f32_32x32x16_bf16 v[50:65], v[144:147], v[136:139], v[50:65]
	s_waitcnt vmcnt(6)
	v_mfma_f32_32x32x16_bf16 v[34:49], v[148:151], v[136:139], v[34:49]
	s_waitcnt vmcnt(5)
	v_mfma_f32_32x32x16_bf16 v[18:33], v[152:155], v[136:139], v[18:33]
	s_waitcnt vmcnt(4)
	v_mfma_f32_32x32x16_bf16 v[2:17], v[156:159], v[136:139], v[2:17]
	s_waitcnt vmcnt(3)
	v_mfma_f32_32x32x16_bf16 v[50:65], v[160:163], v[140:143], v[50:65]
	s_waitcnt vmcnt(2)
	v_mfma_f32_32x32x16_bf16 v[34:49], v[164:167], v[140:143], v[34:49]
	s_waitcnt vmcnt(1)
	v_mfma_f32_32x32x16_bf16 v[18:33], v[168:171], v[140:143], v[18:33]
	s_waitcnt vmcnt(0)
	v_mfma_f32_32x32x16_bf16 v[2:17], v[172:175], v[140:143], v[2:17]
	s_movk_i32 s11, 0x1000
	v_lshl_or_b32 v70, v87, 2, v86
	v_lshlrev_b64 v[86:87], 16, v[70:71]
	v_lshl_add_u64 v[86:87], s[68:69], 0, v[86:87]
	v_lshl_or_b32 v70, v67, 8, v85
	v_lshl_add_u64 v[192:193], v[86:87], 0, v[70:71]
	s_mov_b64 vcc, 0x1000
	v_lshl_add_u64 v[194:195], v[192:193], 0, vcc
	s_nop 7
	s_nop 7
	v_cvt_pk_bf16_f32 v196, v50, v51
	v_cvt_pk_bf16_f32 v197, v52, v53
	global_store_dwordx2 v[192:193], v[196:197], off
	v_cvt_pk_bf16_f32 v198, v54, v55
	v_cvt_pk_bf16_f32 v199, v56, v57
	global_store_dwordx2 v[192:193], v[198:199], off offset:512
	v_cvt_pk_bf16_f32 v200, v58, v59
	v_cvt_pk_bf16_f32 v201, v60, v61
	global_store_dwordx2 v[192:193], v[200:201], off offset:1024
	v_cvt_pk_bf16_f32 v202, v62, v63
	v_cvt_pk_bf16_f32 v203, v64, v65
	global_store_dwordx2 v[192:193], v[202:203], off offset:1536
	v_cvt_pk_bf16_f32 v196, v34, v35
	v_cvt_pk_bf16_f32 v197, v36, v37
	global_store_dwordx2 v[192:193], v[196:197], off offset:2048
	v_cvt_pk_bf16_f32 v198, v38, v39
	v_cvt_pk_bf16_f32 v199, v40, v41
	global_store_dwordx2 v[192:193], v[198:199], off offset:2560
	v_cvt_pk_bf16_f32 v200, v42, v43
	v_cvt_pk_bf16_f32 v201, v44, v45
	global_store_dwordx2 v[192:193], v[200:201], off offset:3072
	v_cvt_pk_bf16_f32 v202, v46, v47
	v_cvt_pk_bf16_f32 v203, v48, v49
	global_store_dwordx2 v[192:193], v[202:203], off offset:3584
	v_cvt_pk_bf16_f32 v196, v18, v19
	v_cvt_pk_bf16_f32 v197, v20, v21
	global_store_dwordx2 v[194:195], v[196:197], off
	v_cvt_pk_bf16_f32 v198, v22, v23
	v_cvt_pk_bf16_f32 v199, v24, v25
	global_store_dwordx2 v[194:195], v[198:199], off offset:512
	v_cvt_pk_bf16_f32 v200, v26, v27
	v_cvt_pk_bf16_f32 v201, v28, v29
	global_store_dwordx2 v[194:195], v[200:201], off offset:1024
	v_cvt_pk_bf16_f32 v202, v30, v31
	v_cvt_pk_bf16_f32 v203, v32, v33
	global_store_dwordx2 v[194:195], v[202:203], off offset:1536
	v_cvt_pk_bf16_f32 v196, v2, v3
	v_cvt_pk_bf16_f32 v197, v4, v5
	global_store_dwordx2 v[194:195], v[196:197], off offset:2048
	v_cvt_pk_bf16_f32 v198, v6, v7
	v_cvt_pk_bf16_f32 v199, v8, v9
	global_store_dwordx2 v[194:195], v[198:199], off offset:2560
	v_cvt_pk_bf16_f32 v200, v10, v11
	v_cvt_pk_bf16_f32 v201, v12, v13
	global_store_dwordx2 v[194:195], v[200:201], off offset:3072
	v_cvt_pk_bf16_f32 v202, v14, v15
	v_cvt_pk_bf16_f32 v203, v16, v17
	global_store_dwordx2 v[194:195], v[202:203], off offset:3584
	s_nop 0
	s_nop 0
	s_nop 0
	s_nop 0
	s_nop 0
	s_nop 0
	s_nop 0
	s_nop 0
	s_nop 0
	s_nop 0
	s_nop 0
	s_nop 0
	s_nop 0
	s_nop 0
	s_nop 0

.Lp4_done:
	s_nop 0
	s_nop 0
	s_nop 0
	s_nop 0
	s_nop 0
	s_nop 0
	s_nop 0
	s_nop 0
	s_nop 0
.LBB0_845:
	s_or_b64 exec, exec, s[0:1]
	s_waitcnt vmcnt(0)
	s_barrier
	s_mov_b64 s[0:1], exec
	v_readlane_b32 s2, v253, 53
	v_readlane_b32 s3, v253, 54
	s_and_b64 s[2:3], s[0:1], s[2:3]
	s_mov_b64 exec, s[2:3]
	s_cbranch_execz .LBB0_897
	s_add_i32 s2, 0, 0x20000
	s_mov_b32 s8, s87
	v_mov_b32_e32 v1, s2
	s_waitcnt vmcnt(0) expcnt(0) lgkmcnt(0)
	ds_read_b32 v3, v1
	s_add_i32 s2, 0, 0x20004
	v_mov_b32_e32 v1, s2
	ds_read_b32 v2, v1
	s_waitcnt lgkmcnt(1)
	v_cmp_ne_u32_e32 vcc, 0, v3
	s_cbranch_vccnz .LBB0_861
	s_mov_b32 s9, 1
	v_mov_b32_e32 v17, 0
	s_branch .LBB0_849

.LBB0_899:
	s_or_b64 exec, exec, s[0:1]
	s_lshl_b32 s0, s84, 5
	v_bitop3_b32 v83, v120, 32, s0 bitop3:0x36
	v_lshl_add_u32 v83, v83, 2, v225
	s_waitcnt lgkmcnt(0)
	s_barrier
	ds_read_b128 v[84:87], v83
	ds_read_b128 v[98:101], v83 offset:16
	ds_read_b128 v[102:105], v83 offset:32
	ds_read_b128 v[106:109], v83 offset:48
	s_mov_b32 s0, 0x3727c5ac
	s_waitcnt lgkmcnt(3)
	v_pk_add_f32 v[66:67], v[66:67], v[84:85]
	v_mov_b64_e32 v[110:111], s[0:1]
	v_pk_fma_f32 v[66:67], v[66:67], s[92:93], v[110:111] op_sel_hi:[1,0,0]
	s_nop 0
	v_mul_f32_e32 v83, 0x4b800000, v66
	v_cmp_gt_f32_e64 s[0:1], s83, v66
	v_cmp_gt_f32_e32 vcc, s83, v67
	s_nop 0
	v_cndmask_b32_e64 v66, v66, v83, s[0:1]
	v_rsq_f32_e32 v66, v66
	s_nop 0
	v_mul_f32_e32 v83, 0x45800000, v66
	v_cndmask_b32_e64 v94, v66, v83, s[0:1]
	v_mul_f32_e32 v66, 0x4b800000, v67
	v_cndmask_b32_e32 v66, v67, v66, vcc
	v_rsq_f32_e32 v66, v66
	v_mul_f32_e32 v50, v50, v94
	v_mul_f32_e32 v34, v34, v94
	v_mul_f32_e32 v18, v18, v94
	v_mul_f32_e32 v67, 0x45800000, v66
	v_cndmask_b32_e32 v96, v66, v67, vcc
	v_pk_add_f32 v[66:67], v[68:69], v[86:87]
	v_mul_f32_e32 v51, v51, v96
	v_pk_fma_f32 v[66:67], v[66:67], s[92:93], v[110:111] op_sel_hi:[1,0,0]
	v_mul_f32_e32 v35, v35, v96
	v_mul_f32_e32 v68, 0x4b800000, v66
	v_cmp_gt_f32_e64 s[0:1], s83, v66
	v_cmp_gt_f32_e32 vcc, s83, v67
	v_mul_f32_e32 v19, v19, v96
	v_cndmask_b32_e64 v66, v66, v68, s[0:1]
	v_rsq_f32_e32 v66, v66
	v_mul_f32_e32 v2, v2, v94
	v_mul_f32_e32 v3, v3, v96
	v_mul_f32_e32 v68, 0x45800000, v66
	v_cndmask_b32_e64 v93, v66, v68, s[0:1]
	v_mul_f32_e32 v66, 0x4b800000, v67
	v_cndmask_b32_e32 v66, v67, v66, vcc
	v_rsq_f32_e32 v66, v66
	s_nop 0
	v_mul_f32_e32 v67, 0x45800000, v66
	v_cndmask_b32_e32 v95, v66, v67, vcc
	s_waitcnt lgkmcnt(2)
	v_pk_add_f32 v[66:67], v[70:71], v[98:99]
	s_nop 0
	v_pk_fma_f32 v[66:67], v[66:67], s[92:93], v[110:111] op_sel_hi:[1,0,0]
	s_nop 0
	v_mul_f32_e32 v68, 0x4b800000, v66
	v_cmp_gt_f32_e64 s[0:1], s83, v66
	v_cmp_gt_f32_e32 vcc, s83, v67
	s_nop 0
	v_cndmask_b32_e64 v66, v66, v68, s[0:1]
	v_rsq_f32_e32 v66, v66
	s_nop 0
	v_mul_f32_e32 v68, 0x45800000, v66
	v_cndmask_b32_e64 v91, v66, v68, s[0:1]
	v_mul_f32_e32 v66, 0x4b800000, v67
	v_cndmask_b32_e32 v66, v67, v66, vcc
	v_rsq_f32_e32 v66, v66
	s_nop 0
	v_mul_f32_e32 v67, 0x45800000, v66
	v_cndmask_b32_e32 v92, v66, v67, vcc
	v_pk_add_f32 v[66:67], v[72:73], v[100:101]
	s_nop 0
	v_pk_fma_f32 v[66:67], v[66:67], s[92:93], v[110:111] op_sel_hi:[1,0,0]
	s_nop 0
	v_mul_f32_e32 v68, 0x4b800000, v66
	v_cmp_gt_f32_e64 s[0:1], s83, v66
	v_cmp_gt_f32_e32 vcc, s83, v67
	s_nop 0
	v_cndmask_b32_e64 v66, v66, v68, s[0:1]
	v_rsq_f32_e32 v66, v66
	s_nop 0
	v_mul_f32_e32 v68, 0x45800000, v66
	v_cndmask_b32_e64 v89, v66, v68, s[0:1]
	v_mul_f32_e32 v66, 0x4b800000, v67
	v_cndmask_b32_e32 v66, v67, v66, vcc
	v_rsq_f32_e32 v66, v66
	s_nop 0
	v_mul_f32_e32 v67, 0x45800000, v66
	v_cndmask_b32_e32 v90, v66, v67, vcc
	s_waitcnt lgkmcnt(1)
	v_pk_add_f32 v[66:67], v[74:75], v[102:103]
	s_nop 0
	v_pk_fma_f32 v[66:67], v[66:67], s[92:93], v[110:111] op_sel_hi:[1,0,0]
	s_nop 0
	v_mul_f32_e32 v68, 0x4b800000, v66
	v_cmp_gt_f32_e64 s[0:1], s83, v66
	v_cmp_gt_f32_e32 vcc, s83, v67
	s_nop 0
	v_cndmask_b32_e64 v66, v66, v68, s[0:1]
	v_rsq_f32_e32 v66, v66
	s_nop 0
	v_mul_f32_e32 v68, 0x45800000, v66
	v_cndmask_b32_e64 v87, v66, v68, s[0:1]
	v_mul_f32_e32 v66, 0x4b800000, v67
	v_cndmask_b32_e32 v66, v67, v66, vcc
	v_rsq_f32_e32 v66, v66
	s_nop 0
	v_mul_f32_e32 v67, 0x45800000, v66
	v_cndmask_b32_e32 v88, v66, v67, vcc
	v_pk_add_f32 v[66:67], v[76:77], v[104:105]
	s_nop 0
	v_pk_fma_f32 v[66:67], v[66:67], s[92:93], v[110:111] op_sel_hi:[1,0,0]
	s_nop 0
	v_mul_f32_e32 v68, 0x4b800000, v66
	v_cmp_gt_f32_e64 s[0:1], s83, v66
	v_cmp_gt_f32_e32 vcc, s83, v67
	s_nop 0
	v_cndmask_b32_e64 v66, v66, v68, s[0:1]
	v_rsq_f32_e32 v66, v66
	s_nop 0
	v_mul_f32_e32 v68, 0x45800000, v66
	v_cndmask_b32_e64 v85, v66, v68, s[0:1]
	v_mul_f32_e32 v66, 0x4b800000, v67
	v_cndmask_b32_e32 v66, v67, v66, vcc
	v_rsq_f32_e32 v66, v66
	s_nop 0
	v_mul_f32_e32 v67, 0x45800000, v66
	v_cndmask_b32_e32 v86, v66, v67, vcc
	s_waitcnt lgkmcnt(0)
	v_pk_add_f32 v[66:67], v[78:79], v[106:107]
	s_nop 0
	v_pk_fma_f32 v[66:67], v[66:67], s[92:93], v[110:111] op_sel_hi:[1,0,0]
	s_nop 0
	v_mul_f32_e32 v68, 0x4b800000, v66
	v_cmp_gt_f32_e64 s[0:1], s83, v66
	v_cmp_gt_f32_e32 vcc, s83, v67
	s_nop 0
	v_cndmask_b32_e64 v66, v66, v68, s[0:1]
	v_rsq_f32_e32 v66, v66
	s_nop 0
	v_mul_f32_e32 v68, 0x45800000, v66
	v_cndmask_b32_e64 v83, v66, v68, s[0:1]
	v_mul_f32_e32 v66, 0x4b800000, v67
	v_cndmask_b32_e32 v66, v67, v66, vcc
	v_rsq_f32_e32 v66, v66
	s_nop 0
	v_mul_f32_e32 v67, 0x45800000, v66
	v_cndmask_b32_e32 v84, v66, v67, vcc
	v_pk_add_f32 v[66:67], v[80:81], v[108:109]
	s_nop 0
	v_pk_fma_f32 v[66:67], v[66:67], s[92:93], v[110:111] op_sel_hi:[1,0,0]
	s_nop 0
	v_mul_f32_e32 v68, 0x4b800000, v66
	v_cmp_gt_f32_e64 s[0:1], s83, v66
	v_cmp_gt_f32_e32 vcc, s83, v67
	s_nop 0
	v_cndmask_b32_e64 v66, v66, v68, s[0:1]
	v_rsq_f32_e32 v66, v66
	s_nop 0
	v_mul_f32_e32 v68, 0x45800000, v66
	v_cndmask_b32_e64 v78, v66, v68, s[0:1]
	v_mul_f32_e32 v66, 0x4b800000, v67
	v_cndmask_b32_e32 v66, v67, v66, vcc
	v_rsq_f32_e32 v66, v66
	v_readlane_b32 s0, v253, 0
	v_readlane_b32 s4, v253, 4
	v_readlane_b32 s5, v253, 5
	v_mul_f32_e32 v67, 0x45800000, v66
	v_cndmask_b32_e32 v79, v66, v67, vcc
	v_lshl_or_b32 v67, s85, 7, v118
	v_or_b32_e32 v80, v67, v231
	v_lshlrev_b32_e32 v81, 2, v80
	v_and_b32_e32 v66, 1, v116
	s_movk_i32 s0, 0x39e
	v_cmp_eq_u32_e32 vcc, 0, v66
	v_or3_b32 v74, v117, v119, v66
	v_bitop3_b32 v66, v67, s0, v231 bitop3:0xc8
	v_lshlrev_b32_e32 v114, 1, v66
	v_ashrrev_i32_e32 v75, 31, v74
	v_lshl_add_u64 v[76:77], s[80:81], 0, v[114:115]
	v_lshlrev_b64 v[72:73], 11, v[74:75]
	v_lshl_add_u64 v[170:171], v[76:77], 0, v[72:73]
	v_or_b32_e32 v186, 2, v74
	v_ashrrev_i32_e32 v187, 31, v186
	v_lshlrev_b64 v[186:187], 11, v[186:187]
	v_lshl_add_u64 v[172:173], v[76:77], 0, v[186:187]
	v_or_b32_e32 v186, 8, v74
	v_ashrrev_i32_e32 v187, 31, v186
	v_lshlrev_b64 v[186:187], 11, v[186:187]
	v_lshl_add_u64 v[174:175], v[76:77], 0, v[186:187]
	v_or_b32_e32 v186, 10, v74
	v_ashrrev_i32_e32 v187, 31, v186
	v_lshlrev_b64 v[186:187], 11, v[186:187]
	v_lshl_add_u64 v[176:177], v[76:77], 0, v[186:187]
	v_or_b32_e32 v186, 16, v74
	v_ashrrev_i32_e32 v187, 31, v186
	v_lshlrev_b64 v[186:187], 11, v[186:187]
	v_lshl_add_u64 v[178:179], v[76:77], 0, v[186:187]
	v_or_b32_e32 v186, 18, v74
	v_ashrrev_i32_e32 v187, 31, v186
	v_lshlrev_b64 v[186:187], 11, v[186:187]
	v_lshl_add_u64 v[180:181], v[76:77], 0, v[186:187]
	v_or_b32_e32 v186, 24, v74
	v_ashrrev_i32_e32 v187, 31, v186
	v_lshlrev_b64 v[186:187], 11, v[186:187]
	v_lshl_add_u64 v[182:183], v[76:77], 0, v[186:187]
	v_or_b32_e32 v186, 26, v74
	v_ashrrev_i32_e32 v187, 31, v186
	v_lshlrev_b64 v[186:187], 11, v[186:187]
	v_lshl_add_u64 v[184:185], v[76:77], 0, v[186:187]
	global_load_dword v97, v81, s[4:5]
	global_load_dword v167, v81, s[4:5] offset:128
	global_load_dword v168, v81, s[4:5] offset:256
	global_load_dword v169, v81, s[4:5] offset:384
	global_load_dword v134, v[170:171], off
	global_load_dword v135, v[172:173], off
	global_load_dword v136, v[174:175], off
	global_load_dword v137, v[176:177], off
	global_load_dword v138, v[178:179], off
	global_load_dword v139, v[180:181], off
	global_load_dword v140, v[182:183], off
	global_load_dword v141, v[184:185], off
	global_load_dword v142, v[170:171], off offset:64
	global_load_dword v143, v[172:173], off offset:64
	global_load_dword v144, v[174:175], off offset:64
	global_load_dword v145, v[176:177], off offset:64
	global_load_dword v146, v[178:179], off offset:64
	global_load_dword v147, v[180:181], off offset:64
	global_load_dword v148, v[182:183], off offset:64
	global_load_dword v149, v[184:185], off offset:64
	global_load_dword v150, v[170:171], off offset:128
	global_load_dword v151, v[172:173], off offset:128
	global_load_dword v152, v[174:175], off offset:128
	global_load_dword v153, v[176:177], off offset:128
	global_load_dword v154, v[178:179], off offset:128
	global_load_dword v155, v[180:181], off offset:128
	global_load_dword v156, v[182:183], off offset:128
	global_load_dword v157, v[184:185], off offset:128
	global_load_dword v158, v[170:171], off offset:192
	global_load_dword v159, v[172:173], off offset:192
	global_load_dword v160, v[174:175], off offset:192
	global_load_dword v161, v[176:177], off offset:192
	global_load_dword v162, v[178:179], off offset:192
	global_load_dword v163, v[180:181], off offset:192
	global_load_dword v164, v[182:183], off offset:192
	global_load_dword v165, v[184:185], off offset:192
	s_waitcnt vmcnt(0)
	s_movk_i32 s0, 0x3be
	v_readlane_b32 s1, v253, 1
	v_readlane_b32 s2, v253, 2
	v_readlane_b32 s3, v253, 3
	v_readlane_b32 s6, v253, 6
	v_readlane_b32 s7, v253, 7
	v_readlane_b32 s8, v253, 8
	v_readlane_b32 s9, v253, 9
	v_readlane_b32 s10, v253, 10
	v_readlane_b32 s11, v253, 11
	v_readlane_b32 s12, v253, 12
	v_readlane_b32 s13, v253, 13
	v_readlane_b32 s14, v253, 14
	v_readlane_b32 s15, v253, 15
	v_mul_f32_e32 v50, v50, v97
	v_mul_f32_e32 v51, v51, v97
	v_cndmask_b32_e32 v66, v50, v51, vcc
	ds_bpermute_b32 v66, v82, v66
	s_waitcnt lgkmcnt(0)
	v_cndmask_b32_e32 v67, v66, v50, vcc
	v_cndmask_b32_e32 v66, v51, v66, vcc
	v_lshl_add_u64 v[50:51], v[76:77], 0, v[72:73]
	v_mov_b32_e32 v68, v134
	v_lshlrev_b32_e32 v69, 16, v68
	v_mul_f32_e32 v70, 0xbfb8aa3b, v69
	v_exp_f32_e32 v70, v70
	v_and_b32_e32 v68, 0xffff0000, v68
	v_add_f32_e32 v70, 1.0, v70
	v_rcp_f32_e32 v70, v70
	s_nop 0
	v_mul_f32_e32 v69, v70, v69
	v_mul_f32_e32 v67, v67, v69
	v_mul_f32_e32 v69, 0xbfb8aa3b, v68
	v_exp_f32_e32 v69, v69
	s_nop 0
	v_add_f32_e32 v69, 1.0, v69
	v_rcp_f32_e32 v69, v69
	s_nop 0
	v_mul_f32_e32 v68, v69, v68
	v_mul_f32_e32 v66, v66, v68
	v_cvt_pk_bf16_f32 v66, v67, v66
	global_store_dword v[50:51], v66, off
	v_mul_f32_e32 v50, v52, v93
	v_mul_f32_e32 v51, v53, v95
	v_mul_f32_e32 v50, v50, v97
	v_mul_f32_e32 v51, v51, v97
	v_cndmask_b32_e32 v52, v50, v51, vcc
	ds_bpermute_b32 v52, v82, v52
	s_waitcnt lgkmcnt(0)
	v_cndmask_b32_e32 v53, v52, v50, vcc
	v_or_b32_e32 v50, 2, v74
	v_cndmask_b32_e32 v52, v51, v52, vcc
	v_ashrrev_i32_e32 v51, 31, v50
	v_lshlrev_b64 v[70:71], 11, v[50:51]
	v_lshl_add_u64 v[50:51], v[76:77], 0, v[70:71]
	v_mov_b32_e32 v66, v135
	v_lshlrev_b32_e32 v67, 16, v66
	v_mul_f32_e32 v68, 0xbfb8aa3b, v67
	v_exp_f32_e32 v68, v68
	v_and_b32_e32 v66, 0xffff0000, v66
	v_add_f32_e32 v68, 1.0, v68
	v_rcp_f32_e32 v68, v68
	s_nop 0
	v_mul_f32_e32 v67, v68, v67
	v_mul_f32_e32 v53, v53, v67
	v_mul_f32_e32 v67, 0xbfb8aa3b, v66
	v_exp_f32_e32 v67, v67
	s_nop 0
	v_add_f32_e32 v67, 1.0, v67
	v_rcp_f32_e32 v67, v67
	s_nop 0
	v_mul_f32_e32 v66, v67, v66
	v_mul_f32_e32 v52, v52, v66
	v_cvt_pk_bf16_f32 v52, v53, v52
	global_store_dword v[50:51], v52, off
	v_mul_f32_e32 v50, v54, v91
	v_mul_f32_e32 v51, v55, v92
	v_mul_f32_e32 v50, v50, v97
	v_mul_f32_e32 v51, v51, v97
	v_cndmask_b32_e32 v52, v50, v51, vcc
	ds_bpermute_b32 v52, v82, v52
	s_waitcnt lgkmcnt(0)
	v_cndmask_b32_e32 v53, v52, v50, vcc
	v_or_b32_e32 v50, 8, v74
	v_cndmask_b32_e32 v52, v51, v52, vcc
	v_ashrrev_i32_e32 v51, 31, v50
	v_lshlrev_b64 v[68:69], 11, v[50:51]
	v_lshl_add_u64 v[50:51], v[76:77], 0, v[68:69]
	v_mov_b32_e32 v54, v136
	v_lshlrev_b32_e32 v55, 16, v54
	v_mul_f32_e32 v66, 0xbfb8aa3b, v55
	v_exp_f32_e32 v66, v66
	v_and_b32_e32 v54, 0xffff0000, v54
	v_add_f32_e32 v66, 1.0, v66
	v_rcp_f32_e32 v66, v66
	s_nop 0
	v_mul_f32_e32 v55, v66, v55
	v_mul_f32_e32 v53, v53, v55
	v_mul_f32_e32 v55, 0xbfb8aa3b, v54
	v_exp_f32_e32 v55, v55
	s_nop 0
	v_add_f32_e32 v55, 1.0, v55
	v_rcp_f32_e32 v55, v55
	s_nop 0
	v_mul_f32_e32 v54, v55, v54
	v_mul_f32_e32 v52, v52, v54
	v_cvt_pk_bf16_f32 v52, v53, v52
	global_store_dword v[50:51], v52, off
	v_mul_f32_e32 v50, v56, v89
	v_mul_f32_e32 v51, v57, v90
	v_mul_f32_e32 v50, v97, v50
	v_mul_f32_e32 v51, v97, v51
	v_cndmask_b32_e32 v52, v50, v51, vcc
	ds_bpermute_b32 v52, v82, v52
	s_waitcnt lgkmcnt(0)
	v_cndmask_b32_e32 v53, v52, v50, vcc
	v_or_b32_e32 v50, 10, v74
	v_cndmask_b32_e32 v52, v51, v52, vcc
	v_ashrrev_i32_e32 v51, 31, v50
	v_lshlrev_b64 v[66:67], 11, v[50:51]
	v_lshl_add_u64 v[50:51], v[76:77], 0, v[66:67]
	v_mov_b32_e32 v54, v137
	v_lshlrev_b32_e32 v55, 16, v54
	v_mul_f32_e32 v56, 0xbfb8aa3b, v55
	v_exp_f32_e32 v56, v56
	v_and_b32_e32 v54, 0xffff0000, v54
	v_add_f32_e32 v56, 1.0, v56
	v_rcp_f32_e32 v56, v56
	s_nop 0
	v_mul_f32_e32 v55, v56, v55
	v_mul_f32_e32 v53, v53, v55
	v_mul_f32_e32 v55, 0xbfb8aa3b, v54
	v_exp_f32_e32 v55, v55
	s_nop 0
	v_add_f32_e32 v55, 1.0, v55
	v_rcp_f32_e32 v55, v55
	s_nop 0
	v_mul_f32_e32 v54, v55, v54
	v_mul_f32_e32 v52, v52, v54
	v_cvt_pk_bf16_f32 v52, v53, v52
	global_store_dword v[50:51], v52, off
	v_mul_f32_e32 v50, v58, v87
	v_mul_f32_e32 v51, v59, v88
	v_mul_f32_e32 v50, v97, v50
	v_mul_f32_e32 v51, v97, v51
	v_cndmask_b32_e32 v52, v50, v51, vcc
	ds_bpermute_b32 v52, v82, v52
	s_waitcnt lgkmcnt(0)
	v_cndmask_b32_e32 v53, v52, v50, vcc
	v_or_b32_e32 v50, 16, v74
	v_cndmask_b32_e32 v52, v51, v52, vcc
	v_ashrrev_i32_e32 v51, 31, v50
	v_lshlrev_b64 v[56:57], 11, v[50:51]
	v_lshl_add_u64 v[50:51], v[76:77], 0, v[56:57]
	v_mov_b32_e32 v54, v138
	v_lshlrev_b32_e32 v55, 16, v54
	v_mul_f32_e32 v58, 0xbfb8aa3b, v55
	v_exp_f32_e32 v58, v58
	v_and_b32_e32 v54, 0xffff0000, v54
	v_add_f32_e32 v58, 1.0, v58
	v_rcp_f32_e32 v58, v58
	s_nop 0
	v_mul_f32_e32 v55, v58, v55
	v_mul_f32_e32 v53, v53, v55
	v_mul_f32_e32 v55, 0xbfb8aa3b, v54
	v_exp_f32_e32 v55, v55
	s_nop 0
	v_add_f32_e32 v55, 1.0, v55
	v_rcp_f32_e32 v55, v55
	s_nop 0
	v_mul_f32_e32 v54, v55, v54
	v_mul_f32_e32 v52, v52, v54
	v_cvt_pk_bf16_f32 v52, v53, v52
	global_store_dword v[50:51], v52, off
	v_mul_f32_e32 v50, v60, v85
	v_mul_f32_e32 v51, v61, v86
	v_mul_f32_e32 v50, v97, v50
	v_mul_f32_e32 v51, v97, v51
	v_cndmask_b32_e32 v52, v50, v51, vcc
	ds_bpermute_b32 v52, v82, v52
	s_waitcnt lgkmcnt(0)
	v_cndmask_b32_e32 v53, v52, v50, vcc
	v_or_b32_e32 v50, 18, v74
	v_cndmask_b32_e32 v52, v51, v52, vcc
	v_ashrrev_i32_e32 v51, 31, v50
	v_lshlrev_b64 v[54:55], 11, v[50:51]
	v_lshl_add_u64 v[50:51], v[76:77], 0, v[54:55]
	v_mov_b32_e32 v58, v139
	v_lshlrev_b32_e32 v59, 16, v58
	v_mul_f32_e32 v60, 0xbfb8aa3b, v59
	v_exp_f32_e32 v60, v60
	v_and_b32_e32 v58, 0xffff0000, v58
	v_add_f32_e32 v60, 1.0, v60
	v_rcp_f32_e32 v60, v60
	s_nop 0
	v_mul_f32_e32 v59, v60, v59
	v_mul_f32_e32 v53, v53, v59
	v_mul_f32_e32 v59, 0xbfb8aa3b, v58
	v_exp_f32_e32 v59, v59
	s_nop 0
	v_add_f32_e32 v59, 1.0, v59
	v_rcp_f32_e32 v59, v59
	s_nop 0
	v_mul_f32_e32 v58, v59, v58
	v_mul_f32_e32 v52, v52, v58
	v_cvt_pk_bf16_f32 v52, v53, v52
	global_store_dword v[50:51], v52, off
	v_mul_f32_e32 v50, v62, v83
	v_mul_f32_e32 v51, v63, v84
	v_mul_f32_e32 v50, v97, v50
	v_mul_f32_e32 v51, v97, v51
	v_cndmask_b32_e32 v52, v50, v51, vcc
	ds_bpermute_b32 v52, v82, v52
	s_waitcnt lgkmcnt(0)
	v_cndmask_b32_e32 v58, v52, v50, vcc
	v_or_b32_e32 v50, 24, v74
	v_cndmask_b32_e32 v59, v51, v52, vcc
	v_ashrrev_i32_e32 v51, 31, v50
	v_lshlrev_b64 v[52:53], 11, v[50:51]
	v_lshl_add_u64 v[50:51], v[76:77], 0, v[52:53]
	v_mov_b32_e32 v60, v140
	v_lshlrev_b32_e32 v61, 16, v60
	v_mul_f32_e32 v62, 0xbfb8aa3b, v61
	v_exp_f32_e32 v62, v62
	v_and_b32_e32 v60, 0xffff0000, v60
	v_add_f32_e32 v62, 1.0, v62
	v_rcp_f32_e32 v62, v62
	s_nop 0
	v_mul_f32_e32 v61, v62, v61
	v_mul_f32_e32 v58, v58, v61
	v_mul_f32_e32 v61, 0xbfb8aa3b, v60
	v_exp_f32_e32 v61, v61
	s_nop 0
	v_add_f32_e32 v61, 1.0, v61
	v_rcp_f32_e32 v61, v61
	s_nop 0
	v_mul_f32_e32 v60, v61, v60
	v_mul_f32_e32 v59, v59, v60
	v_cvt_pk_bf16_f32 v58, v58, v59
	global_store_dword v[50:51], v58, off
	v_mul_f32_e32 v50, v64, v78
	v_mul_f32_e32 v51, v65, v79
	v_mul_f32_e32 v50, v97, v50
	v_mul_f32_e32 v51, v97, v51
	v_cndmask_b32_e32 v58, v50, v51, vcc
	ds_bpermute_b32 v58, v82, v58
	s_waitcnt lgkmcnt(0)
	v_cndmask_b32_e32 v60, v58, v50, vcc
	v_or_b32_e32 v50, 26, v74
	v_cndmask_b32_e32 v61, v51, v58, vcc
	v_ashrrev_i32_e32 v51, 31, v50
	v_lshlrev_b64 v[50:51], 11, v[50:51]
	v_lshl_add_u64 v[58:59], v[76:77], 0, v[50:51]
	v_mov_b32_e32 v62, v141
	v_lshlrev_b32_e32 v63, 16, v62
	v_mul_f32_e32 v64, 0xbfb8aa3b, v63
	v_exp_f32_e32 v64, v64
	v_and_b32_e32 v62, 0xffff0000, v62
	v_add_f32_e32 v64, 1.0, v64
	v_rcp_f32_e32 v64, v64
	s_nop 0
	v_mul_f32_e32 v63, v64, v63
	v_mul_f32_e32 v60, v60, v63
	v_mul_f32_e32 v63, 0xbfb8aa3b, v62
	v_exp_f32_e32 v63, v63
	s_nop 0
	v_add_f32_e32 v63, 1.0, v63
	v_rcp_f32_e32 v63, v63
	s_nop 0
	v_mul_f32_e32 v62, v63, v62
	v_mul_f32_e32 v61, v61, v62
	v_cvt_pk_bf16_f32 v60, v60, v61
	global_store_dword v[58:59], v60, off
	v_mov_b32_e32 v60, v167
	v_bitop3_b32 v58, v80, s0, 32 bitop3:0xc8
	v_lshlrev_b32_e32 v114, 1, v58
	v_lshl_add_u64 v[58:59], s[80:81], 0, v[114:115]
	s_movk_i32 s0, 0x3de
	v_mul_f32_e32 v34, v34, v60
	v_mul_f32_e32 v35, v35, v60
	v_cndmask_b32_e32 v61, v34, v35, vcc
	ds_bpermute_b32 v61, v82, v61
	s_waitcnt lgkmcnt(0)
	v_cndmask_b32_e32 v62, v61, v34, vcc
	v_cndmask_b32_e32 v61, v35, v61, vcc
	v_lshl_add_u64 v[34:35], v[58:59], 0, v[72:73]
	v_mov_b32_e32 v63, v142
	v_lshlrev_b32_e32 v64, 16, v63
	v_mul_f32_e32 v65, 0xbfb8aa3b, v64
	v_exp_f32_e32 v65, v65
	v_and_b32_e32 v63, 0xffff0000, v63
	v_add_f32_e32 v65, 1.0, v65
	v_rcp_f32_e32 v65, v65
	s_nop 0
	v_mul_f32_e32 v64, v65, v64
	v_mul_f32_e32 v62, v62, v64
	v_mul_f32_e32 v64, 0xbfb8aa3b, v63
	v_exp_f32_e32 v64, v64
	s_nop 0
	v_add_f32_e32 v64, 1.0, v64
	v_rcp_f32_e32 v64, v64
	s_nop 0
	v_mul_f32_e32 v63, v64, v63
	v_mul_f32_e32 v61, v61, v63
	v_cvt_pk_bf16_f32 v61, v62, v61
	global_store_dword v[34:35], v61, off
	v_mul_f32_e32 v34, v36, v93
	v_mul_f32_e32 v35, v37, v95
	v_mul_f32_e32 v34, v34, v60
	v_mul_f32_e32 v35, v35, v60
	v_cndmask_b32_e32 v36, v34, v35, vcc
	ds_bpermute_b32 v36, v82, v36
	s_waitcnt lgkmcnt(0)
	v_cndmask_b32_e32 v37, v36, v34, vcc
	v_cndmask_b32_e32 v36, v35, v36, vcc
	v_lshl_add_u64 v[34:35], v[58:59], 0, v[70:71]
	v_mov_b32_e32 v61, v143
	v_lshlrev_b32_e32 v62, 16, v61
	v_mul_f32_e32 v63, 0xbfb8aa3b, v62
	v_exp_f32_e32 v63, v63
	v_and_b32_e32 v61, 0xffff0000, v61
	v_add_f32_e32 v63, 1.0, v63
	v_rcp_f32_e32 v63, v63
	s_nop 0
	v_mul_f32_e32 v62, v63, v62
	v_mul_f32_e32 v37, v37, v62
	v_mul_f32_e32 v62, 0xbfb8aa3b, v61
	v_exp_f32_e32 v62, v62
	s_nop 0
	v_add_f32_e32 v62, 1.0, v62
	v_rcp_f32_e32 v62, v62
	s_nop 0
	v_mul_f32_e32 v61, v62, v61
	v_mul_f32_e32 v36, v36, v61
	v_cvt_pk_bf16_f32 v36, v37, v36
	global_store_dword v[34:35], v36, off
	v_mul_f32_e32 v34, v38, v91
	v_mul_f32_e32 v35, v39, v92
	v_mul_f32_e32 v34, v34, v60
	v_mul_f32_e32 v35, v35, v60
	v_cndmask_b32_e32 v36, v34, v35, vcc
	ds_bpermute_b32 v36, v82, v36
	s_waitcnt lgkmcnt(0)
	v_cndmask_b32_e32 v37, v36, v34, vcc
	v_cndmask_b32_e32 v36, v35, v36, vcc
	v_lshl_add_u64 v[34:35], v[58:59], 0, v[68:69]
	v_mov_b32_e32 v38, v144
	v_lshlrev_b32_e32 v39, 16, v38
	v_mul_f32_e32 v61, 0xbfb8aa3b, v39
	v_exp_f32_e32 v61, v61
	v_and_b32_e32 v38, 0xffff0000, v38
	v_add_f32_e32 v61, 1.0, v61
	v_rcp_f32_e32 v61, v61
	s_nop 0
	v_mul_f32_e32 v39, v61, v39
	v_mul_f32_e32 v37, v37, v39
	v_mul_f32_e32 v39, 0xbfb8aa3b, v38
	v_exp_f32_e32 v39, v39
	s_nop 0
	v_add_f32_e32 v39, 1.0, v39
	v_rcp_f32_e32 v39, v39
	s_nop 0
	v_mul_f32_e32 v38, v39, v38
	v_mul_f32_e32 v36, v36, v38
	v_cvt_pk_bf16_f32 v36, v37, v36
	global_store_dword v[34:35], v36, off
	v_mul_f32_e32 v34, v40, v89
	v_mul_f32_e32 v35, v41, v90
	v_mul_f32_e32 v34, v34, v60
	v_mul_f32_e32 v35, v35, v60
	v_cndmask_b32_e32 v36, v34, v35, vcc
	ds_bpermute_b32 v36, v82, v36
	s_waitcnt lgkmcnt(0)
	v_cndmask_b32_e32 v37, v36, v34, vcc
	v_cndmask_b32_e32 v36, v35, v36, vcc
	v_lshl_add_u64 v[34:35], v[58:59], 0, v[66:67]
	v_mov_b32_e32 v38, v145
	v_lshlrev_b32_e32 v39, 16, v38
	v_mul_f32_e32 v40, 0xbfb8aa3b, v39
	v_exp_f32_e32 v40, v40
	v_and_b32_e32 v38, 0xffff0000, v38
	v_add_f32_e32 v40, 1.0, v40
	v_rcp_f32_e32 v40, v40
	s_nop 0
	v_mul_f32_e32 v39, v40, v39
	v_mul_f32_e32 v37, v37, v39
	v_mul_f32_e32 v39, 0xbfb8aa3b, v38
	v_exp_f32_e32 v39, v39
	s_nop 0
	v_add_f32_e32 v39, 1.0, v39
	v_rcp_f32_e32 v39, v39
	s_nop 0
	v_mul_f32_e32 v38, v39, v38
	v_mul_f32_e32 v36, v36, v38
	v_cvt_pk_bf16_f32 v36, v37, v36
	global_store_dword v[34:35], v36, off
	v_mul_f32_e32 v34, v42, v87
	v_mul_f32_e32 v35, v43, v88
	v_mul_f32_e32 v34, v34, v60
	v_mul_f32_e32 v35, v35, v60
	v_cndmask_b32_e32 v36, v34, v35, vcc
	ds_bpermute_b32 v36, v82, v36
	s_waitcnt lgkmcnt(0)
	v_cndmask_b32_e32 v37, v36, v34, vcc
	v_cndmask_b32_e32 v36, v35, v36, vcc
	v_lshl_add_u64 v[34:35], v[58:59], 0, v[56:57]
	v_mov_b32_e32 v38, v146
	v_lshlrev_b32_e32 v39, 16, v38
	v_mul_f32_e32 v40, 0xbfb8aa3b, v39
	v_exp_f32_e32 v40, v40
	v_and_b32_e32 v38, 0xffff0000, v38
	v_add_f32_e32 v40, 1.0, v40
	v_rcp_f32_e32 v40, v40
	s_nop 0
	v_mul_f32_e32 v39, v40, v39
	v_mul_f32_e32 v37, v37, v39
	v_mul_f32_e32 v39, 0xbfb8aa3b, v38
	v_exp_f32_e32 v39, v39
	s_nop 0
	v_add_f32_e32 v39, 1.0, v39
	v_rcp_f32_e32 v39, v39
	s_nop 0
	v_mul_f32_e32 v38, v39, v38
	v_mul_f32_e32 v36, v36, v38
	v_cvt_pk_bf16_f32 v36, v37, v36
	global_store_dword v[34:35], v36, off
	v_mul_f32_e32 v34, v44, v85
	v_mul_f32_e32 v35, v45, v86
	v_mul_f32_e32 v34, v34, v60
	v_mul_f32_e32 v35, v35, v60
	v_cndmask_b32_e32 v36, v34, v35, vcc
	ds_bpermute_b32 v36, v82, v36
	s_waitcnt lgkmcnt(0)
	v_cndmask_b32_e32 v37, v36, v34, vcc
	v_cndmask_b32_e32 v36, v35, v36, vcc
	v_lshl_add_u64 v[34:35], v[58:59], 0, v[54:55]
	v_mov_b32_e32 v38, v147
	v_lshlrev_b32_e32 v39, 16, v38
	v_mul_f32_e32 v40, 0xbfb8aa3b, v39
	v_exp_f32_e32 v40, v40
	v_and_b32_e32 v38, 0xffff0000, v38
	v_add_f32_e32 v40, 1.0, v40
	v_rcp_f32_e32 v40, v40
	s_nop 0
	v_mul_f32_e32 v39, v40, v39
	v_mul_f32_e32 v37, v37, v39
	v_mul_f32_e32 v39, 0xbfb8aa3b, v38
	v_exp_f32_e32 v39, v39
	s_nop 0
	v_add_f32_e32 v39, 1.0, v39
	v_rcp_f32_e32 v39, v39
	s_nop 0
	v_mul_f32_e32 v38, v39, v38
	v_mul_f32_e32 v36, v36, v38
	v_cvt_pk_bf16_f32 v36, v37, v36
	global_store_dword v[34:35], v36, off
	v_mul_f32_e32 v34, v46, v83
	v_mul_f32_e32 v35, v47, v84
	v_mul_f32_e32 v34, v34, v60
	v_mul_f32_e32 v35, v35, v60
	v_cndmask_b32_e32 v36, v34, v35, vcc
	ds_bpermute_b32 v36, v82, v36
	s_waitcnt lgkmcnt(0)
	v_cndmask_b32_e32 v37, v36, v34, vcc
	v_cndmask_b32_e32 v36, v35, v36, vcc
	v_lshl_add_u64 v[34:35], v[58:59], 0, v[52:53]
	v_mov_b32_e32 v38, v148
	v_lshlrev_b32_e32 v39, 16, v38
	v_mul_f32_e32 v40, 0xbfb8aa3b, v39
	v_exp_f32_e32 v40, v40
	v_and_b32_e32 v38, 0xffff0000, v38
	v_add_f32_e32 v40, 1.0, v40
	v_rcp_f32_e32 v40, v40
	s_nop 0
	v_mul_f32_e32 v39, v40, v39
	v_mul_f32_e32 v37, v37, v39
	v_mul_f32_e32 v39, 0xbfb8aa3b, v38
	v_exp_f32_e32 v39, v39
	s_nop 0
	v_add_f32_e32 v39, 1.0, v39
	v_rcp_f32_e32 v39, v39
	s_nop 0
	v_mul_f32_e32 v38, v39, v38
	v_mul_f32_e32 v36, v36, v38
	v_cvt_pk_bf16_f32 v36, v37, v36
	global_store_dword v[34:35], v36, off
	v_mul_f32_e32 v34, v48, v78
	v_mul_f32_e32 v35, v49, v79
	v_mul_f32_e32 v34, v34, v60
	v_mul_f32_e32 v35, v35, v60
	v_cndmask_b32_e32 v36, v34, v35, vcc
	ds_bpermute_b32 v36, v82, v36
	s_waitcnt lgkmcnt(0)
	v_cndmask_b32_e32 v37, v36, v34, vcc
	v_cndmask_b32_e32 v36, v35, v36, vcc
	v_lshl_add_u64 v[34:35], v[58:59], 0, v[50:51]
	v_mov_b32_e32 v38, v149
	v_lshlrev_b32_e32 v39, 16, v38
	v_mul_f32_e32 v40, 0xbfb8aa3b, v39
	v_exp_f32_e32 v40, v40
	v_and_b32_e32 v38, 0xffff0000, v38
	v_add_f32_e32 v40, 1.0, v40
	v_rcp_f32_e32 v40, v40
	s_nop 0
	v_mul_f32_e32 v39, v40, v39
	v_mul_f32_e32 v37, v37, v39
	v_mul_f32_e32 v39, 0xbfb8aa3b, v38
	v_exp_f32_e32 v39, v39
	s_nop 0
	v_add_f32_e32 v39, 1.0, v39
	v_rcp_f32_e32 v39, v39
	s_nop 0
	v_mul_f32_e32 v38, v39, v38
	v_mul_f32_e32 v36, v36, v38
	v_cvt_pk_bf16_f32 v36, v37, v36
	global_store_dword v[34:35], v36, off
	v_mov_b32_e32 v36, v168
	v_bitop3_b32 v34, v80, s0, 64 bitop3:0xc8
	v_lshlrev_b32_e32 v114, 1, v34
	v_lshl_add_u64 v[34:35], s[80:81], 0, v[114:115]
	s_movk_i32 s0, 0x3fe
	v_mul_f32_e32 v18, v18, v36
	v_mul_f32_e32 v19, v19, v36
	v_cndmask_b32_e32 v37, v18, v19, vcc
	ds_bpermute_b32 v37, v82, v37
	s_waitcnt lgkmcnt(0)
	v_cndmask_b32_e32 v38, v37, v18, vcc
	v_cndmask_b32_e32 v37, v19, v37, vcc
	v_lshl_add_u64 v[18:19], v[34:35], 0, v[72:73]
	v_mov_b32_e32 v39, v150
	v_lshlrev_b32_e32 v40, 16, v39
	v_mul_f32_e32 v41, 0xbfb8aa3b, v40
	v_exp_f32_e32 v41, v41
	v_and_b32_e32 v39, 0xffff0000, v39
	v_add_f32_e32 v41, 1.0, v41
	v_rcp_f32_e32 v41, v41
	s_nop 0
	v_mul_f32_e32 v40, v41, v40
	v_mul_f32_e32 v38, v38, v40
	v_mul_f32_e32 v40, 0xbfb8aa3b, v39
	v_exp_f32_e32 v40, v40
	s_nop 0
	v_add_f32_e32 v40, 1.0, v40
	v_rcp_f32_e32 v40, v40
	s_nop 0
	v_mul_f32_e32 v39, v40, v39
	v_mul_f32_e32 v37, v37, v39
	v_cvt_pk_bf16_f32 v37, v38, v37
	global_store_dword v[18:19], v37, off
	v_mul_f32_e32 v18, v20, v93
	v_mul_f32_e32 v19, v21, v95
	v_mul_f32_e32 v18, v18, v36
	v_mul_f32_e32 v19, v19, v36
	v_cndmask_b32_e32 v20, v18, v19, vcc
	ds_bpermute_b32 v20, v82, v20
	s_waitcnt lgkmcnt(0)
	v_cndmask_b32_e32 v21, v20, v18, vcc
	v_cndmask_b32_e32 v20, v19, v20, vcc
	v_lshl_add_u64 v[18:19], v[34:35], 0, v[70:71]
	v_mov_b32_e32 v37, v151
	v_lshlrev_b32_e32 v38, 16, v37
	v_mul_f32_e32 v39, 0xbfb8aa3b, v38
	v_exp_f32_e32 v39, v39
	v_and_b32_e32 v37, 0xffff0000, v37
	v_add_f32_e32 v39, 1.0, v39
	v_rcp_f32_e32 v39, v39
	s_nop 0
	v_mul_f32_e32 v38, v39, v38
	v_mul_f32_e32 v21, v21, v38
	v_mul_f32_e32 v38, 0xbfb8aa3b, v37
	v_exp_f32_e32 v38, v38
	s_nop 0
	v_add_f32_e32 v38, 1.0, v38
	v_rcp_f32_e32 v38, v38
	s_nop 0
	v_mul_f32_e32 v37, v38, v37
	v_mul_f32_e32 v20, v20, v37
	v_cvt_pk_bf16_f32 v20, v21, v20
	global_store_dword v[18:19], v20, off
	v_mul_f32_e32 v18, v22, v91
	v_mul_f32_e32 v19, v23, v92
	v_mul_f32_e32 v18, v18, v36
	v_mul_f32_e32 v19, v19, v36
	v_cndmask_b32_e32 v20, v18, v19, vcc
	ds_bpermute_b32 v20, v82, v20
	s_waitcnt lgkmcnt(0)
	v_cndmask_b32_e32 v21, v20, v18, vcc
	v_cndmask_b32_e32 v20, v19, v20, vcc
	v_lshl_add_u64 v[18:19], v[34:35], 0, v[68:69]
	v_mov_b32_e32 v22, v152
	v_lshlrev_b32_e32 v23, 16, v22
	v_mul_f32_e32 v37, 0xbfb8aa3b, v23
	v_exp_f32_e32 v37, v37
	v_and_b32_e32 v22, 0xffff0000, v22
	v_add_f32_e32 v37, 1.0, v37
	v_rcp_f32_e32 v37, v37
	s_nop 0
	v_mul_f32_e32 v23, v37, v23
	v_mul_f32_e32 v21, v21, v23
	v_mul_f32_e32 v23, 0xbfb8aa3b, v22
	v_exp_f32_e32 v23, v23
	s_nop 0
	v_add_f32_e32 v23, 1.0, v23
	v_rcp_f32_e32 v23, v23
	s_nop 0
	v_mul_f32_e32 v22, v23, v22
	v_mul_f32_e32 v20, v20, v22
	v_cvt_pk_bf16_f32 v20, v21, v20
	global_store_dword v[18:19], v20, off
	v_mul_f32_e32 v18, v24, v89
	v_mul_f32_e32 v19, v25, v90
	v_mul_f32_e32 v18, v18, v36
	v_mul_f32_e32 v19, v19, v36
	v_cndmask_b32_e32 v20, v18, v19, vcc
	ds_bpermute_b32 v20, v82, v20
	s_waitcnt lgkmcnt(0)
	v_cndmask_b32_e32 v21, v20, v18, vcc
	v_cndmask_b32_e32 v20, v19, v20, vcc
	v_lshl_add_u64 v[18:19], v[34:35], 0, v[66:67]
	v_mov_b32_e32 v22, v153
	v_lshlrev_b32_e32 v23, 16, v22
	v_mul_f32_e32 v24, 0xbfb8aa3b, v23
	v_exp_f32_e32 v24, v24
	v_and_b32_e32 v22, 0xffff0000, v22
	v_add_f32_e32 v24, 1.0, v24
	v_rcp_f32_e32 v24, v24
	s_nop 0
	v_mul_f32_e32 v23, v24, v23
	v_mul_f32_e32 v21, v21, v23
	v_mul_f32_e32 v23, 0xbfb8aa3b, v22
	v_exp_f32_e32 v23, v23
	s_nop 0
	v_add_f32_e32 v23, 1.0, v23
	v_rcp_f32_e32 v23, v23
	s_nop 0
	v_mul_f32_e32 v22, v23, v22
	v_mul_f32_e32 v20, v20, v22
	v_cvt_pk_bf16_f32 v20, v21, v20
	global_store_dword v[18:19], v20, off
	v_mul_f32_e32 v18, v26, v87
	v_mul_f32_e32 v19, v27, v88
	v_mul_f32_e32 v18, v18, v36
	v_mul_f32_e32 v19, v19, v36
	v_cndmask_b32_e32 v20, v18, v19, vcc
	ds_bpermute_b32 v20, v82, v20
	s_waitcnt lgkmcnt(0)
	v_cndmask_b32_e32 v21, v20, v18, vcc
	v_cndmask_b32_e32 v20, v19, v20, vcc
	v_lshl_add_u64 v[18:19], v[34:35], 0, v[56:57]
	v_mov_b32_e32 v22, v154
	v_lshlrev_b32_e32 v23, 16, v22
	v_mul_f32_e32 v24, 0xbfb8aa3b, v23
	v_exp_f32_e32 v24, v24
	v_and_b32_e32 v22, 0xffff0000, v22
	v_add_f32_e32 v24, 1.0, v24
	v_rcp_f32_e32 v24, v24
	s_nop 0
	v_mul_f32_e32 v23, v24, v23
	v_mul_f32_e32 v21, v21, v23
	v_mul_f32_e32 v23, 0xbfb8aa3b, v22
	v_exp_f32_e32 v23, v23
	s_nop 0
	v_add_f32_e32 v23, 1.0, v23
	v_rcp_f32_e32 v23, v23
	s_nop 0
	v_mul_f32_e32 v22, v23, v22
	v_mul_f32_e32 v20, v20, v22
	v_cvt_pk_bf16_f32 v20, v21, v20
	global_store_dword v[18:19], v20, off
	v_mul_f32_e32 v18, v28, v85
	v_mul_f32_e32 v19, v29, v86
	v_mul_f32_e32 v18, v18, v36
	v_mul_f32_e32 v19, v19, v36
	v_cndmask_b32_e32 v20, v18, v19, vcc
	ds_bpermute_b32 v20, v82, v20
	s_waitcnt lgkmcnt(0)
	v_cndmask_b32_e32 v21, v20, v18, vcc
	v_cndmask_b32_e32 v20, v19, v20, vcc
	v_lshl_add_u64 v[18:19], v[34:35], 0, v[54:55]
	v_mov_b32_e32 v22, v155
	v_lshlrev_b32_e32 v23, 16, v22
	v_mul_f32_e32 v24, 0xbfb8aa3b, v23
	v_exp_f32_e32 v24, v24
	v_and_b32_e32 v22, 0xffff0000, v22
	v_add_f32_e32 v24, 1.0, v24
	v_rcp_f32_e32 v24, v24
	s_nop 0
	v_mul_f32_e32 v23, v24, v23
	v_mul_f32_e32 v21, v21, v23
	v_mul_f32_e32 v23, 0xbfb8aa3b, v22
	v_exp_f32_e32 v23, v23
	s_nop 0
	v_add_f32_e32 v23, 1.0, v23
	v_rcp_f32_e32 v23, v23
	s_nop 0
	v_mul_f32_e32 v22, v23, v22
	v_mul_f32_e32 v20, v20, v22
	v_cvt_pk_bf16_f32 v20, v21, v20
	global_store_dword v[18:19], v20, off
	v_mul_f32_e32 v18, v30, v83
	v_mul_f32_e32 v19, v31, v84
	v_mul_f32_e32 v18, v18, v36
	v_mul_f32_e32 v19, v19, v36
	v_cndmask_b32_e32 v20, v18, v19, vcc
	ds_bpermute_b32 v20, v82, v20
	s_waitcnt lgkmcnt(0)
	v_cndmask_b32_e32 v21, v20, v18, vcc
	v_cndmask_b32_e32 v20, v19, v20, vcc
	v_lshl_add_u64 v[18:19], v[34:35], 0, v[52:53]
	v_mov_b32_e32 v22, v156
	v_lshlrev_b32_e32 v23, 16, v22
	v_mul_f32_e32 v24, 0xbfb8aa3b, v23
	v_exp_f32_e32 v24, v24
	v_and_b32_e32 v22, 0xffff0000, v22
	v_add_f32_e32 v24, 1.0, v24
	v_rcp_f32_e32 v24, v24
	s_nop 0
	v_mul_f32_e32 v23, v24, v23
	v_mul_f32_e32 v21, v21, v23
	v_mul_f32_e32 v23, 0xbfb8aa3b, v22
	v_exp_f32_e32 v23, v23
	s_nop 0
	v_add_f32_e32 v23, 1.0, v23
	v_rcp_f32_e32 v23, v23
	s_nop 0
	v_mul_f32_e32 v22, v23, v22
	v_mul_f32_e32 v20, v20, v22
	v_cvt_pk_bf16_f32 v20, v21, v20
	global_store_dword v[18:19], v20, off
	v_mul_f32_e32 v18, v32, v78
	v_mul_f32_e32 v19, v33, v79
	v_mul_f32_e32 v18, v18, v36
	v_mul_f32_e32 v19, v19, v36
	v_cndmask_b32_e32 v20, v18, v19, vcc
	ds_bpermute_b32 v20, v82, v20
	s_waitcnt lgkmcnt(0)
	v_cndmask_b32_e32 v21, v20, v18, vcc
	v_cndmask_b32_e32 v20, v19, v20, vcc
	v_lshl_add_u64 v[18:19], v[34:35], 0, v[50:51]
	v_mov_b32_e32 v22, v157
	v_lshlrev_b32_e32 v23, 16, v22
	v_mul_f32_e32 v24, 0xbfb8aa3b, v23
	v_exp_f32_e32 v24, v24
	v_and_b32_e32 v22, 0xffff0000, v22
	v_add_f32_e32 v24, 1.0, v24
	v_rcp_f32_e32 v24, v24
	s_nop 0
	v_mul_f32_e32 v23, v24, v23
	v_mul_f32_e32 v21, v21, v23
	v_mul_f32_e32 v23, 0xbfb8aa3b, v22
	v_exp_f32_e32 v23, v23
	s_nop 0
	v_add_f32_e32 v23, 1.0, v23
	v_rcp_f32_e32 v23, v23
	s_nop 0
	v_mul_f32_e32 v22, v23, v22
	v_mul_f32_e32 v20, v20, v22
	v_cvt_pk_bf16_f32 v20, v21, v20
	global_store_dword v[18:19], v20, off
	v_mov_b32_e32 v20, v169
	v_bitop3_b32 v18, v80, s0, v230 bitop3:0xc8
	v_lshlrev_b32_e32 v114, 1, v18
	v_lshl_add_u64 v[18:19], s[80:81], 0, v[114:115]
	v_mul_f32_e32 v2, v2, v20
	v_mul_f32_e32 v3, v3, v20
	v_cndmask_b32_e32 v21, v2, v3, vcc
	ds_bpermute_b32 v21, v82, v21
	s_waitcnt lgkmcnt(0)
	v_cndmask_b32_e32 v22, v21, v2, vcc
	v_cndmask_b32_e32 v21, v3, v21, vcc
	v_lshl_add_u64 v[2:3], v[18:19], 0, v[72:73]
	v_mov_b32_e32 v23, v158
	v_lshlrev_b32_e32 v24, 16, v23
	v_mul_f32_e32 v25, 0xbfb8aa3b, v24
	v_exp_f32_e32 v25, v25
	v_and_b32_e32 v23, 0xffff0000, v23
	v_add_f32_e32 v25, 1.0, v25
	v_rcp_f32_e32 v25, v25
	s_nop 0
	v_mul_f32_e32 v24, v25, v24
	v_mul_f32_e32 v22, v22, v24
	v_mul_f32_e32 v24, 0xbfb8aa3b, v23
	v_exp_f32_e32 v24, v24
	s_nop 0
	v_add_f32_e32 v24, 1.0, v24
	v_rcp_f32_e32 v24, v24
	s_nop 0
	v_mul_f32_e32 v23, v24, v23
	v_mul_f32_e32 v21, v21, v23
	v_cvt_pk_bf16_f32 v21, v22, v21
	global_store_dword v[2:3], v21, off
	v_mul_f32_e32 v2, v4, v93
	v_mul_f32_e32 v3, v5, v95
	v_mul_f32_e32 v2, v2, v20
	v_mul_f32_e32 v3, v3, v20
	v_cndmask_b32_e32 v4, v2, v3, vcc
	ds_bpermute_b32 v4, v82, v4
	s_waitcnt lgkmcnt(0)
	v_cndmask_b32_e32 v5, v4, v2, vcc
	v_cndmask_b32_e32 v4, v3, v4, vcc
	v_lshl_add_u64 v[2:3], v[18:19], 0, v[70:71]
	v_mov_b32_e32 v21, v159
	v_lshlrev_b32_e32 v22, 16, v21
	v_mul_f32_e32 v23, 0xbfb8aa3b, v22
	v_exp_f32_e32 v23, v23
	v_and_b32_e32 v21, 0xffff0000, v21
	v_add_f32_e32 v23, 1.0, v23
	v_rcp_f32_e32 v23, v23
	s_nop 0
	v_mul_f32_e32 v22, v23, v22
	v_mul_f32_e32 v5, v5, v22
	v_mul_f32_e32 v22, 0xbfb8aa3b, v21
	v_exp_f32_e32 v22, v22
	s_nop 0
	v_add_f32_e32 v22, 1.0, v22
	v_rcp_f32_e32 v22, v22
	s_nop 0
	v_mul_f32_e32 v21, v22, v21
	v_mul_f32_e32 v4, v4, v21
	v_cvt_pk_bf16_f32 v4, v5, v4
	global_store_dword v[2:3], v4, off
	v_mul_f32_e32 v2, v6, v91
	v_mul_f32_e32 v3, v7, v92
	v_mul_f32_e32 v2, v2, v20
	v_mul_f32_e32 v3, v3, v20
	v_cndmask_b32_e32 v4, v2, v3, vcc
	ds_bpermute_b32 v4, v82, v4
	s_waitcnt lgkmcnt(0)
	v_cndmask_b32_e32 v5, v4, v2, vcc
	v_cndmask_b32_e32 v4, v3, v4, vcc
	v_lshl_add_u64 v[2:3], v[18:19], 0, v[68:69]
	v_mov_b32_e32 v6, v160
	v_lshlrev_b32_e32 v7, 16, v6
	v_mul_f32_e32 v21, 0xbfb8aa3b, v7
	v_exp_f32_e32 v21, v21
	v_and_b32_e32 v6, 0xffff0000, v6
	v_add_f32_e32 v21, 1.0, v21
	v_rcp_f32_e32 v21, v21
	s_nop 0
	v_mul_f32_e32 v7, v21, v7
	v_mul_f32_e32 v5, v5, v7
	v_mul_f32_e32 v7, 0xbfb8aa3b, v6
	v_exp_f32_e32 v7, v7
	s_nop 0
	v_add_f32_e32 v7, 1.0, v7
	v_rcp_f32_e32 v7, v7
	s_nop 0
	v_mul_f32_e32 v6, v7, v6
	v_mul_f32_e32 v4, v4, v6
	v_cvt_pk_bf16_f32 v4, v5, v4
	global_store_dword v[2:3], v4, off
	v_mul_f32_e32 v2, v8, v89
	v_mul_f32_e32 v3, v9, v90
	v_mul_f32_e32 v2, v2, v20
	v_mul_f32_e32 v3, v3, v20
	v_cndmask_b32_e32 v4, v2, v3, vcc
	ds_bpermute_b32 v4, v82, v4
	s_waitcnt lgkmcnt(0)
	v_cndmask_b32_e32 v5, v4, v2, vcc
	v_cndmask_b32_e32 v4, v3, v4, vcc
	v_lshl_add_u64 v[2:3], v[18:19], 0, v[66:67]
	v_mov_b32_e32 v6, v161
	v_lshlrev_b32_e32 v7, 16, v6
	v_mul_f32_e32 v8, 0xbfb8aa3b, v7
	v_exp_f32_e32 v8, v8
	v_and_b32_e32 v6, 0xffff0000, v6
	v_add_f32_e32 v8, 1.0, v8
	v_rcp_f32_e32 v8, v8
	s_nop 0
	v_mul_f32_e32 v7, v8, v7
	v_mul_f32_e32 v5, v5, v7
	v_mul_f32_e32 v7, 0xbfb8aa3b, v6
	v_exp_f32_e32 v7, v7
	s_nop 0
	v_add_f32_e32 v7, 1.0, v7
	v_rcp_f32_e32 v7, v7
	s_nop 0
	v_mul_f32_e32 v6, v7, v6
	v_mul_f32_e32 v4, v4, v6
	v_cvt_pk_bf16_f32 v4, v5, v4
	global_store_dword v[2:3], v4, off
	v_mul_f32_e32 v2, v10, v87
	v_mul_f32_e32 v3, v11, v88
	v_mul_f32_e32 v2, v2, v20
	v_mul_f32_e32 v3, v3, v20
	v_cndmask_b32_e32 v4, v2, v3, vcc
	ds_bpermute_b32 v4, v82, v4
	s_waitcnt lgkmcnt(0)
	v_cndmask_b32_e32 v5, v4, v2, vcc
	v_cndmask_b32_e32 v4, v3, v4, vcc
	v_lshl_add_u64 v[2:3], v[18:19], 0, v[56:57]
	v_mov_b32_e32 v6, v162
	v_lshlrev_b32_e32 v7, 16, v6
	v_mul_f32_e32 v8, 0xbfb8aa3b, v7
	v_exp_f32_e32 v8, v8
	v_and_b32_e32 v6, 0xffff0000, v6
	v_add_f32_e32 v8, 1.0, v8
	v_rcp_f32_e32 v8, v8
	s_nop 0
	v_mul_f32_e32 v7, v8, v7
	v_mul_f32_e32 v5, v5, v7
	v_mul_f32_e32 v7, 0xbfb8aa3b, v6
	v_exp_f32_e32 v7, v7
	s_nop 0
	v_add_f32_e32 v7, 1.0, v7
	v_rcp_f32_e32 v7, v7
	s_nop 0
	v_mul_f32_e32 v6, v7, v6
	v_mul_f32_e32 v4, v4, v6
	v_cvt_pk_bf16_f32 v4, v5, v4
	global_store_dword v[2:3], v4, off
	v_mul_f32_e32 v2, v12, v85
	v_mul_f32_e32 v3, v13, v86
	v_mul_f32_e32 v2, v2, v20
	v_mul_f32_e32 v3, v3, v20
	v_cndmask_b32_e32 v4, v2, v3, vcc
	ds_bpermute_b32 v4, v82, v4
	s_waitcnt lgkmcnt(0)
	v_cndmask_b32_e32 v5, v4, v2, vcc
	v_cndmask_b32_e32 v4, v3, v4, vcc
	v_lshl_add_u64 v[2:3], v[18:19], 0, v[54:55]
	v_mov_b32_e32 v6, v163
	v_lshlrev_b32_e32 v7, 16, v6
	v_mul_f32_e32 v8, 0xbfb8aa3b, v7
	v_exp_f32_e32 v8, v8
	v_and_b32_e32 v6, 0xffff0000, v6
	v_add_f32_e32 v8, 1.0, v8
	v_rcp_f32_e32 v8, v8
	s_nop 0
	v_mul_f32_e32 v7, v8, v7
	v_mul_f32_e32 v5, v5, v7
	v_mul_f32_e32 v7, 0xbfb8aa3b, v6
	v_exp_f32_e32 v7, v7
	s_nop 0
	v_add_f32_e32 v7, 1.0, v7
	v_rcp_f32_e32 v7, v7
	s_nop 0
	v_mul_f32_e32 v6, v7, v6
	v_mul_f32_e32 v4, v4, v6
	v_cvt_pk_bf16_f32 v4, v5, v4
	global_store_dword v[2:3], v4, off
	v_mul_f32_e32 v2, v14, v83
	v_mul_f32_e32 v3, v15, v84
	v_mul_f32_e32 v2, v2, v20
	v_mul_f32_e32 v3, v3, v20
	v_cndmask_b32_e32 v4, v2, v3, vcc
	ds_bpermute_b32 v4, v82, v4
	s_waitcnt lgkmcnt(0)
	v_cndmask_b32_e32 v5, v4, v2, vcc
	v_cndmask_b32_e32 v4, v3, v4, vcc
	v_lshl_add_u64 v[2:3], v[18:19], 0, v[52:53]
	v_mov_b32_e32 v6, v164
	v_lshlrev_b32_e32 v7, 16, v6
	v_mul_f32_e32 v8, 0xbfb8aa3b, v7
	v_exp_f32_e32 v8, v8
	v_and_b32_e32 v6, 0xffff0000, v6
	v_add_f32_e32 v8, 1.0, v8
	v_rcp_f32_e32 v8, v8
	s_nop 0
	v_mul_f32_e32 v7, v8, v7
	v_mul_f32_e32 v5, v5, v7
	v_mul_f32_e32 v7, 0xbfb8aa3b, v6
	v_exp_f32_e32 v7, v7
	s_nop 0
	v_add_f32_e32 v7, 1.0, v7
	v_rcp_f32_e32 v7, v7
	s_nop 0
	v_mul_f32_e32 v6, v7, v6
	v_mul_f32_e32 v4, v4, v6
	v_cvt_pk_bf16_f32 v4, v5, v4
	global_store_dword v[2:3], v4, off
	v_mul_f32_e32 v2, v16, v78
	v_mul_f32_e32 v3, v17, v79
	v_mul_f32_e32 v2, v2, v20
	v_mul_f32_e32 v3, v3, v20
	v_cndmask_b32_e32 v4, v2, v3, vcc
	ds_bpermute_b32 v4, v82, v4
	s_waitcnt lgkmcnt(0)
	v_cndmask_b32_e32 v5, v4, v2, vcc
	v_cndmask_b32_e32 v4, v3, v4, vcc
	v_lshl_add_u64 v[2:3], v[18:19], 0, v[50:51]
	v_mov_b32_e32 v6, v165
	v_lshlrev_b32_e32 v7, 16, v6
	v_mul_f32_e32 v8, 0xbfb8aa3b, v7
	v_exp_f32_e32 v8, v8
	v_and_b32_e32 v6, 0xffff0000, v6
	v_add_f32_e32 v8, 1.0, v8
	v_rcp_f32_e32 v8, v8
	s_nop 0
	v_mul_f32_e32 v7, v8, v7
	v_mul_f32_e32 v5, v5, v7
	v_mul_f32_e32 v7, 0xbfb8aa3b, v6
	v_exp_f32_e32 v7, v7
	s_nop 0
	v_add_f32_e32 v7, 1.0, v7
	v_rcp_f32_e32 v7, v7
	s_nop 0
	v_mul_f32_e32 v6, v7, v6
	v_mul_f32_e32 v4, v4, v6
	v_cvt_pk_bf16_f32 v4, v5, v4
	global_store_dword v[2:3], v4, off
	s_nop 0
	s_nop 0
	s_nop 0
.LBB0_900:
	s_or_b64 exec, exec, s[36:37]
	v_readlane_b32 s0, v254, 7
	v_add_u32_e32 v1, s33, v1
	v_add_u32_e32 v228, s33, v228
	v_add_u32_e32 v227, s0, v227
	s_movk_i32 s0, 0x5ff
	v_cmp_lt_i32_e32 vcc, s0, v1
	s_or_b64 s[70:71], vcc, s[70:71]
	s_andn2_b64 exec, exec, s[70:71]
	s_cbranch_execz .LBB0_963

.LBB0_1069:
	s_or_b64 exec, exec, s[6:7]
	v_cvt_f32_u32_e32 v5, v3
	s_waitcnt vmcnt(0)
	v_readfirstlane_b32 s2, v4
	v_sub_u32_e32 v4, 0, v3
	v_rcp_iflag_f32_e32 v5, v5
	v_add_u32_e32 v6, s2, v1
	v_mul_f32_e32 v5, 0x4f7ffffe, v5
	v_cvt_u32_f32_e32 v5, v5
	v_mul_lo_u32 v1, v4, v5
	v_mul_hi_u32 v1, v5, v1
	v_add_u32_e32 v1, v5, v1
	v_mul_hi_u32 v1, v6, v1
	v_mul_lo_u32 v4, v1, v3
	v_sub_u32_e32 v4, v6, v4
	v_add_u32_e32 v5, 1, v1
	v_cmp_ge_u32_e32 vcc, v4, v3
	s_nop 1
	v_cndmask_b32_e32 v1, v1, v5, vcc
	v_sub_u32_e32 v5, v4, v3
	v_cndmask_b32_e32 v4, v4, v5, vcc
	v_add_u32_e32 v5, 1, v1
	v_cmp_ge_u32_e32 vcc, v4, v3
	v_add_u32_e32 v4, 1, v6
	s_nop 0
	v_cndmask_b32_e32 v1, v1, v5, vcc
	v_mul_lo_u32 v5, v3, v1
	v_add_u32_e32 v3, v5, v3
	v_cmp_ne_u32_e32 vcc, v4, v3
	s_and_saveexec_b64 s[2:3], vcc
	s_xor_b64 s[2:3], exec, s[2:3]
	s_cbranch_execz .LBB0_1083
	s_add_i32 s6, s20, 0x900
	s_mov_b32 s7, 0
	s_lshl_b64 s[6:7], s[6:7], 2
	s_add_u32 s8, s62, 0xf71d500
	s_addc_u32 s9, s63, 0
	s_waitcnt lgkmcnt(0)
	v_mov_b32_e32 v2, 0
	global_load_dword v3, v2, s[8:9] sc1
	s_waitcnt vmcnt(0)
	v_cmp_eq_u32_e32 vcc, v3, v1
	s_and_saveexec_b64 s[6:7], vcc
	s_cbranch_execz .LBB0_1082
	s_mov_b32 s21, 1
	s_mov_b64 s[10:11], 0
	s_branch .LBB0_1073

.LBB0_1132:
	s_or_b64 exec, exec, s[8:9]
	v_cvt_f32_u32_e32 v5, v3
	s_waitcnt vmcnt(0)
	v_readfirstlane_b32 s2, v4
	v_sub_u32_e32 v4, 0, v3
	v_rcp_iflag_f32_e32 v5, v5
	v_add_u32_e32 v6, s2, v1
	v_mul_f32_e32 v5, 0x4f7ffffe, v5
	v_cvt_u32_f32_e32 v5, v5
	v_mul_lo_u32 v1, v4, v5
	v_mul_hi_u32 v1, v5, v1
	v_add_u32_e32 v1, v5, v1
	v_mul_hi_u32 v1, v6, v1
	v_mul_lo_u32 v4, v1, v3
	v_sub_u32_e32 v4, v6, v4
	v_add_u32_e32 v5, 1, v1
	v_cmp_ge_u32_e32 vcc, v4, v3
	s_nop 1
	v_cndmask_b32_e32 v1, v1, v5, vcc
	v_sub_u32_e32 v5, v4, v3
	v_cndmask_b32_e32 v4, v4, v5, vcc
	v_add_u32_e32 v5, 1, v1
	v_cmp_ge_u32_e32 vcc, v4, v3
	v_add_u32_e32 v4, 1, v6
	s_nop 0
	v_cndmask_b32_e32 v1, v1, v5, vcc
	v_mul_lo_u32 v5, v3, v1
	v_add_u32_e32 v3, v5, v3
	v_cmp_ne_u32_e32 vcc, v4, v3
	s_and_saveexec_b64 s[2:3], vcc
	s_xor_b64 s[2:3], exec, s[2:3]
	s_cbranch_execz .LBB0_1146
	s_add_i32 s8, s24, 0x900
	s_mov_b32 s9, 0
	s_lshl_b64 s[8:9], s[8:9], 2
	s_add_u32 s10, s62, 0xf71d500
	s_addc_u32 s11, s63, 0
	s_waitcnt lgkmcnt(0)
	v_mov_b32_e32 v2, 0
	global_load_dword v3, v2, s[10:11] sc1
	s_waitcnt vmcnt(0)
	v_cmp_eq_u32_e32 vcc, v3, v1
	s_and_saveexec_b64 s[8:9], vcc
	s_cbranch_execz .LBB0_1145
	s_mov_b32 s25, 1
	s_mov_b64 s[12:13], 0
	s_branch .LBB0_1136

.LBB0_1424:
	s_or_b64 exec, exec, s[8:9]
	v_cvt_f32_u32_e32 v5, v3
	s_waitcnt vmcnt(0)
	v_readfirstlane_b32 s2, v4
	v_sub_u32_e32 v4, 0, v3
	v_rcp_iflag_f32_e32 v5, v5
	v_add_u32_e32 v6, s2, v1
	v_mul_f32_e32 v5, 0x4f7ffffe, v5
	v_cvt_u32_f32_e32 v5, v5
	v_mul_lo_u32 v1, v4, v5
	v_mul_hi_u32 v1, v5, v1
	v_add_u32_e32 v1, v5, v1
	v_mul_hi_u32 v1, v6, v1
	v_mul_lo_u32 v4, v1, v3
	v_sub_u32_e32 v4, v6, v4
	v_add_u32_e32 v5, 1, v1
	v_cmp_ge_u32_e32 vcc, v4, v3
	s_nop 1
	v_cndmask_b32_e32 v1, v1, v5, vcc
	v_sub_u32_e32 v5, v4, v3
	v_cndmask_b32_e32 v4, v4, v5, vcc
	v_add_u32_e32 v5, 1, v1
	v_cmp_ge_u32_e32 vcc, v4, v3
	v_add_u32_e32 v4, 1, v6
	s_nop 0
	v_cndmask_b32_e32 v1, v1, v5, vcc
	v_mul_lo_u32 v5, v3, v1
	v_add_u32_e32 v3, v5, v3
	v_cmp_ne_u32_e32 vcc, v4, v3
	s_and_saveexec_b64 s[2:3], vcc
	s_xor_b64 s[2:3], exec, s[2:3]
	s_cbranch_execz .LBB0_1438
	s_add_i32 s8, s33, 0x900
	s_mov_b32 s9, 0
	s_lshl_b64 s[8:9], s[8:9], 2
	s_add_u32 s10, s62, 0xf71d500
	s_addc_u32 s11, s63, 0
	s_waitcnt lgkmcnt(0)
	v_mov_b32_e32 v2, 0
	global_load_dword v3, v2, s[10:11] sc1
	s_waitcnt vmcnt(0)
	v_cmp_eq_u32_e32 vcc, v3, v1
	s_and_saveexec_b64 s[8:9], vcc
	s_cbranch_execz .LBB0_1437
	s_mov_b32 s34, 1
	s_mov_b64 s[12:13], 0
	s_branch .LBB0_1428

.LBB0_1558:
	s_or_b64 exec, exec, s[10:11]
	v_cvt_f32_u32_e32 v5, v3
	s_waitcnt vmcnt(0)
	v_readfirstlane_b32 s2, v4
	v_sub_u32_e32 v4, 0, v3
	v_rcp_iflag_f32_e32 v5, v5
	v_add_u32_e32 v6, s2, v2
	v_mul_f32_e32 v5, 0x4f7ffffe, v5
	v_cvt_u32_f32_e32 v5, v5
	v_mul_lo_u32 v2, v4, v5
	v_mul_hi_u32 v2, v5, v2
	v_add_u32_e32 v2, v5, v2
	v_mul_hi_u32 v2, v6, v2
	v_mul_lo_u32 v4, v2, v3
	v_sub_u32_e32 v4, v6, v4
	v_add_u32_e32 v5, 1, v2
	v_cmp_ge_u32_e32 vcc, v4, v3
	s_nop 1
	v_cndmask_b32_e32 v2, v2, v5, vcc
	v_sub_u32_e32 v5, v4, v3
	v_cndmask_b32_e32 v4, v4, v5, vcc
	v_add_u32_e32 v5, 1, v2
	v_cmp_ge_u32_e32 vcc, v4, v3
	v_add_u32_e32 v4, 1, v6
	s_nop 0
	v_cndmask_b32_e32 v2, v2, v5, vcc
	v_mul_lo_u32 v5, v3, v2
	v_add_u32_e32 v3, v5, v3
	v_cmp_ne_u32_e32 vcc, v4, v3
	s_and_saveexec_b64 s[2:3], vcc
	s_xor_b64 s[2:3], exec, s[2:3]
	s_cbranch_execz .LBB0_1572
	s_add_i32 s10, s33, 0x900
	s_mov_b32 s11, 0
	s_lshl_b64 s[10:11], s[10:11], 2
	s_add_u32 s12, s62, 0xf71d500
	s_addc_u32 s13, s63, 0
	s_waitcnt lgkmcnt(0)
	v_mov_b32_e32 v1, 0
	global_load_dword v3, v1, s[12:13] sc1
	s_waitcnt vmcnt(0)
	v_cmp_eq_u32_e32 vcc, v3, v2
	s_and_saveexec_b64 s[10:11], vcc
	s_cbranch_execz .LBB0_1571
	s_mov_b32 s36, 1
	s_mov_b64 s[24:25], 0
	s_branch .LBB0_1562

.LBB0_1595:
	v_add_u32_e32 v2, s1, v168
	v_ashrrev_i32_e32 v3, 31, v2
	v_add_u32_e32 v4, 16, v2
	v_lshlrev_b64 v[2:3], 11, v[2:3]
	v_ashrrev_i32_e32 v5, 31, v4
	v_lshl_add_u64 v[2:3], v[156:157], 0, v[2:3]
	v_lshlrev_b64 v[6:7], 11, v[4:5]
	global_load_dwordx4 v[2:5], v[2:3], off
	v_lshl_add_u64 v[6:7], v[156:157], 0, v[6:7]
	global_load_dwordx4 v[114:117], v[6:7], off
	s_add_i32 s1, s1, 32
	s_cmpk_eq_i32 s1, 0x80
	s_waitcnt vmcnt(1)
	v_mfma_f32_32x32x16_bf16 v[176:191], v[2:5], v[130:133], 0
	v_mfma_f32_32x32x16_bf16 v[192:207], v[2:5], v[134:137], 0
	v_mfma_f32_32x32x16_bf16 v[208:223], v[2:5], v[138:141], 0
	v_mfma_f32_32x32x16_bf16 v[224:239], v[2:5], v[142:145], 0
	s_waitcnt vmcnt(0)
	v_mfma_f32_32x32x16_bf16 v[50:65], v[114:117], v[130:133], 0
	v_mfma_f32_32x32x16_bf16 v[66:81], v[114:117], v[134:137], 0
	v_mfma_f32_32x32x16_bf16 v[82:97], v[114:117], v[138:141], 0
	v_mfma_f32_32x32x16_bf16 v[98:113], v[114:117], v[142:145], 0
	s_nop 7
	v_fma_f32 v244, -v153, v35, v176
	v_fma_f32 v245, v153, v34, v192
	v_fma_f32 v246, -v155, v119, v208
	v_fma_f32 v247, v155, v118, v224
	v_fma_f32 v240, v152, v34, v244
	v_fma_f32 v241, v152, v35, v245
	v_fma_f32 v242, v154, v118, v246
	v_fma_f32 v243, v154, v119, v247
	v_fma_f32 v244, -v153, v241, v177
	v_fma_f32 v245, v153, v240, v193
	v_fma_f32 v246, -v155, v243, v209
	v_fma_f32 v247, v155, v242, v225
	v_fma_f32 v34, v152, v240, v244
	v_fma_f32 v35, v152, v241, v245
	v_fma_f32 v118, v154, v242, v246
	v_fma_f32 v119, v154, v243, v247
	v_fma_f32 v244, -v153, v35, v178
	v_fma_f32 v245, v153, v34, v194
	v_fma_f32 v246, -v155, v119, v210
	v_fma_f32 v247, v155, v118, v226
	v_fma_f32 v240, v152, v34, v244
	v_fma_f32 v241, v152, v35, v245
	v_fma_f32 v242, v154, v118, v246
	v_fma_f32 v243, v154, v119, v247
	v_fma_f32 v244, -v153, v241, v179
	v_fma_f32 v245, v153, v240, v195
	v_fma_f32 v246, -v155, v243, v211
	v_fma_f32 v247, v155, v242, v227
	v_fma_f32 v34, v152, v240, v244
	v_fma_f32 v35, v152, v241, v245
	v_fma_f32 v118, v154, v242, v246
	v_fma_f32 v119, v154, v243, v247
	v_fma_f32 v244, -v153, v35, v180
	v_fma_f32 v245, v153, v34, v196
	v_fma_f32 v246, -v155, v119, v212
	v_fma_f32 v247, v155, v118, v228
	v_fma_f32 v240, v152, v34, v244
	v_fma_f32 v241, v152, v35, v245
	v_fma_f32 v242, v154, v118, v246
	v_fma_f32 v243, v154, v119, v247
	v_fma_f32 v244, -v153, v241, v181
	v_fma_f32 v245, v153, v240, v197
	v_fma_f32 v246, -v155, v243, v213
	v_fma_f32 v247, v155, v242, v229
	v_fma_f32 v34, v152, v240, v244
	v_fma_f32 v35, v152, v241, v245
	v_fma_f32 v118, v154, v242, v246
	v_fma_f32 v119, v154, v243, v247
	v_fma_f32 v244, -v153, v35, v182
	v_fma_f32 v245, v153, v34, v198
	v_fma_f32 v246, -v155, v119, v214
	v_fma_f32 v247, v155, v118, v230
	v_fma_f32 v240, v152, v34, v244
	v_fma_f32 v241, v152, v35, v245
	v_fma_f32 v242, v154, v118, v246
	v_fma_f32 v243, v154, v119, v247
	v_fma_f32 v244, -v153, v241, v183
	v_fma_f32 v245, v153, v240, v199
	v_fma_f32 v246, -v155, v243, v215
	v_fma_f32 v247, v155, v242, v231
	v_fma_f32 v34, v152, v240, v244
	v_fma_f32 v35, v152, v241, v245
	v_fma_f32 v118, v154, v242, v246
	v_fma_f32 v119, v154, v243, v247
	v_fma_f32 v244, -v153, v35, v184
	v_fma_f32 v245, v153, v34, v200
	v_fma_f32 v246, -v155, v119, v216
	v_fma_f32 v247, v155, v118, v232
	v_fma_f32 v240, v152, v34, v244
	v_fma_f32 v241, v152, v35, v245
	v_fma_f32 v242, v154, v118, v246
	v_fma_f32 v243, v154, v119, v247
	v_fma_f32 v244, -v153, v241, v185
	v_fma_f32 v245, v153, v240, v201
	v_fma_f32 v246, -v155, v243, v217
	v_fma_f32 v247, v155, v242, v233
	v_fma_f32 v34, v152, v240, v244
	v_fma_f32 v35, v152, v241, v245
	v_fma_f32 v118, v154, v242, v246
	v_fma_f32 v119, v154, v243, v247
	v_fma_f32 v244, -v153, v35, v186
	v_fma_f32 v245, v153, v34, v202
	v_fma_f32 v246, -v155, v119, v218
	v_fma_f32 v247, v155, v118, v234
	v_fma_f32 v240, v152, v34, v244
	v_fma_f32 v241, v152, v35, v245
	v_fma_f32 v242, v154, v118, v246
	v_fma_f32 v243, v154, v119, v247
	v_fma_f32 v244, -v153, v241, v187
	v_fma_f32 v245, v153, v240, v203
	v_fma_f32 v246, -v155, v243, v219
	v_fma_f32 v247, v155, v242, v235
	v_fma_f32 v34, v152, v240, v244
	v_fma_f32 v35, v152, v241, v245
	v_fma_f32 v118, v154, v242, v246
	v_fma_f32 v119, v154, v243, v247
	v_fma_f32 v244, -v153, v35, v188
	v_fma_f32 v245, v153, v34, v204
	v_fma_f32 v246, -v155, v119, v220
	v_fma_f32 v247, v155, v118, v236
	v_fma_f32 v240, v152, v34, v244
	v_fma_f32 v241, v152, v35, v245
	v_fma_f32 v242, v154, v118, v246
	v_fma_f32 v243, v154, v119, v247
	v_fma_f32 v244, -v153, v241, v189
	v_fma_f32 v245, v153, v240, v205
	v_fma_f32 v246, -v155, v243, v221
	v_fma_f32 v247, v155, v242, v237
	v_fma_f32 v34, v152, v240, v244
	v_fma_f32 v35, v152, v241, v245
	v_fma_f32 v118, v154, v242, v246
	v_fma_f32 v119, v154, v243, v247
	v_fma_f32 v244, -v153, v35, v190
	v_fma_f32 v245, v153, v34, v206
	v_fma_f32 v246, -v155, v119, v222
	v_fma_f32 v247, v155, v118, v238
	v_fma_f32 v240, v152, v34, v244
	v_fma_f32 v241, v152, v35, v245
	v_fma_f32 v242, v154, v118, v246
	v_fma_f32 v243, v154, v119, v247
	v_fma_f32 v244, -v153, v241, v191
	v_fma_f32 v245, v153, v240, v207
	v_fma_f32 v246, -v155, v243, v223
	v_fma_f32 v247, v155, v242, v239
	v_fma_f32 v34, v152, v240, v244
	v_fma_f32 v35, v152, v241, v245
	v_fma_f32 v118, v154, v242, v246
	v_fma_f32 v119, v154, v243, v247
	v_fma_f32 v244, -v153, v35, v50
	v_fma_f32 v245, v153, v34, v66
	v_fma_f32 v246, -v155, v119, v82
	v_fma_f32 v247, v155, v118, v98
	v_fma_f32 v240, v152, v34, v244
	v_fma_f32 v241, v152, v35, v245
	v_fma_f32 v242, v154, v118, v246
	v_fma_f32 v243, v154, v119, v247
	v_fma_f32 v244, -v153, v241, v51
	v_fma_f32 v245, v153, v240, v67
	v_fma_f32 v246, -v155, v243, v83
	v_fma_f32 v247, v155, v242, v99
	v_fma_f32 v34, v152, v240, v244
	v_fma_f32 v35, v152, v241, v245
	v_fma_f32 v118, v154, v242, v246
	v_fma_f32 v119, v154, v243, v247
	v_fma_f32 v244, -v153, v35, v52
	v_fma_f32 v245, v153, v34, v68
	v_fma_f32 v246, -v155, v119, v84
	v_fma_f32 v247, v155, v118, v100
	v_fma_f32 v240, v152, v34, v244
	v_fma_f32 v241, v152, v35, v245
	v_fma_f32 v242, v154, v118, v246
	v_fma_f32 v243, v154, v119, v247
	v_fma_f32 v244, -v153, v241, v53
	v_fma_f32 v245, v153, v240, v69
	v_fma_f32 v246, -v155, v243, v85
	v_fma_f32 v247, v155, v242, v101
	v_fma_f32 v34, v152, v240, v244
	v_fma_f32 v35, v152, v241, v245
	v_fma_f32 v118, v154, v242, v246
	v_fma_f32 v119, v154, v243, v247
	v_fma_f32 v244, -v153, v35, v54
	v_fma_f32 v245, v153, v34, v70
	v_fma_f32 v246, -v155, v119, v86
	v_fma_f32 v247, v155, v118, v102
	v_fma_f32 v240, v152, v34, v244
	v_fma_f32 v241, v152, v35, v245
	v_fma_f32 v242, v154, v118, v246
	v_fma_f32 v243, v154, v119, v247
	v_fma_f32 v244, -v153, v241, v55
	v_fma_f32 v245, v153, v240, v71
	v_fma_f32 v246, -v155, v243, v87
	v_fma_f32 v247, v155, v242, v103
	v_fma_f32 v34, v152, v240, v244
	v_fma_f32 v35, v152, v241, v245
	v_fma_f32 v118, v154, v242, v246
	v_fma_f32 v119, v154, v243, v247
	v_fma_f32 v244, -v153, v35, v56
	v_fma_f32 v245, v153, v34, v72
	v_fma_f32 v246, -v155, v119, v88
	v_fma_f32 v247, v155, v118, v104
	v_fma_f32 v240, v152, v34, v244
	v_fma_f32 v241, v152, v35, v245
	v_fma_f32 v242, v154, v118, v246
	v_fma_f32 v243, v154, v119, v247
	v_fma_f32 v244, -v153, v241, v57
	v_fma_f32 v245, v153, v240, v73
	v_fma_f32 v246, -v155, v243, v89
	v_fma_f32 v247, v155, v242, v105
	v_fma_f32 v34, v152, v240, v244
	v_fma_f32 v35, v152, v241, v245
	v_fma_f32 v118, v154, v242, v246
	v_fma_f32 v119, v154, v243, v247
	v_fma_f32 v244, -v153, v35, v58
	v_fma_f32 v245, v153, v34, v74
	v_fma_f32 v246, -v155, v119, v90
	v_fma_f32 v247, v155, v118, v106
	v_fma_f32 v240, v152, v34, v244
	v_fma_f32 v241, v152, v35, v245
	v_fma_f32 v242, v154, v118, v246
	v_fma_f32 v243, v154, v119, v247
	v_fma_f32 v244, -v153, v241, v59
	v_fma_f32 v245, v153, v240, v75
	v_fma_f32 v246, -v155, v243, v91
	v_fma_f32 v247, v155, v242, v107
	v_fma_f32 v34, v152, v240, v244
	v_fma_f32 v35, v152, v241, v245
	v_fma_f32 v118, v154, v242, v246
	v_fma_f32 v119, v154, v243, v247
	v_fma_f32 v244, -v153, v35, v60
	v_fma_f32 v245, v153, v34, v76
	v_fma_f32 v246, -v155, v119, v92
	v_fma_f32 v247, v155, v118, v108
	v_fma_f32 v240, v152, v34, v244
	v_fma_f32 v241, v152, v35, v245
	v_fma_f32 v242, v154, v118, v246
	v_fma_f32 v243, v154, v119, v247
	v_fma_f32 v244, -v153, v241, v61
	v_fma_f32 v245, v153, v240, v77
	v_fma_f32 v246, -v155, v243, v93
	v_fma_f32 v247, v155, v242, v109
	v_fma_f32 v34, v152, v240, v244
	v_fma_f32 v35, v152, v241, v245
	v_fma_f32 v118, v154, v242, v246
	v_fma_f32 v119, v154, v243, v247
	v_fma_f32 v244, -v153, v35, v62
	v_fma_f32 v245, v153, v34, v78
	v_fma_f32 v246, -v155, v119, v94
	v_fma_f32 v247, v155, v118, v110
	v_fma_f32 v240, v152, v34, v244
	v_fma_f32 v241, v152, v35, v245
	v_fma_f32 v242, v154, v118, v246
	v_fma_f32 v243, v154, v119, v247
	v_fma_f32 v244, -v153, v241, v63
	v_fma_f32 v245, v153, v240, v79
	v_fma_f32 v246, -v155, v243, v95
	v_fma_f32 v247, v155, v242, v111
	v_fma_f32 v34, v152, v240, v244
	v_fma_f32 v35, v152, v241, v245
	v_fma_f32 v118, v154, v242, v246
	v_fma_f32 v119, v154, v243, v247
	v_fma_f32 v244, -v153, v35, v64
	v_fma_f32 v245, v153, v34, v80
	v_fma_f32 v246, -v155, v119, v96
	v_fma_f32 v247, v155, v118, v112
	v_fma_f32 v240, v152, v34, v244
	v_fma_f32 v241, v152, v35, v245
	v_fma_f32 v242, v154, v118, v246
	v_fma_f32 v243, v154, v119, v247
	v_fma_f32 v244, -v153, v241, v65
	v_fma_f32 v245, v153, v240, v81
	v_fma_f32 v246, -v155, v243, v97
	v_fma_f32 v247, v155, v242, v113
	v_fma_f32 v34, v152, v240, v244
	v_fma_f32 v35, v152, v241, v245
	v_fma_f32 v118, v154, v242, v246
	v_fma_f32 v119, v154, v243, v247
	s_cbranch_scc0 .LBB0_1595
	s_nop 0
	s_nop 0
	s_nop 0
	s_nop 0
	s_nop 0
	s_nop 0
	s_nop 0
	s_nop 0
	v_lshlrev_b32_e32 v2, 7, v167
	v_or3_b32 v2, v2, v163, v166
	v_ashrrev_i32_e32 v3, 31, v2
	v_lshlrev_b64 v[2:3], 9, v[2:3]
	s_add_i32 s0, s0, s96
	v_lshl_add_u64 v[2:3], v[150:151], 0, v[2:3]
	s_cmpk_gt_i32 s0, 0x1ff
	global_store_dwordx2 v[2:3], v[34:35], off
	global_store_dwordx2 v[2:3], v[118:119], off offset:256
	s_cbranch_scc0 .LBB0_1594

.LBB0_1615:
	s_or_b64 exec, exec, s[12:13]
	v_cvt_f32_u32_e32 v5, v3
	s_waitcnt vmcnt(0)
	v_readfirstlane_b32 s10, v4
	v_sub_u32_e32 v4, 0, v3
	v_rcp_iflag_f32_e32 v5, v5
	v_add_u32_e32 v6, s10, v1
	v_mul_f32_e32 v5, 0x4f7ffffe, v5
	v_cvt_u32_f32_e32 v5, v5
	v_mul_lo_u32 v1, v4, v5
	v_mul_hi_u32 v1, v5, v1
	v_add_u32_e32 v1, v5, v1
	v_mul_hi_u32 v1, v6, v1
	v_mul_lo_u32 v4, v1, v3
	v_sub_u32_e32 v4, v6, v4
	v_add_u32_e32 v5, 1, v1
	v_cmp_ge_u32_e32 vcc, v4, v3
	s_nop 1
	v_cndmask_b32_e32 v1, v1, v5, vcc
	v_sub_u32_e32 v5, v4, v3
	v_cndmask_b32_e32 v4, v4, v5, vcc
	v_add_u32_e32 v5, 1, v1
	v_cmp_ge_u32_e32 vcc, v4, v3
	v_add_u32_e32 v4, 1, v6
	s_nop 0
	v_cndmask_b32_e32 v1, v1, v5, vcc
	v_mul_lo_u32 v5, v3, v1
	v_add_u32_e32 v3, v5, v3
	v_cmp_ne_u32_e32 vcc, v4, v3
	s_and_saveexec_b64 s[10:11], vcc
	s_xor_b64 s[10:11], exec, s[10:11]
	s_cbranch_execz .LBB0_1629
	s_add_i32 s12, s33, 0x900
	s_mov_b32 s13, 0
	s_lshl_b64 s[12:13], s[12:13], 2
	s_add_u32 s28, s62, 0xf71d500
	s_addc_u32 s29, s63, 0
	s_waitcnt lgkmcnt(0)
	v_mov_b32_e32 v2, 0
	global_load_dword v3, v2, s[28:29] sc1
	s_waitcnt vmcnt(0)
	v_cmp_eq_u32_e32 vcc, v3, v1
	s_and_saveexec_b64 s[12:13], vcc
	s_cbranch_execz .LBB0_1628
	s_mov_b32 s42, 1
	s_mov_b64 s[30:31], 0
	s_branch .LBB0_1619

.LBB0_1656:
	v_add_u32_e32 v16, 0xfffffc40, v8
	v_ashrrev_i32_e32 v17, 31, v16
	v_lshlrev_b64 v[16:17], 9, v[16:17]
	v_lshl_add_u64 v[18:19], v[4:5], 0, v[16:17]
	v_lshl_add_u64 v[20:21], v[6:7], 0, v[16:17]
	s_mov_b64 vcc, 0x8000
	global_load_dwordx2 v[100:101], v[18:19], off
	v_lshl_add_u64 v[18:19], v[18:19], 0, vcc
	global_load_dwordx2 v[102:103], v[18:19], off
	v_lshl_add_u64 v[18:19], v[18:19], 0, vcc
	global_load_dwordx2 v[104:105], v[18:19], off
	v_lshl_add_u64 v[18:19], v[18:19], 0, vcc
	global_load_dwordx2 v[106:107], v[18:19], off
	v_lshl_add_u64 v[18:19], v[18:19], 0, vcc
	global_load_dwordx2 v[108:109], v[18:19], off
	v_lshl_add_u64 v[18:19], v[18:19], 0, vcc
	global_load_dwordx2 v[110:111], v[18:19], off
	v_lshl_add_u64 v[18:19], v[18:19], 0, vcc
	global_load_dwordx2 v[112:113], v[18:19], off
	v_lshl_add_u64 v[18:19], v[18:19], 0, vcc
	global_load_dwordx2 v[114:115], v[18:19], off
	v_lshl_add_u64 v[18:19], v[18:19], 0, vcc
	global_load_dwordx2 v[116:117], v[18:19], off
	v_lshl_add_u64 v[18:19], v[18:19], 0, vcc
	global_load_dwordx2 v[118:119], v[18:19], off
	v_lshl_add_u64 v[18:19], v[18:19], 0, vcc
	global_load_dwordx2 v[120:121], v[18:19], off
	v_lshl_add_u64 v[18:19], v[18:19], 0, vcc
	global_load_dwordx2 v[122:123], v[18:19], off
	v_lshl_add_u64 v[18:19], v[18:19], 0, vcc
	global_load_dwordx2 v[124:125], v[18:19], off
	v_lshl_add_u64 v[18:19], v[18:19], 0, vcc
	global_load_dwordx2 v[126:127], v[18:19], off
	v_lshl_add_u64 v[18:19], v[18:19], 0, vcc
	global_load_dwordx2 v[128:129], v[18:19], off
	v_lshl_add_u64 v[18:19], v[18:19], 0, vcc
	global_load_dwordx2 v[130:131], v[18:19], off
	v_lshl_add_u64 v[18:19], v[18:19], 0, vcc
	global_load_dwordx2 v[132:133], v[18:19], off
	v_lshl_add_u64 v[18:19], v[18:19], 0, vcc
	global_load_dwordx2 v[134:135], v[18:19], off
	v_lshl_add_u64 v[18:19], v[18:19], 0, vcc
	global_load_dwordx2 v[136:137], v[18:19], off
	v_lshl_add_u64 v[18:19], v[18:19], 0, vcc
	global_load_dwordx2 v[138:139], v[18:19], off
	v_lshl_add_u64 v[18:19], v[18:19], 0, vcc
	global_load_dwordx2 v[140:141], v[18:19], off
	v_lshl_add_u64 v[18:19], v[18:19], 0, vcc
	global_load_dwordx2 v[142:143], v[18:19], off
	v_lshl_add_u64 v[18:19], v[18:19], 0, vcc
	global_load_dwordx2 v[144:145], v[18:19], off
	v_lshl_add_u64 v[18:19], v[18:19], 0, vcc
	global_load_dwordx2 v[146:147], v[18:19], off
	v_lshl_add_u64 v[18:19], v[18:19], 0, vcc
	global_load_dwordx2 v[148:149], v[18:19], off
	v_lshl_add_u64 v[18:19], v[18:19], 0, vcc
	global_load_dwordx2 v[150:151], v[18:19], off
	v_lshl_add_u64 v[18:19], v[18:19], 0, vcc
	global_load_dwordx2 v[152:153], v[18:19], off
	v_lshl_add_u64 v[18:19], v[18:19], 0, vcc
	global_load_dwordx2 v[154:155], v[18:19], off
	v_lshl_add_u64 v[18:19], v[18:19], 0, vcc
	global_load_dwordx2 v[156:157], v[18:19], off
	v_lshl_add_u64 v[18:19], v[18:19], 0, vcc
	global_load_dwordx2 v[158:159], v[18:19], off
	v_lshl_add_u64 v[18:19], v[18:19], 0, vcc
	global_store_dwordx2 v[20:21], v[14:15], off
	v_lshl_add_u64 v[20:21], v[20:21], 0, vcc
	v_pk_mul_f32 v[22:23], v[12:13], v[14:15]
	global_load_dwordx2 v[160:161], v[18:19], off
	v_lshl_add_u64 v[18:19], v[18:19], 0, vcc
	v_pk_fma_f32 v[86:87], v[10:11], v[14:15], v[22:23] op_sel:[0,0,1] op_sel_hi:[1,1,0] neg_lo:[0,0,1] neg_hi:[0,0,1]
	v_pk_fma_f32 v[14:15], v[10:11], v[14:15], v[22:23] op_sel:[0,0,1] op_sel_hi:[1,1,0]
	s_nop 0
	v_mov_b32_e32 v87, v15
	s_waitcnt vmcnt(31)
	v_pk_add_f32 v[14:15], v[86:87], v[100:101]
	global_store_dwordx2 v[20:21], v[14:15], off
	v_lshl_add_u64 v[20:21], v[20:21], 0, vcc
	v_pk_mul_f32 v[22:23], v[12:13], v[14:15]
	global_load_dwordx2 v[162:163], v[18:19], off
	v_lshl_add_u64 v[18:19], v[18:19], 0, vcc
	v_pk_fma_f32 v[86:87], v[10:11], v[14:15], v[22:23] op_sel:[0,0,1] op_sel_hi:[1,1,0] neg_lo:[0,0,1] neg_hi:[0,0,1]
	v_pk_fma_f32 v[14:15], v[10:11], v[14:15], v[22:23] op_sel:[0,0,1] op_sel_hi:[1,1,0]
	s_nop 0
	v_mov_b32_e32 v87, v15
	s_waitcnt vmcnt(32)
	v_pk_add_f32 v[14:15], v[86:87], v[102:103]
	global_store_dwordx2 v[20:21], v[14:15], off
	v_lshl_add_u64 v[20:21], v[20:21], 0, vcc
	v_pk_mul_f32 v[22:23], v[12:13], v[14:15]
	global_load_dwordx2 v[164:165], v[18:19], off
	v_lshl_add_u64 v[18:19], v[18:19], 0, vcc
	v_pk_fma_f32 v[86:87], v[10:11], v[14:15], v[22:23] op_sel:[0,0,1] op_sel_hi:[1,1,0] neg_lo:[0,0,1] neg_hi:[0,0,1]
	v_pk_fma_f32 v[14:15], v[10:11], v[14:15], v[22:23] op_sel:[0,0,1] op_sel_hi:[1,1,0]
	s_nop 0
	v_mov_b32_e32 v87, v15
	s_waitcnt vmcnt(33)
	v_pk_add_f32 v[14:15], v[86:87], v[104:105]
	global_store_dwordx2 v[20:21], v[14:15], off
	v_lshl_add_u64 v[20:21], v[20:21], 0, vcc
	v_pk_mul_f32 v[22:23], v[12:13], v[14:15]
	global_load_dwordx2 v[166:167], v[18:19], off
	v_lshl_add_u64 v[18:19], v[18:19], 0, vcc
	v_pk_fma_f32 v[86:87], v[10:11], v[14:15], v[22:23] op_sel:[0,0,1] op_sel_hi:[1,1,0] neg_lo:[0,0,1] neg_hi:[0,0,1]
	v_pk_fma_f32 v[14:15], v[10:11], v[14:15], v[22:23] op_sel:[0,0,1] op_sel_hi:[1,1,0]
	s_nop 0
	v_mov_b32_e32 v87, v15
	s_waitcnt vmcnt(34)
	v_pk_add_f32 v[14:15], v[86:87], v[106:107]
	global_store_dwordx2 v[20:21], v[14:15], off
	v_lshl_add_u64 v[20:21], v[20:21], 0, vcc
	v_pk_mul_f32 v[22:23], v[12:13], v[14:15]
	global_load_dwordx2 v[168:169], v[18:19], off
	v_lshl_add_u64 v[18:19], v[18:19], 0, vcc
	v_pk_fma_f32 v[86:87], v[10:11], v[14:15], v[22:23] op_sel:[0,0,1] op_sel_hi:[1,1,0] neg_lo:[0,0,1] neg_hi:[0,0,1]
	v_pk_fma_f32 v[14:15], v[10:11], v[14:15], v[22:23] op_sel:[0,0,1] op_sel_hi:[1,1,0]
	s_nop 0
	v_mov_b32_e32 v87, v15
	s_waitcnt vmcnt(35)
	v_pk_add_f32 v[14:15], v[86:87], v[108:109]
	global_store_dwordx2 v[20:21], v[14:15], off
	v_lshl_add_u64 v[20:21], v[20:21], 0, vcc
	v_pk_mul_f32 v[22:23], v[12:13], v[14:15]
	global_load_dwordx2 v[170:171], v[18:19], off
	v_lshl_add_u64 v[18:19], v[18:19], 0, vcc
	v_pk_fma_f32 v[86:87], v[10:11], v[14:15], v[22:23] op_sel:[0,0,1] op_sel_hi:[1,1,0] neg_lo:[0,0,1] neg_hi:[0,0,1]
	v_pk_fma_f32 v[14:15], v[10:11], v[14:15], v[22:23] op_sel:[0,0,1] op_sel_hi:[1,1,0]
	s_nop 0
	v_mov_b32_e32 v87, v15
	s_waitcnt vmcnt(36)
	v_pk_add_f32 v[14:15], v[86:87], v[110:111]
	global_store_dwordx2 v[20:21], v[14:15], off
	v_lshl_add_u64 v[20:21], v[20:21], 0, vcc
	v_pk_mul_f32 v[22:23], v[12:13], v[14:15]
	global_load_dwordx2 v[172:173], v[18:19], off
	v_lshl_add_u64 v[18:19], v[18:19], 0, vcc
	v_pk_fma_f32 v[86:87], v[10:11], v[14:15], v[22:23] op_sel:[0,0,1] op_sel_hi:[1,1,0] neg_lo:[0,0,1] neg_hi:[0,0,1]
	v_pk_fma_f32 v[14:15], v[10:11], v[14:15], v[22:23] op_sel:[0,0,1] op_sel_hi:[1,1,0]
	s_nop 0
	v_mov_b32_e32 v87, v15
	s_waitcnt vmcnt(37)
	v_pk_add_f32 v[14:15], v[86:87], v[112:113]
	global_store_dwordx2 v[20:21], v[14:15], off
	v_lshl_add_u64 v[20:21], v[20:21], 0, vcc
	v_pk_mul_f32 v[22:23], v[12:13], v[14:15]
	global_load_dwordx2 v[174:175], v[18:19], off
	v_lshl_add_u64 v[18:19], v[18:19], 0, vcc
	v_pk_fma_f32 v[86:87], v[10:11], v[14:15], v[22:23] op_sel:[0,0,1] op_sel_hi:[1,1,0] neg_lo:[0,0,1] neg_hi:[0,0,1]
	v_pk_fma_f32 v[14:15], v[10:11], v[14:15], v[22:23] op_sel:[0,0,1] op_sel_hi:[1,1,0]
	s_nop 0
	v_mov_b32_e32 v87, v15
	s_waitcnt vmcnt(38)
	v_pk_add_f32 v[14:15], v[86:87], v[114:115]
	global_store_dwordx2 v[20:21], v[14:15], off
	v_lshl_add_u64 v[20:21], v[20:21], 0, vcc
	v_pk_mul_f32 v[22:23], v[12:13], v[14:15]
	global_load_dwordx2 v[176:177], v[18:19], off
	v_lshl_add_u64 v[18:19], v[18:19], 0, vcc
	v_pk_fma_f32 v[86:87], v[10:11], v[14:15], v[22:23] op_sel:[0,0,1] op_sel_hi:[1,1,0] neg_lo:[0,0,1] neg_hi:[0,0,1]
	v_pk_fma_f32 v[14:15], v[10:11], v[14:15], v[22:23] op_sel:[0,0,1] op_sel_hi:[1,1,0]
	s_nop 0
	v_mov_b32_e32 v87, v15
	s_waitcnt vmcnt(39)
	v_pk_add_f32 v[14:15], v[86:87], v[116:117]
	global_store_dwordx2 v[20:21], v[14:15], off
	v_lshl_add_u64 v[20:21], v[20:21], 0, vcc
	v_pk_mul_f32 v[22:23], v[12:13], v[14:15]
	global_load_dwordx2 v[178:179], v[18:19], off
	v_lshl_add_u64 v[18:19], v[18:19], 0, vcc
	v_pk_fma_f32 v[86:87], v[10:11], v[14:15], v[22:23] op_sel:[0,0,1] op_sel_hi:[1,1,0] neg_lo:[0,0,1] neg_hi:[0,0,1]
	v_pk_fma_f32 v[14:15], v[10:11], v[14:15], v[22:23] op_sel:[0,0,1] op_sel_hi:[1,1,0]
	s_nop 0
	v_mov_b32_e32 v87, v15
	s_waitcnt vmcnt(40)
	v_pk_add_f32 v[14:15], v[86:87], v[118:119]
	global_store_dwordx2 v[20:21], v[14:15], off
	v_lshl_add_u64 v[20:21], v[20:21], 0, vcc
	v_pk_mul_f32 v[22:23], v[12:13], v[14:15]
	global_load_dwordx2 v[180:181], v[18:19], off
	v_lshl_add_u64 v[18:19], v[18:19], 0, vcc
	v_pk_fma_f32 v[86:87], v[10:11], v[14:15], v[22:23] op_sel:[0,0,1] op_sel_hi:[1,1,0] neg_lo:[0,0,1] neg_hi:[0,0,1]
	v_pk_fma_f32 v[14:15], v[10:11], v[14:15], v[22:23] op_sel:[0,0,1] op_sel_hi:[1,1,0]
	s_nop 0
	v_mov_b32_e32 v87, v15
	s_waitcnt vmcnt(41)
	v_pk_add_f32 v[14:15], v[86:87], v[120:121]
	global_store_dwordx2 v[20:21], v[14:15], off
	v_lshl_add_u64 v[20:21], v[20:21], 0, vcc
	v_pk_mul_f32 v[22:23], v[12:13], v[14:15]
	global_load_dwordx2 v[182:183], v[18:19], off
	v_lshl_add_u64 v[18:19], v[18:19], 0, vcc
	v_pk_fma_f32 v[86:87], v[10:11], v[14:15], v[22:23] op_sel:[0,0,1] op_sel_hi:[1,1,0] neg_lo:[0,0,1] neg_hi:[0,0,1]
	v_pk_fma_f32 v[14:15], v[10:11], v[14:15], v[22:23] op_sel:[0,0,1] op_sel_hi:[1,1,0]
	s_nop 0
	v_mov_b32_e32 v87, v15
	s_waitcnt vmcnt(42)
	v_pk_add_f32 v[14:15], v[86:87], v[122:123]
	global_store_dwordx2 v[20:21], v[14:15], off
	v_lshl_add_u64 v[20:21], v[20:21], 0, vcc
	v_pk_mul_f32 v[22:23], v[12:13], v[14:15]
	global_load_dwordx2 v[184:185], v[18:19], off
	v_lshl_add_u64 v[18:19], v[18:19], 0, vcc
	v_pk_fma_f32 v[86:87], v[10:11], v[14:15], v[22:23] op_sel:[0,0,1] op_sel_hi:[1,1,0] neg_lo:[0,0,1] neg_hi:[0,0,1]
	v_pk_fma_f32 v[14:15], v[10:11], v[14:15], v[22:23] op_sel:[0,0,1] op_sel_hi:[1,1,0]
	s_nop 0
	v_mov_b32_e32 v87, v15
	s_waitcnt vmcnt(43)
	v_pk_add_f32 v[14:15], v[86:87], v[124:125]
	global_store_dwordx2 v[20:21], v[14:15], off
	v_lshl_add_u64 v[20:21], v[20:21], 0, vcc
	v_pk_mul_f32 v[22:23], v[12:13], v[14:15]
	global_load_dwordx2 v[186:187], v[18:19], off
	v_lshl_add_u64 v[18:19], v[18:19], 0, vcc
	v_pk_fma_f32 v[86:87], v[10:11], v[14:15], v[22:23] op_sel:[0,0,1] op_sel_hi:[1,1,0] neg_lo:[0,0,1] neg_hi:[0,0,1]
	v_pk_fma_f32 v[14:15], v[10:11], v[14:15], v[22:23] op_sel:[0,0,1] op_sel_hi:[1,1,0]
	s_nop 0
	v_mov_b32_e32 v87, v15
	s_waitcnt vmcnt(44)
	v_pk_add_f32 v[14:15], v[86:87], v[126:127]
	global_store_dwordx2 v[20:21], v[14:15], off
	v_lshl_add_u64 v[20:21], v[20:21], 0, vcc
	v_pk_mul_f32 v[22:23], v[12:13], v[14:15]
	global_load_dwordx2 v[188:189], v[18:19], off
	v_lshl_add_u64 v[18:19], v[18:19], 0, vcc
	v_pk_fma_f32 v[86:87], v[10:11], v[14:15], v[22:23] op_sel:[0,0,1] op_sel_hi:[1,1,0] neg_lo:[0,0,1] neg_hi:[0,0,1]
	v_pk_fma_f32 v[14:15], v[10:11], v[14:15], v[22:23] op_sel:[0,0,1] op_sel_hi:[1,1,0]
	s_nop 0
	v_mov_b32_e32 v87, v15
	s_waitcnt vmcnt(45)
	v_pk_add_f32 v[14:15], v[86:87], v[128:129]
	global_store_dwordx2 v[20:21], v[14:15], off
	v_lshl_add_u64 v[20:21], v[20:21], 0, vcc
	v_pk_mul_f32 v[22:23], v[12:13], v[14:15]
	global_load_dwordx2 v[190:191], v[18:19], off
	v_lshl_add_u64 v[18:19], v[18:19], 0, vcc
	v_pk_fma_f32 v[86:87], v[10:11], v[14:15], v[22:23] op_sel:[0,0,1] op_sel_hi:[1,1,0] neg_lo:[0,0,1] neg_hi:[0,0,1]
	v_pk_fma_f32 v[14:15], v[10:11], v[14:15], v[22:23] op_sel:[0,0,1] op_sel_hi:[1,1,0]
	s_nop 0
	v_mov_b32_e32 v87, v15
	s_waitcnt vmcnt(46)
	v_pk_add_f32 v[14:15], v[86:87], v[130:131]
	global_store_dwordx2 v[20:21], v[14:15], off
	v_lshl_add_u64 v[20:21], v[20:21], 0, vcc
	v_pk_mul_f32 v[22:23], v[12:13], v[14:15]
	global_load_dwordx2 v[192:193], v[18:19], off
	v_lshl_add_u64 v[18:19], v[18:19], 0, vcc
	v_pk_fma_f32 v[86:87], v[10:11], v[14:15], v[22:23] op_sel:[0,0,1] op_sel_hi:[1,1,0] neg_lo:[0,0,1] neg_hi:[0,0,1]
	v_pk_fma_f32 v[14:15], v[10:11], v[14:15], v[22:23] op_sel:[0,0,1] op_sel_hi:[1,1,0]
	s_nop 0
	v_mov_b32_e32 v87, v15
	s_waitcnt vmcnt(47)
	v_pk_add_f32 v[14:15], v[86:87], v[132:133]
	global_store_dwordx2 v[20:21], v[14:15], off
	v_lshl_add_u64 v[20:21], v[20:21], 0, vcc
	v_pk_mul_f32 v[22:23], v[12:13], v[14:15]
	global_load_dwordx2 v[194:195], v[18:19], off
	v_lshl_add_u64 v[18:19], v[18:19], 0, vcc
	v_pk_fma_f32 v[86:87], v[10:11], v[14:15], v[22:23] op_sel:[0,0,1] op_sel_hi:[1,1,0] neg_lo:[0,0,1] neg_hi:[0,0,1]
	v_pk_fma_f32 v[14:15], v[10:11], v[14:15], v[22:23] op_sel:[0,0,1] op_sel_hi:[1,1,0]
	s_nop 0
	v_mov_b32_e32 v87, v15
	s_waitcnt vmcnt(48)
	v_pk_add_f32 v[14:15], v[86:87], v[134:135]
	global_store_dwordx2 v[20:21], v[14:15], off
	v_lshl_add_u64 v[20:21], v[20:21], 0, vcc
	v_pk_mul_f32 v[22:23], v[12:13], v[14:15]
	global_load_dwordx2 v[196:197], v[18:19], off
	v_lshl_add_u64 v[18:19], v[18:19], 0, vcc
	v_pk_fma_f32 v[86:87], v[10:11], v[14:15], v[22:23] op_sel:[0,0,1] op_sel_hi:[1,1,0] neg_lo:[0,0,1] neg_hi:[0,0,1]
	v_pk_fma_f32 v[14:15], v[10:11], v[14:15], v[22:23] op_sel:[0,0,1] op_sel_hi:[1,1,0]
	s_nop 0
	v_mov_b32_e32 v87, v15
	s_waitcnt vmcnt(49)
	v_pk_add_f32 v[14:15], v[86:87], v[136:137]
	global_store_dwordx2 v[20:21], v[14:15], off
	v_lshl_add_u64 v[20:21], v[20:21], 0, vcc
	v_pk_mul_f32 v[22:23], v[12:13], v[14:15]
	global_load_dwordx2 v[198:199], v[18:19], off
	v_lshl_add_u64 v[18:19], v[18:19], 0, vcc
	v_pk_fma_f32 v[86:87], v[10:11], v[14:15], v[22:23] op_sel:[0,0,1] op_sel_hi:[1,1,0] neg_lo:[0,0,1] neg_hi:[0,0,1]
	v_pk_fma_f32 v[14:15], v[10:11], v[14:15], v[22:23] op_sel:[0,0,1] op_sel_hi:[1,1,0]
	s_nop 0
	v_mov_b32_e32 v87, v15
	s_waitcnt vmcnt(50)
	v_pk_add_f32 v[14:15], v[86:87], v[138:139]
	global_store_dwordx2 v[20:21], v[14:15], off
	v_lshl_add_u64 v[20:21], v[20:21], 0, vcc
	v_pk_mul_f32 v[22:23], v[12:13], v[14:15]
	global_load_dwordx2 v[200:201], v[18:19], off
	v_lshl_add_u64 v[18:19], v[18:19], 0, vcc
	v_pk_fma_f32 v[86:87], v[10:11], v[14:15], v[22:23] op_sel:[0,0,1] op_sel_hi:[1,1,0] neg_lo:[0,0,1] neg_hi:[0,0,1]
	v_pk_fma_f32 v[14:15], v[10:11], v[14:15], v[22:23] op_sel:[0,0,1] op_sel_hi:[1,1,0]
	s_nop 0
	v_mov_b32_e32 v87, v15
	s_waitcnt vmcnt(51)
	v_pk_add_f32 v[14:15], v[86:87], v[140:141]
	global_store_dwordx2 v[20:21], v[14:15], off
	v_lshl_add_u64 v[20:21], v[20:21], 0, vcc
	v_pk_mul_f32 v[22:23], v[12:13], v[14:15]
	global_load_dwordx2 v[202:203], v[18:19], off
	v_lshl_add_u64 v[18:19], v[18:19], 0, vcc
	v_pk_fma_f32 v[86:87], v[10:11], v[14:15], v[22:23] op_sel:[0,0,1] op_sel_hi:[1,1,0] neg_lo:[0,0,1] neg_hi:[0,0,1]
	v_pk_fma_f32 v[14:15], v[10:11], v[14:15], v[22:23] op_sel:[0,0,1] op_sel_hi:[1,1,0]
	s_nop 0
	v_mov_b32_e32 v87, v15
	s_waitcnt vmcnt(52)
	v_pk_add_f32 v[14:15], v[86:87], v[142:143]
	global_store_dwordx2 v[20:21], v[14:15], off
	v_lshl_add_u64 v[20:21], v[20:21], 0, vcc
	v_pk_mul_f32 v[22:23], v[12:13], v[14:15]
	global_load_dwordx2 v[204:205], v[18:19], off
	v_lshl_add_u64 v[18:19], v[18:19], 0, vcc
	v_pk_fma_f32 v[86:87], v[10:11], v[14:15], v[22:23] op_sel:[0,0,1] op_sel_hi:[1,1,0] neg_lo:[0,0,1] neg_hi:[0,0,1]
	v_pk_fma_f32 v[14:15], v[10:11], v[14:15], v[22:23] op_sel:[0,0,1] op_sel_hi:[1,1,0]
	s_nop 0
	v_mov_b32_e32 v87, v15
	s_waitcnt vmcnt(53)
	v_pk_add_f32 v[14:15], v[86:87], v[144:145]
	global_store_dwordx2 v[20:21], v[14:15], off
	v_lshl_add_u64 v[20:21], v[20:21], 0, vcc
	v_pk_mul_f32 v[22:23], v[12:13], v[14:15]
	global_load_dwordx2 v[206:207], v[18:19], off
	v_lshl_add_u64 v[18:19], v[18:19], 0, vcc
	v_pk_fma_f32 v[86:87], v[10:11], v[14:15], v[22:23] op_sel:[0,0,1] op_sel_hi:[1,1,0] neg_lo:[0,0,1] neg_hi:[0,0,1]
	v_pk_fma_f32 v[14:15], v[10:11], v[14:15], v[22:23] op_sel:[0,0,1] op_sel_hi:[1,1,0]
	s_nop 0
	v_mov_b32_e32 v87, v15
	s_waitcnt vmcnt(54)
	v_pk_add_f32 v[14:15], v[86:87], v[146:147]
	global_store_dwordx2 v[20:21], v[14:15], off
	v_lshl_add_u64 v[20:21], v[20:21], 0, vcc
	v_pk_mul_f32 v[22:23], v[12:13], v[14:15]
	global_load_dwordx2 v[208:209], v[18:19], off
	v_lshl_add_u64 v[18:19], v[18:19], 0, vcc
	v_pk_fma_f32 v[86:87], v[10:11], v[14:15], v[22:23] op_sel:[0,0,1] op_sel_hi:[1,1,0] neg_lo:[0,0,1] neg_hi:[0,0,1]
	v_pk_fma_f32 v[14:15], v[10:11], v[14:15], v[22:23] op_sel:[0,0,1] op_sel_hi:[1,1,0]
	s_nop 0
	v_mov_b32_e32 v87, v15
	s_waitcnt vmcnt(55)
	v_pk_add_f32 v[14:15], v[86:87], v[148:149]
	global_store_dwordx2 v[20:21], v[14:15], off
	v_lshl_add_u64 v[20:21], v[20:21], 0, vcc
	v_pk_mul_f32 v[22:23], v[12:13], v[14:15]
	global_load_dwordx2 v[210:211], v[18:19], off
	v_lshl_add_u64 v[18:19], v[18:19], 0, vcc
	v_pk_fma_f32 v[86:87], v[10:11], v[14:15], v[22:23] op_sel:[0,0,1] op_sel_hi:[1,1,0] neg_lo:[0,0,1] neg_hi:[0,0,1]
	v_pk_fma_f32 v[14:15], v[10:11], v[14:15], v[22:23] op_sel:[0,0,1] op_sel_hi:[1,1,0]
	s_nop 0
	v_mov_b32_e32 v87, v15
	s_waitcnt vmcnt(56)
	v_pk_add_f32 v[14:15], v[86:87], v[150:151]
	global_store_dwordx2 v[20:21], v[14:15], off
	v_lshl_add_u64 v[20:21], v[20:21], 0, vcc
	v_pk_mul_f32 v[22:23], v[12:13], v[14:15]
	global_load_dwordx2 v[212:213], v[18:19], off
	v_lshl_add_u64 v[18:19], v[18:19], 0, vcc
	v_pk_fma_f32 v[86:87], v[10:11], v[14:15], v[22:23] op_sel:[0,0,1] op_sel_hi:[1,1,0] neg_lo:[0,0,1] neg_hi:[0,0,1]
	v_pk_fma_f32 v[14:15], v[10:11], v[14:15], v[22:23] op_sel:[0,0,1] op_sel_hi:[1,1,0]
	s_nop 0
	v_mov_b32_e32 v87, v15
	s_waitcnt vmcnt(57)
	v_pk_add_f32 v[14:15], v[86:87], v[152:153]
	global_store_dwordx2 v[20:21], v[14:15], off
	v_lshl_add_u64 v[20:21], v[20:21], 0, vcc
	v_pk_mul_f32 v[22:23], v[12:13], v[14:15]
	global_load_dwordx2 v[214:215], v[18:19], off
	v_lshl_add_u64 v[18:19], v[18:19], 0, vcc
	v_pk_fma_f32 v[86:87], v[10:11], v[14:15], v[22:23] op_sel:[0,0,1] op_sel_hi:[1,1,0] neg_lo:[0,0,1] neg_hi:[0,0,1]
	v_pk_fma_f32 v[14:15], v[10:11], v[14:15], v[22:23] op_sel:[0,0,1] op_sel_hi:[1,1,0]
	s_nop 0
	v_mov_b32_e32 v87, v15
	s_waitcnt vmcnt(58)
	v_pk_add_f32 v[14:15], v[86:87], v[154:155]
	global_store_dwordx2 v[20:21], v[14:15], off
	v_lshl_add_u64 v[20:21], v[20:21], 0, vcc
	v_pk_mul_f32 v[22:23], v[12:13], v[14:15]
	global_load_dwordx2 v[216:217], v[18:19], off
	v_lshl_add_u64 v[18:19], v[18:19], 0, vcc
	v_pk_fma_f32 v[86:87], v[10:11], v[14:15], v[22:23] op_sel:[0,0,1] op_sel_hi:[1,1,0] neg_lo:[0,0,1] neg_hi:[0,0,1]
	v_pk_fma_f32 v[14:15], v[10:11], v[14:15], v[22:23] op_sel:[0,0,1] op_sel_hi:[1,1,0]
	s_nop 0
	v_mov_b32_e32 v87, v15
	s_waitcnt vmcnt(59)
	v_pk_add_f32 v[14:15], v[86:87], v[156:157]
	global_store_dwordx2 v[20:21], v[14:15], off
	v_lshl_add_u64 v[20:21], v[20:21], 0, vcc
	v_pk_mul_f32 v[22:23], v[12:13], v[14:15]
	global_load_dwordx2 v[218:219], v[18:19], off
	v_lshl_add_u64 v[18:19], v[18:19], 0, vcc
	v_pk_fma_f32 v[86:87], v[10:11], v[14:15], v[22:23] op_sel:[0,0,1] op_sel_hi:[1,1,0] neg_lo:[0,0,1] neg_hi:[0,0,1]
	v_pk_fma_f32 v[14:15], v[10:11], v[14:15], v[22:23] op_sel:[0,0,1] op_sel_hi:[1,1,0]
	s_nop 0
	v_mov_b32_e32 v87, v15
	s_waitcnt vmcnt(60)
	v_pk_add_f32 v[14:15], v[86:87], v[158:159]
	global_store_dwordx2 v[20:21], v[14:15], off
	v_lshl_add_u64 v[20:21], v[20:21], 0, vcc
	v_pk_mul_f32 v[22:23], v[12:13], v[14:15]
	global_load_dwordx2 v[220:221], v[18:19], off
	v_lshl_add_u64 v[18:19], v[18:19], 0, vcc
	v_pk_fma_f32 v[86:87], v[10:11], v[14:15], v[22:23] op_sel:[0,0,1] op_sel_hi:[1,1,0] neg_lo:[0,0,1] neg_hi:[0,0,1]
	v_pk_fma_f32 v[14:15], v[10:11], v[14:15], v[22:23] op_sel:[0,0,1] op_sel_hi:[1,1,0]
	s_nop 0
	v_mov_b32_e32 v87, v15
	s_waitcnt vmcnt(60)
	v_pk_add_f32 v[14:15], v[86:87], v[160:161]
	global_store_dwordx2 v[20:21], v[14:15], off
	v_lshl_add_u64 v[20:21], v[20:21], 0, vcc
	v_pk_mul_f32 v[22:23], v[12:13], v[14:15]
	global_load_dwordx2 v[222:223], v[18:19], off
	v_lshl_add_u64 v[18:19], v[18:19], 0, vcc
	v_pk_fma_f32 v[86:87], v[10:11], v[14:15], v[22:23] op_sel:[0,0,1] op_sel_hi:[1,1,0] neg_lo:[0,0,1] neg_hi:[0,0,1]
	v_pk_fma_f32 v[14:15], v[10:11], v[14:15], v[22:23] op_sel:[0,0,1] op_sel_hi:[1,1,0]
	s_nop 0
	v_mov_b32_e32 v87, v15
	s_waitcnt vmcnt(60)
	v_pk_add_f32 v[14:15], v[86:87], v[162:163]
	global_store_dwordx2 v[20:21], v[14:15], off
	v_lshl_add_u64 v[20:21], v[20:21], 0, vcc
	v_pk_mul_f32 v[22:23], v[12:13], v[14:15]
	global_load_dwordx2 v[224:225], v[18:19], off
	v_lshl_add_u64 v[18:19], v[18:19], 0, vcc
	v_pk_fma_f32 v[86:87], v[10:11], v[14:15], v[22:23] op_sel:[0,0,1] op_sel_hi:[1,1,0] neg_lo:[0,0,1] neg_hi:[0,0,1]
	v_pk_fma_f32 v[14:15], v[10:11], v[14:15], v[22:23] op_sel:[0,0,1] op_sel_hi:[1,1,0]
	s_nop 0
	v_mov_b32_e32 v87, v15
	s_waitcnt vmcnt(60)
	v_pk_add_f32 v[14:15], v[86:87], v[164:165]
	global_store_dwordx2 v[20:21], v[14:15], off
	v_lshl_add_u64 v[20:21], v[20:21], 0, vcc
	v_pk_mul_f32 v[22:23], v[12:13], v[14:15]
	global_load_dwordx2 v[226:227], v[18:19], off
	v_lshl_add_u64 v[18:19], v[18:19], 0, vcc
	v_pk_fma_f32 v[86:87], v[10:11], v[14:15], v[22:23] op_sel:[0,0,1] op_sel_hi:[1,1,0] neg_lo:[0,0,1] neg_hi:[0,0,1]
	v_pk_fma_f32 v[14:15], v[10:11], v[14:15], v[22:23] op_sel:[0,0,1] op_sel_hi:[1,1,0]
	s_nop 0
	v_mov_b32_e32 v87, v15
	s_waitcnt vmcnt(60)
	v_pk_add_f32 v[14:15], v[86:87], v[166:167]
	global_store_dwordx2 v[20:21], v[14:15], off
	v_lshl_add_u64 v[20:21], v[20:21], 0, vcc
	v_pk_mul_f32 v[22:23], v[12:13], v[14:15]
	v_pk_fma_f32 v[86:87], v[10:11], v[14:15], v[22:23] op_sel:[0,0,1] op_sel_hi:[1,1,0] neg_lo:[0,0,1] neg_hi:[0,0,1]
	v_pk_fma_f32 v[14:15], v[10:11], v[14:15], v[22:23] op_sel:[0,0,1] op_sel_hi:[1,1,0]
	s_nop 0
	v_mov_b32_e32 v87, v15
	s_waitcnt vmcnt(59)
	v_pk_add_f32 v[14:15], v[86:87], v[168:169]
	global_store_dwordx2 v[20:21], v[14:15], off
	v_lshl_add_u64 v[20:21], v[20:21], 0, vcc
	v_pk_mul_f32 v[22:23], v[12:13], v[14:15]
	v_pk_fma_f32 v[86:87], v[10:11], v[14:15], v[22:23] op_sel:[0,0,1] op_sel_hi:[1,1,0] neg_lo:[0,0,1] neg_hi:[0,0,1]
	v_pk_fma_f32 v[14:15], v[10:11], v[14:15], v[22:23] op_sel:[0,0,1] op_sel_hi:[1,1,0]
	s_nop 0
	v_mov_b32_e32 v87, v15
	s_waitcnt vmcnt(58)
	v_pk_add_f32 v[14:15], v[86:87], v[170:171]
	global_store_dwordx2 v[20:21], v[14:15], off
	v_lshl_add_u64 v[20:21], v[20:21], 0, vcc
	v_pk_mul_f32 v[22:23], v[12:13], v[14:15]
	v_pk_fma_f32 v[86:87], v[10:11], v[14:15], v[22:23] op_sel:[0,0,1] op_sel_hi:[1,1,0] neg_lo:[0,0,1] neg_hi:[0,0,1]
	v_pk_fma_f32 v[14:15], v[10:11], v[14:15], v[22:23] op_sel:[0,0,1] op_sel_hi:[1,1,0]
	s_nop 0
	v_mov_b32_e32 v87, v15
	s_waitcnt vmcnt(57)
	v_pk_add_f32 v[14:15], v[86:87], v[172:173]
	global_store_dwordx2 v[20:21], v[14:15], off
	v_lshl_add_u64 v[20:21], v[20:21], 0, vcc
	v_pk_mul_f32 v[22:23], v[12:13], v[14:15]
	v_pk_fma_f32 v[86:87], v[10:11], v[14:15], v[22:23] op_sel:[0,0,1] op_sel_hi:[1,1,0] neg_lo:[0,0,1] neg_hi:[0,0,1]
	v_pk_fma_f32 v[14:15], v[10:11], v[14:15], v[22:23] op_sel:[0,0,1] op_sel_hi:[1,1,0]
	s_nop 0
	v_mov_b32_e32 v87, v15
	s_waitcnt vmcnt(56)
	v_pk_add_f32 v[14:15], v[86:87], v[174:175]
	global_store_dwordx2 v[20:21], v[14:15], off
	v_lshl_add_u64 v[20:21], v[20:21], 0, vcc
	v_pk_mul_f32 v[22:23], v[12:13], v[14:15]
	v_pk_fma_f32 v[86:87], v[10:11], v[14:15], v[22:23] op_sel:[0,0,1] op_sel_hi:[1,1,0] neg_lo:[0,0,1] neg_hi:[0,0,1]
	v_pk_fma_f32 v[14:15], v[10:11], v[14:15], v[22:23] op_sel:[0,0,1] op_sel_hi:[1,1,0]
	s_nop 0
	v_mov_b32_e32 v87, v15
	s_waitcnt vmcnt(55)
	v_pk_add_f32 v[14:15], v[86:87], v[176:177]
	global_store_dwordx2 v[20:21], v[14:15], off
	v_lshl_add_u64 v[20:21], v[20:21], 0, vcc
	v_pk_mul_f32 v[22:23], v[12:13], v[14:15]
	v_pk_fma_f32 v[86:87], v[10:11], v[14:15], v[22:23] op_sel:[0,0,1] op_sel_hi:[1,1,0] neg_lo:[0,0,1] neg_hi:[0,0,1]
	v_pk_fma_f32 v[14:15], v[10:11], v[14:15], v[22:23] op_sel:[0,0,1] op_sel_hi:[1,1,0]
	s_nop 0
	v_mov_b32_e32 v87, v15
	s_waitcnt vmcnt(54)
	v_pk_add_f32 v[14:15], v[86:87], v[178:179]
	global_store_dwordx2 v[20:21], v[14:15], off
	v_lshl_add_u64 v[20:21], v[20:21], 0, vcc
	v_pk_mul_f32 v[22:23], v[12:13], v[14:15]
	v_pk_fma_f32 v[86:87], v[10:11], v[14:15], v[22:23] op_sel:[0,0,1] op_sel_hi:[1,1,0] neg_lo:[0,0,1] neg_hi:[0,0,1]
	v_pk_fma_f32 v[14:15], v[10:11], v[14:15], v[22:23] op_sel:[0,0,1] op_sel_hi:[1,1,0]
	s_nop 0
	v_mov_b32_e32 v87, v15
	s_waitcnt vmcnt(53)
	v_pk_add_f32 v[14:15], v[86:87], v[180:181]
	global_store_dwordx2 v[20:21], v[14:15], off
	v_lshl_add_u64 v[20:21], v[20:21], 0, vcc
	v_pk_mul_f32 v[22:23], v[12:13], v[14:15]
	v_pk_fma_f32 v[86:87], v[10:11], v[14:15], v[22:23] op_sel:[0,0,1] op_sel_hi:[1,1,0] neg_lo:[0,0,1] neg_hi:[0,0,1]
	v_pk_fma_f32 v[14:15], v[10:11], v[14:15], v[22:23] op_sel:[0,0,1] op_sel_hi:[1,1,0]
	s_nop 0
	v_mov_b32_e32 v87, v15
	s_waitcnt vmcnt(52)
	v_pk_add_f32 v[14:15], v[86:87], v[182:183]
	global_store_dwordx2 v[20:21], v[14:15], off
	v_lshl_add_u64 v[20:21], v[20:21], 0, vcc
	v_pk_mul_f32 v[22:23], v[12:13], v[14:15]
	v_pk_fma_f32 v[86:87], v[10:11], v[14:15], v[22:23] op_sel:[0,0,1] op_sel_hi:[1,1,0] neg_lo:[0,0,1] neg_hi:[0,0,1]
	v_pk_fma_f32 v[14:15], v[10:11], v[14:15], v[22:23] op_sel:[0,0,1] op_sel_hi:[1,1,0]
	s_nop 0
	v_mov_b32_e32 v87, v15
	s_waitcnt vmcnt(51)
	v_pk_add_f32 v[14:15], v[86:87], v[184:185]
	global_store_dwordx2 v[20:21], v[14:15], off
	v_lshl_add_u64 v[20:21], v[20:21], 0, vcc
	v_pk_mul_f32 v[22:23], v[12:13], v[14:15]
	v_pk_fma_f32 v[86:87], v[10:11], v[14:15], v[22:23] op_sel:[0,0,1] op_sel_hi:[1,1,0] neg_lo:[0,0,1] neg_hi:[0,0,1]
	v_pk_fma_f32 v[14:15], v[10:11], v[14:15], v[22:23] op_sel:[0,0,1] op_sel_hi:[1,1,0]
	s_nop 0
	v_mov_b32_e32 v87, v15
	s_waitcnt vmcnt(50)
	v_pk_add_f32 v[14:15], v[86:87], v[186:187]
	global_store_dwordx2 v[20:21], v[14:15], off
	v_lshl_add_u64 v[20:21], v[20:21], 0, vcc
	v_pk_mul_f32 v[22:23], v[12:13], v[14:15]
	v_pk_fma_f32 v[86:87], v[10:11], v[14:15], v[22:23] op_sel:[0,0,1] op_sel_hi:[1,1,0] neg_lo:[0,0,1] neg_hi:[0,0,1]
	v_pk_fma_f32 v[14:15], v[10:11], v[14:15], v[22:23] op_sel:[0,0,1] op_sel_hi:[1,1,0]
	s_nop 0
	v_mov_b32_e32 v87, v15
	s_waitcnt vmcnt(49)
	v_pk_add_f32 v[14:15], v[86:87], v[188:189]
	global_store_dwordx2 v[20:21], v[14:15], off
	v_lshl_add_u64 v[20:21], v[20:21], 0, vcc
	v_pk_mul_f32 v[22:23], v[12:13], v[14:15]
	v_pk_fma_f32 v[86:87], v[10:11], v[14:15], v[22:23] op_sel:[0,0,1] op_sel_hi:[1,1,0] neg_lo:[0,0,1] neg_hi:[0,0,1]
	v_pk_fma_f32 v[14:15], v[10:11], v[14:15], v[22:23] op_sel:[0,0,1] op_sel_hi:[1,1,0]
	s_nop 0
	v_mov_b32_e32 v87, v15
	s_waitcnt vmcnt(48)
	v_pk_add_f32 v[14:15], v[86:87], v[190:191]
	global_store_dwordx2 v[20:21], v[14:15], off
	v_lshl_add_u64 v[20:21], v[20:21], 0, vcc
	v_pk_mul_f32 v[22:23], v[12:13], v[14:15]
	v_pk_fma_f32 v[86:87], v[10:11], v[14:15], v[22:23] op_sel:[0,0,1] op_sel_hi:[1,1,0] neg_lo:[0,0,1] neg_hi:[0,0,1]
	v_pk_fma_f32 v[14:15], v[10:11], v[14:15], v[22:23] op_sel:[0,0,1] op_sel_hi:[1,1,0]
	s_nop 0
	v_mov_b32_e32 v87, v15
	s_waitcnt vmcnt(47)
	v_pk_add_f32 v[14:15], v[86:87], v[192:193]
	global_store_dwordx2 v[20:21], v[14:15], off
	v_lshl_add_u64 v[20:21], v[20:21], 0, vcc
	v_pk_mul_f32 v[22:23], v[12:13], v[14:15]
	v_pk_fma_f32 v[86:87], v[10:11], v[14:15], v[22:23] op_sel:[0,0,1] op_sel_hi:[1,1,0] neg_lo:[0,0,1] neg_hi:[0,0,1]
	v_pk_fma_f32 v[14:15], v[10:11], v[14:15], v[22:23] op_sel:[0,0,1] op_sel_hi:[1,1,0]
	s_nop 0
	v_mov_b32_e32 v87, v15
	s_waitcnt vmcnt(46)
	v_pk_add_f32 v[14:15], v[86:87], v[194:195]
	global_store_dwordx2 v[20:21], v[14:15], off
	v_lshl_add_u64 v[20:21], v[20:21], 0, vcc
	v_pk_mul_f32 v[22:23], v[12:13], v[14:15]
	v_pk_fma_f32 v[86:87], v[10:11], v[14:15], v[22:23] op_sel:[0,0,1] op_sel_hi:[1,1,0] neg_lo:[0,0,1] neg_hi:[0,0,1]
	v_pk_fma_f32 v[14:15], v[10:11], v[14:15], v[22:23] op_sel:[0,0,1] op_sel_hi:[1,1,0]
	s_nop 0
	v_mov_b32_e32 v87, v15
	s_waitcnt vmcnt(45)
	v_pk_add_f32 v[14:15], v[86:87], v[196:197]
	global_store_dwordx2 v[20:21], v[14:15], off
	v_lshl_add_u64 v[20:21], v[20:21], 0, vcc
	v_pk_mul_f32 v[22:23], v[12:13], v[14:15]
	v_pk_fma_f32 v[86:87], v[10:11], v[14:15], v[22:23] op_sel:[0,0,1] op_sel_hi:[1,1,0] neg_lo:[0,0,1] neg_hi:[0,0,1]
	v_pk_fma_f32 v[14:15], v[10:11], v[14:15], v[22:23] op_sel:[0,0,1] op_sel_hi:[1,1,0]
	s_nop 0
	v_mov_b32_e32 v87, v15
	s_waitcnt vmcnt(44)
	v_pk_add_f32 v[14:15], v[86:87], v[198:199]
	global_store_dwordx2 v[20:21], v[14:15], off
	v_lshl_add_u64 v[20:21], v[20:21], 0, vcc
	v_pk_mul_f32 v[22:23], v[12:13], v[14:15]
	v_pk_fma_f32 v[86:87], v[10:11], v[14:15], v[22:23] op_sel:[0,0,1] op_sel_hi:[1,1,0] neg_lo:[0,0,1] neg_hi:[0,0,1]
	v_pk_fma_f32 v[14:15], v[10:11], v[14:15], v[22:23] op_sel:[0,0,1] op_sel_hi:[1,1,0]
	s_nop 0
	v_mov_b32_e32 v87, v15
	s_waitcnt vmcnt(43)
	v_pk_add_f32 v[14:15], v[86:87], v[200:201]
	global_store_dwordx2 v[20:21], v[14:15], off
	v_lshl_add_u64 v[20:21], v[20:21], 0, vcc
	v_pk_mul_f32 v[22:23], v[12:13], v[14:15]
	v_pk_fma_f32 v[86:87], v[10:11], v[14:15], v[22:23] op_sel:[0,0,1] op_sel_hi:[1,1,0] neg_lo:[0,0,1] neg_hi:[0,0,1]
	v_pk_fma_f32 v[14:15], v[10:11], v[14:15], v[22:23] op_sel:[0,0,1] op_sel_hi:[1,1,0]
	s_nop 0
	v_mov_b32_e32 v87, v15
	s_waitcnt vmcnt(42)
	v_pk_add_f32 v[14:15], v[86:87], v[202:203]
	global_store_dwordx2 v[20:21], v[14:15], off
	v_lshl_add_u64 v[20:21], v[20:21], 0, vcc
	v_pk_mul_f32 v[22:23], v[12:13], v[14:15]
	v_pk_fma_f32 v[86:87], v[10:11], v[14:15], v[22:23] op_sel:[0,0,1] op_sel_hi:[1,1,0] neg_lo:[0,0,1] neg_hi:[0,0,1]
	v_pk_fma_f32 v[14:15], v[10:11], v[14:15], v[22:23] op_sel:[0,0,1] op_sel_hi:[1,1,0]
	s_nop 0
	v_mov_b32_e32 v87, v15
	s_waitcnt vmcnt(41)
	v_pk_add_f32 v[14:15], v[86:87], v[204:205]
	global_store_dwordx2 v[20:21], v[14:15], off
	v_lshl_add_u64 v[20:21], v[20:21], 0, vcc
	v_pk_mul_f32 v[22:23], v[12:13], v[14:15]
	v_pk_fma_f32 v[86:87], v[10:11], v[14:15], v[22:23] op_sel:[0,0,1] op_sel_hi:[1,1,0] neg_lo:[0,0,1] neg_hi:[0,0,1]
	v_pk_fma_f32 v[14:15], v[10:11], v[14:15], v[22:23] op_sel:[0,0,1] op_sel_hi:[1,1,0]
	s_nop 0
	v_mov_b32_e32 v87, v15
	s_waitcnt vmcnt(40)
	v_pk_add_f32 v[14:15], v[86:87], v[206:207]
	global_store_dwordx2 v[20:21], v[14:15], off
	v_lshl_add_u64 v[20:21], v[20:21], 0, vcc
	v_pk_mul_f32 v[22:23], v[12:13], v[14:15]
	v_pk_fma_f32 v[86:87], v[10:11], v[14:15], v[22:23] op_sel:[0,0,1] op_sel_hi:[1,1,0] neg_lo:[0,0,1] neg_hi:[0,0,1]
	v_pk_fma_f32 v[14:15], v[10:11], v[14:15], v[22:23] op_sel:[0,0,1] op_sel_hi:[1,1,0]
	s_nop 0
	v_mov_b32_e32 v87, v15
	s_waitcnt vmcnt(39)
	v_pk_add_f32 v[14:15], v[86:87], v[208:209]
	global_store_dwordx2 v[20:21], v[14:15], off
	v_lshl_add_u64 v[20:21], v[20:21], 0, vcc
	v_pk_mul_f32 v[22:23], v[12:13], v[14:15]
	v_pk_fma_f32 v[86:87], v[10:11], v[14:15], v[22:23] op_sel:[0,0,1] op_sel_hi:[1,1,0] neg_lo:[0,0,1] neg_hi:[0,0,1]
	v_pk_fma_f32 v[14:15], v[10:11], v[14:15], v[22:23] op_sel:[0,0,1] op_sel_hi:[1,1,0]
	s_nop 0
	v_mov_b32_e32 v87, v15
	s_waitcnt vmcnt(38)
	v_pk_add_f32 v[14:15], v[86:87], v[210:211]
	global_store_dwordx2 v[20:21], v[14:15], off
	v_lshl_add_u64 v[20:21], v[20:21], 0, vcc
	v_pk_mul_f32 v[22:23], v[12:13], v[14:15]
	v_pk_fma_f32 v[86:87], v[10:11], v[14:15], v[22:23] op_sel:[0,0,1] op_sel_hi:[1,1,0] neg_lo:[0,0,1] neg_hi:[0,0,1]
	v_pk_fma_f32 v[14:15], v[10:11], v[14:15], v[22:23] op_sel:[0,0,1] op_sel_hi:[1,1,0]
	s_nop 0
	v_mov_b32_e32 v87, v15
	s_waitcnt vmcnt(37)
	v_pk_add_f32 v[14:15], v[86:87], v[212:213]
	global_store_dwordx2 v[20:21], v[14:15], off
	v_lshl_add_u64 v[20:21], v[20:21], 0, vcc
	v_pk_mul_f32 v[22:23], v[12:13], v[14:15]
	v_pk_fma_f32 v[86:87], v[10:11], v[14:15], v[22:23] op_sel:[0,0,1] op_sel_hi:[1,1,0] neg_lo:[0,0,1] neg_hi:[0,0,1]
	v_pk_fma_f32 v[14:15], v[10:11], v[14:15], v[22:23] op_sel:[0,0,1] op_sel_hi:[1,1,0]
	s_nop 0
	v_mov_b32_e32 v87, v15
	s_waitcnt vmcnt(36)
	v_pk_add_f32 v[14:15], v[86:87], v[214:215]
	global_store_dwordx2 v[20:21], v[14:15], off
	v_lshl_add_u64 v[20:21], v[20:21], 0, vcc
	v_pk_mul_f32 v[22:23], v[12:13], v[14:15]
	v_pk_fma_f32 v[86:87], v[10:11], v[14:15], v[22:23] op_sel:[0,0,1] op_sel_hi:[1,1,0] neg_lo:[0,0,1] neg_hi:[0,0,1]
	v_pk_fma_f32 v[14:15], v[10:11], v[14:15], v[22:23] op_sel:[0,0,1] op_sel_hi:[1,1,0]
	s_nop 0
	v_mov_b32_e32 v87, v15
	s_waitcnt vmcnt(35)
	v_pk_add_f32 v[14:15], v[86:87], v[216:217]
	global_store_dwordx2 v[20:21], v[14:15], off
	v_lshl_add_u64 v[20:21], v[20:21], 0, vcc
	v_pk_mul_f32 v[22:23], v[12:13], v[14:15]
	v_pk_fma_f32 v[86:87], v[10:11], v[14:15], v[22:23] op_sel:[0,0,1] op_sel_hi:[1,1,0] neg_lo:[0,0,1] neg_hi:[0,0,1]
	v_pk_fma_f32 v[14:15], v[10:11], v[14:15], v[22:23] op_sel:[0,0,1] op_sel_hi:[1,1,0]
	s_nop 0
	v_mov_b32_e32 v87, v15
	s_waitcnt vmcnt(34)
	v_pk_add_f32 v[14:15], v[86:87], v[218:219]
	global_store_dwordx2 v[20:21], v[14:15], off
	v_lshl_add_u64 v[20:21], v[20:21], 0, vcc
	v_pk_mul_f32 v[22:23], v[12:13], v[14:15]
	v_pk_fma_f32 v[86:87], v[10:11], v[14:15], v[22:23] op_sel:[0,0,1] op_sel_hi:[1,1,0] neg_lo:[0,0,1] neg_hi:[0,0,1]
	v_pk_fma_f32 v[14:15], v[10:11], v[14:15], v[22:23] op_sel:[0,0,1] op_sel_hi:[1,1,0]
	s_nop 0
	v_mov_b32_e32 v87, v15
	s_waitcnt vmcnt(33)
	v_pk_add_f32 v[14:15], v[86:87], v[220:221]
	global_store_dwordx2 v[20:21], v[14:15], off
	v_lshl_add_u64 v[20:21], v[20:21], 0, vcc
	v_pk_mul_f32 v[22:23], v[12:13], v[14:15]
	v_pk_fma_f32 v[86:87], v[10:11], v[14:15], v[22:23] op_sel:[0,0,1] op_sel_hi:[1,1,0] neg_lo:[0,0,1] neg_hi:[0,0,1]
	v_pk_fma_f32 v[14:15], v[10:11], v[14:15], v[22:23] op_sel:[0,0,1] op_sel_hi:[1,1,0]
	s_nop 0
	v_mov_b32_e32 v87, v15
	s_waitcnt vmcnt(32)
	v_pk_add_f32 v[14:15], v[86:87], v[222:223]
	global_store_dwordx2 v[20:21], v[14:15], off
	v_lshl_add_u64 v[20:21], v[20:21], 0, vcc
	v_pk_mul_f32 v[22:23], v[12:13], v[14:15]
	v_pk_fma_f32 v[86:87], v[10:11], v[14:15], v[22:23] op_sel:[0,0,1] op_sel_hi:[1,1,0] neg_lo:[0,0,1] neg_hi:[0,0,1]
	v_pk_fma_f32 v[14:15], v[10:11], v[14:15], v[22:23] op_sel:[0,0,1] op_sel_hi:[1,1,0]
	s_nop 0
	v_mov_b32_e32 v87, v15
	s_waitcnt vmcnt(31)
	v_pk_add_f32 v[14:15], v[86:87], v[224:225]
	global_store_dwordx2 v[20:21], v[14:15], off
	v_lshl_add_u64 v[20:21], v[20:21], 0, vcc
	v_pk_mul_f32 v[22:23], v[12:13], v[14:15]
	v_pk_fma_f32 v[86:87], v[10:11], v[14:15], v[22:23] op_sel:[0,0,1] op_sel_hi:[1,1,0] neg_lo:[0,0,1] neg_hi:[0,0,1]
	v_pk_fma_f32 v[14:15], v[10:11], v[14:15], v[22:23] op_sel:[0,0,1] op_sel_hi:[1,1,0]
	s_nop 0
	v_mov_b32_e32 v87, v15
	s_waitcnt vmcnt(30)
	v_pk_add_f32 v[14:15], v[86:87], v[226:227]
	v_readlane_b32 s0, v254, 5
	s_nop 1
	v_add_u32_e32 v1, s0, v1
	s_movk_i32 s0, 0x1fff
	v_cmp_lt_i32_e32 vcc, s0, v1
	s_or_b64 s[30:31], vcc, s[30:31]
	s_andn2_b64 exec, exec, s[30:31]
	s_cbranch_execnz .LBB0_1651
	s_nop 0
	s_nop 0
	s_nop 0
	s_nop 0
	s_nop 0
	s_nop 0
.LBB0_1658:
	s_or_b64 exec, exec, s[28:29]
	s_waitcnt vmcnt(0)
	s_barrier
	s_mov_b64 s[0:1], exec
	v_readlane_b32 s10, v253, 53
	v_readlane_b32 s11, v253, 54
	v_readlane_b32 s44, v254, 47
	v_readlane_b32 s46, v254, 42
	v_readlane_b32 s72, v254, 12
	v_readlane_b32 s42, v254, 14
	v_readlane_b32 s84, v254, 40
	v_readlane_b32 s86, v254, 38
	s_and_b64 s[10:11], s[0:1], s[10:11]
	v_readlane_b32 s45, v254, 48
	v_readlane_b32 s47, v254, 43
	v_readlane_b32 s73, v254, 13
	v_readlane_b32 s43, v254, 15
	v_readlane_b32 s85, v254, 41
	v_readlane_b32 s87, v254, 39
	s_mov_b64 exec, s[10:11]
	s_cbranch_execz .LBB0_1710
	s_add_i32 s10, 0, 0x20000
	s_mov_b32 s30, s93
	v_mov_b32_e32 v1, s10
	s_waitcnt vmcnt(0) expcnt(0) lgkmcnt(0)
	ds_read_b32 v3, v1
	s_add_i32 s10, 0, 0x20004
	v_mov_b32_e32 v1, s10
	ds_read_b32 v1, v1
	s_waitcnt lgkmcnt(1)
	v_cmp_ne_u32_e32 vcc, 0, v3
	s_cbranch_vccnz .LBB0_1674
	s_mov_b32 s31, 1
	v_mov_b32_e32 v17, 0
	s_branch .LBB0_1662

.LBB0_1676:
	s_or_b64 exec, exec, s[12:13]
	v_cvt_f32_u32_e32 v5, v3
	s_waitcnt vmcnt(0)
	v_readfirstlane_b32 s10, v4
	v_sub_u32_e32 v4, 0, v3
	v_rcp_iflag_f32_e32 v5, v5
	v_add_u32_e32 v6, s10, v2
	v_mul_f32_e32 v5, 0x4f7ffffe, v5
	v_cvt_u32_f32_e32 v5, v5
	v_mul_lo_u32 v2, v4, v5
	v_mul_hi_u32 v2, v5, v2
	v_add_u32_e32 v2, v5, v2
	v_mul_hi_u32 v2, v6, v2
	v_mul_lo_u32 v4, v2, v3
	v_sub_u32_e32 v4, v6, v4
	v_add_u32_e32 v5, 1, v2
	v_cmp_ge_u32_e32 vcc, v4, v3
	s_nop 1
	v_cndmask_b32_e32 v2, v2, v5, vcc
	v_sub_u32_e32 v5, v4, v3
	v_cndmask_b32_e32 v4, v4, v5, vcc
	v_add_u32_e32 v5, 1, v2
	v_cmp_ge_u32_e32 vcc, v4, v3
	v_add_u32_e32 v4, 1, v6
	s_nop 0
	v_cndmask_b32_e32 v2, v2, v5, vcc
	v_mul_lo_u32 v5, v3, v2
	v_add_u32_e32 v3, v5, v3
	v_cmp_ne_u32_e32 vcc, v4, v3
	s_and_saveexec_b64 s[10:11], vcc
	s_xor_b64 s[10:11], exec, s[10:11]
	s_cbranch_execz .LBB0_1690
	s_add_i32 s12, s33, 0x900
	s_mov_b32 s13, 0
	s_lshl_b64 s[12:13], s[12:13], 2
	s_add_u32 s28, s62, 0xf71d500
	s_addc_u32 s29, s63, 0
	s_waitcnt lgkmcnt(0)
	v_mov_b32_e32 v1, 0
	global_load_dword v3, v1, s[28:29] sc1
	s_waitcnt vmcnt(0)
	v_cmp_eq_u32_e32 vcc, v3, v2
	s_and_saveexec_b64 s[12:13], vcc
	s_cbranch_execz .LBB0_1689
	s_mov_b32 s42, 1
	s_mov_b64 s[30:31], 0
	s_branch .LBB0_1680

.LBB0_1714:
	v_add_u32_e32 v140, s13, v100
	v_lshlrev_b32_e32 v142, 2, v112
	v_lshl_or_b32 v141, v140, 12, v142
	v_add_u32_e32 v143, 0x1000, v141
	v_add_u32_e32 v144, 0x3000, v141
	v_add_u32_e32 v145, 0x81000, v141
	v_add_u32_e32 v146, 0x83000, v141
	v_lshlrev_b32_e32 v147, 3, v140
	v_readlane_b32 s98, v253, 18
	v_readlane_b32 s99, v253, 19
	s_nop 4
	global_load_dword v138, v142, s[98:99]
	v_readlane_b32 s98, v253, 20
	v_readlane_b32 s99, v253, 21
	s_nop 4
	global_load_dword v139, v142, s[98:99]
	s_add_u32 s98, s62, 0xf000000
	s_addc_u32 s99, s63, 0
	global_load_dwordx4 v[148:151], v147, s[98:99]
	global_load_dwordx4 v[152:155], v147, s[98:99] offset:16
	global_load_dwordx4 v[244:247], v147, s[98:99] offset:1024
	global_load_dwordx4 v[248:251], v147, s[98:99] offset:1040
	global_load_dword v156, v143, s[66:67] offset:-4096
	global_load_dword v157, v143, s[66:67]
	global_load_dword v158, v144, s[66:67] offset:-4096
	global_load_dword v159, v144, s[66:67]
	global_load_dword v160, v145, s[66:67] offset:-4096
	global_load_dword v161, v145, s[66:67]
	global_load_dword v162, v146, s[66:67] offset:-4096
	global_load_dword v163, v146, s[66:67]
	s_waitcnt lgkmcnt(0)
	v_mfma_f32_32x32x16_bf16 v[164:179], v[18:21], v[64:67], 0
	v_mfma_f32_32x32x16_bf16 v[180:195], v[18:21], v[68:71], 0
	v_mfma_f32_32x32x16_bf16 v[196:211], v[18:21], v[72:75], 0
	v_mfma_f32_32x32x16_bf16 v[212:227], v[18:21], v[76:79], 0
	v_add_u32_e32 v228, 0x200, v129
	v_add_u32_e32 v229, 0x400, v129
	v_add_u32_e32 v230, 0x600, v129
	v_add_u32_e32 v231, 0x800, v129
	v_add_u32_e32 v232, 0xa00, v129
	v_add_u32_e32 v233, 0xc00, v129
	v_add_u32_e32 v234, 0xe00, v129
	s_nop 15
	s_nop 3
	v_fma_f32 v236, -v109, v49, v164
	v_fma_f32 v237, v109, v48, v180
	v_fma_f32 v238, -v111, v121, v196
	v_fma_f32 v239, v111, v120, v212
	v_fma_f32 v48, v108, v48, v236
	v_fma_f32 v49, v108, v49, v237
	v_fma_f32 v120, v110, v120, v238
	v_fma_f32 v121, v110, v121, v239
	v_cvt_pk_bf16_f32 v240, v48, v49
	v_cvt_pk_bf16_f32 v241, v120, v121
	ds_write2_b32 v129, v240, v241 offset0:0 offset1:32
	v_fma_f32 v236, -v109, v49, v165
	v_fma_f32 v237, v109, v48, v181
	v_fma_f32 v238, -v111, v121, v197
	v_fma_f32 v239, v111, v120, v213
	v_fma_f32 v48, v108, v48, v236
	v_fma_f32 v49, v108, v49, v237
	v_fma_f32 v120, v110, v120, v238
	v_fma_f32 v121, v110, v121, v239
	v_cvt_pk_bf16_f32 v242, v48, v49
	v_cvt_pk_bf16_f32 v243, v120, v121
	ds_write2_b32 v129, v242, v243 offset0:68 offset1:100
	v_fma_f32 v236, -v109, v49, v166
	v_fma_f32 v237, v109, v48, v182
	v_fma_f32 v238, -v111, v121, v198
	v_fma_f32 v239, v111, v120, v214
	v_fma_f32 v48, v108, v48, v236
	v_fma_f32 v49, v108, v49, v237
	v_fma_f32 v120, v110, v120, v238
	v_fma_f32 v121, v110, v121, v239
	v_cvt_pk_bf16_f32 v240, v48, v49
	v_cvt_pk_bf16_f32 v241, v120, v121
	ds_write2_b32 v228, v240, v241 offset0:8 offset1:40
	v_fma_f32 v236, -v109, v49, v167
	v_fma_f32 v237, v109, v48, v183
	v_fma_f32 v238, -v111, v121, v199
	v_fma_f32 v239, v111, v120, v215
	v_fma_f32 v48, v108, v48, v236
	v_fma_f32 v49, v108, v49, v237
	v_fma_f32 v120, v110, v120, v238
	v_fma_f32 v121, v110, v121, v239
	v_cvt_pk_bf16_f32 v242, v48, v49
	v_cvt_pk_bf16_f32 v243, v120, v121
	ds_write2_b32 v228, v242, v243 offset0:76 offset1:108
	v_fma_f32 v236, -v109, v49, v168
	v_fma_f32 v237, v109, v48, v184
	v_fma_f32 v238, -v111, v121, v200
	v_fma_f32 v239, v111, v120, v216
	v_fma_f32 v48, v108, v48, v236
	v_fma_f32 v49, v108, v49, v237
	v_fma_f32 v120, v110, v120, v238
	v_fma_f32 v121, v110, v121, v239
	v_cvt_pk_bf16_f32 v240, v48, v49
	v_cvt_pk_bf16_f32 v241, v120, v121
	ds_write2_b32 v229, v240, v241 offset0:16 offset1:48
	v_fma_f32 v236, -v109, v49, v169
	v_fma_f32 v237, v109, v48, v185
	v_fma_f32 v238, -v111, v121, v201
	v_fma_f32 v239, v111, v120, v217
	v_fma_f32 v48, v108, v48, v236
	v_fma_f32 v49, v108, v49, v237
	v_fma_f32 v120, v110, v120, v238
	v_fma_f32 v121, v110, v121, v239
	v_cvt_pk_bf16_f32 v242, v48, v49
	v_cvt_pk_bf16_f32 v243, v120, v121
	ds_write2_b32 v229, v242, v243 offset0:84 offset1:116
	v_fma_f32 v236, -v109, v49, v170
	v_fma_f32 v237, v109, v48, v186
	v_fma_f32 v238, -v111, v121, v202
	v_fma_f32 v239, v111, v120, v218
	v_fma_f32 v48, v108, v48, v236
	v_fma_f32 v49, v108, v49, v237
	v_fma_f32 v120, v110, v120, v238
	v_fma_f32 v121, v110, v121, v239
	v_cvt_pk_bf16_f32 v240, v48, v49
	v_cvt_pk_bf16_f32 v241, v120, v121
	ds_write2_b32 v230, v240, v241 offset0:24 offset1:56
	v_fma_f32 v236, -v109, v49, v171
	v_fma_f32 v237, v109, v48, v187
	v_fma_f32 v238, -v111, v121, v203
	v_fma_f32 v239, v111, v120, v219
	v_fma_f32 v48, v108, v48, v236
	v_fma_f32 v49, v108, v49, v237
	v_fma_f32 v120, v110, v120, v238
	v_fma_f32 v121, v110, v121, v239
	v_cvt_pk_bf16_f32 v242, v48, v49
	v_cvt_pk_bf16_f32 v243, v120, v121
	ds_write2_b32 v230, v242, v243 offset0:92 offset1:124
	v_fma_f32 v236, -v109, v49, v172
	v_fma_f32 v237, v109, v48, v188
	v_fma_f32 v238, -v111, v121, v204
	v_fma_f32 v239, v111, v120, v220
	v_fma_f32 v48, v108, v48, v236
	v_fma_f32 v49, v108, v49, v237
	v_fma_f32 v120, v110, v120, v238
	v_fma_f32 v121, v110, v121, v239
	v_cvt_pk_bf16_f32 v240, v48, v49
	v_cvt_pk_bf16_f32 v241, v120, v121
	ds_write2_b32 v231, v240, v241 offset0:32 offset1:64
	v_fma_f32 v236, -v109, v49, v173
	v_fma_f32 v237, v109, v48, v189
	v_fma_f32 v238, -v111, v121, v205
	v_fma_f32 v239, v111, v120, v221
	v_fma_f32 v48, v108, v48, v236
	v_fma_f32 v49, v108, v49, v237
	v_fma_f32 v120, v110, v120, v238
	v_fma_f32 v121, v110, v121, v239
	v_cvt_pk_bf16_f32 v242, v48, v49
	v_cvt_pk_bf16_f32 v243, v120, v121
	ds_write2_b32 v231, v242, v243 offset0:100 offset1:132
	v_fma_f32 v236, -v109, v49, v174
	v_fma_f32 v237, v109, v48, v190
	v_fma_f32 v238, -v111, v121, v206
	v_fma_f32 v239, v111, v120, v222
	v_fma_f32 v48, v108, v48, v236
	v_fma_f32 v49, v108, v49, v237
	v_fma_f32 v120, v110, v120, v238
	v_fma_f32 v121, v110, v121, v239
	v_cvt_pk_bf16_f32 v240, v48, v49
	v_cvt_pk_bf16_f32 v241, v120, v121
	ds_write2_b32 v232, v240, v241 offset0:40 offset1:72
	v_fma_f32 v236, -v109, v49, v175
	v_fma_f32 v237, v109, v48, v191
	v_fma_f32 v238, -v111, v121, v207
	v_fma_f32 v239, v111, v120, v223
	v_fma_f32 v48, v108, v48, v236
	v_fma_f32 v49, v108, v49, v237
	v_fma_f32 v120, v110, v120, v238
	v_fma_f32 v121, v110, v121, v239
	v_cvt_pk_bf16_f32 v242, v48, v49
	v_cvt_pk_bf16_f32 v243, v120, v121
	ds_write2_b32 v232, v242, v243 offset0:108 offset1:140
	v_fma_f32 v236, -v109, v49, v176
	v_fma_f32 v237, v109, v48, v192
	v_fma_f32 v238, -v111, v121, v208
	v_fma_f32 v239, v111, v120, v224
	v_fma_f32 v48, v108, v48, v236
	v_fma_f32 v49, v108, v49, v237
	v_fma_f32 v120, v110, v120, v238
	v_fma_f32 v121, v110, v121, v239
	v_cvt_pk_bf16_f32 v240, v48, v49
	v_cvt_pk_bf16_f32 v241, v120, v121
	ds_write2_b32 v233, v240, v241 offset0:48 offset1:80
	v_fma_f32 v236, -v109, v49, v177
	v_fma_f32 v237, v109, v48, v193
	v_fma_f32 v238, -v111, v121, v209
	v_fma_f32 v239, v111, v120, v225
	v_fma_f32 v48, v108, v48, v236
	v_fma_f32 v49, v108, v49, v237
	v_fma_f32 v120, v110, v120, v238
	v_fma_f32 v121, v110, v121, v239
	v_cvt_pk_bf16_f32 v242, v48, v49
	v_cvt_pk_bf16_f32 v243, v120, v121
	ds_write2_b32 v233, v242, v243 offset0:116 offset1:148
	v_fma_f32 v236, -v109, v49, v178
	v_fma_f32 v237, v109, v48, v194
	v_fma_f32 v238, -v111, v121, v210
	v_fma_f32 v239, v111, v120, v226
	v_fma_f32 v48, v108, v48, v236
	v_fma_f32 v49, v108, v49, v237
	v_fma_f32 v120, v110, v120, v238
	v_fma_f32 v121, v110, v121, v239
	v_cvt_pk_bf16_f32 v240, v48, v49
	v_cvt_pk_bf16_f32 v241, v120, v121
	ds_write2_b32 v234, v240, v241 offset0:56 offset1:88
	v_fma_f32 v236, -v109, v49, v179
	v_fma_f32 v237, v109, v48, v195
	v_fma_f32 v238, -v111, v121, v211
	v_fma_f32 v239, v111, v120, v227
	v_fma_f32 v48, v108, v48, v236
	v_fma_f32 v49, v108, v49, v237
	v_fma_f32 v120, v110, v120, v238
	v_fma_f32 v121, v110, v121, v239
	v_cvt_pk_bf16_f32 v242, v48, v49
	v_cvt_pk_bf16_f32 v243, v120, v121
	ds_write2_b32 v234, v242, v243 offset0:124 offset1:156
	v_add_u32_e32 v14, s13, v100
	v_ashrrev_i32_e32 v15, 31, v14
	v_add_u32_e32 v10, 1, v14
	v_ashrrev_i32_e32 v11, 31, v10
	v_lshlrev_b64 v[18:19], 10, v[10:11]
	v_lshlrev_b64 v[16:17], 10, v[14:15]
	v_or_b32_e32 v16, v16, v112
	s_waitcnt lgkmcnt(0)
	s_nop 0
	s_nop 0
	s_nop 0
	s_nop 0
	s_nop 0
	s_nop 0
	s_nop 0
	s_nop 0
	s_nop 0
	s_nop 0
	v_lshl_add_u64 v[2:3], v[16:17], 2, s[66:67]
	ds_read_b128 v[2:5], v130
	ds_read_b128 v[6:9], v130 offset:64
	v_or_b32_e32 v18, v18, v112
	s_waitcnt lgkmcnt(1)
	v_mfma_f32_16x16x32_bf16 v[2:5], v[2:5], v[80:83], 0
	v_lshl_add_u64 v[10:11], v[18:19], 2, s[66:67]
	s_add_i32 s13, s13, 16
	s_waitcnt lgkmcnt(0)
	v_mfma_f32_16x16x32_bf16 v[2:5], v[6:9], v[84:87], v[2:5]
	ds_read_b128 v[6:9], v130 offset:128
	ds_read_b128 v[10:13], v130 offset:192
	s_cmpk_eq_i32 s13, 0x80
	s_waitcnt lgkmcnt(1)
	v_mfma_f32_16x16x32_bf16 v[2:5], v[6:9], v[88:91], v[2:5]
	v_add_u32_e32 v6, 2, v14
	v_ashrrev_i32_e32 v7, 31, v6
	v_lshlrev_b64 v[22:23], 10, v[6:7]
	v_or_b32_e32 v22, v22, v112
	v_lshl_add_u64 v[6:7], v[22:23], 2, s[66:67]
	v_add_u32_e32 v6, 3, v14
	v_ashrrev_i32_e32 v7, 31, v6
	v_lshlrev_b64 v[24:25], 10, v[6:7]
	v_or_b32_e32 v24, v24, v112
	v_lshl_add_u64 v[6:7], v[24:25], 2, s[66:67]
	v_add_u32_e32 v6, 0x80, v14
	s_waitcnt lgkmcnt(0)
	v_mfma_f32_16x16x32_bf16 v[2:5], v[10:13], v[92:95], v[2:5]
	v_ashrrev_i32_e32 v7, 31, v6
	v_add_u32_e32 v8, 0x81, v14
	v_add_u32_e32 v10, 0x82, v14
	v_add_u32_e32 v12, 0x83, v14
	v_lshlrev_b64 v[26:27], 10, v[6:7]
	v_ashrrev_i32_e32 v9, 31, v8
	v_ashrrev_i32_e32 v11, 31, v10
	v_ashrrev_i32_e32 v13, 31, v12
	v_or_b32_e32 v26, v26, v112
	v_lshlrev_b64 v[28:29], 10, v[8:9]
	v_lshlrev_b64 v[30:31], 10, v[10:11]
	v_lshlrev_b64 v[32:33], 10, v[12:13]
	v_lshl_add_u64 v[6:7], v[26:27], 2, s[66:67]
	v_or_b32_e32 v28, v28, v112
	v_or_b32_e32 v30, v30, v112
	v_or_b32_e32 v32, v32, v112
	v_lshl_add_u64 v[8:9], v[28:29], 2, s[66:67]
	v_lshl_add_u64 v[10:11], v[30:31], 2, s[66:67]
	v_lshl_add_u64 v[12:13], v[32:33], 2, s[66:67]
	ds_read_b128 v[10:13], v130 offset:4416
	s_waitcnt vmcnt(7)
	v_sub_f32_e32 v156, v156, v148
	v_mul_f32_e32 v156, v156, v149
	v_fma_f32 v156, v138, v156, v139
	v_fma_f32 v2, v131, v156, v2
	v_mul_f32_e32 v6, 0x3d372713, v2
	v_mul_f32_e32 v6, v2, v6
	v_fma_f32 v6, v2, v6, v2
	v_mul_f32_e32 v6, 0x3f4c422a, v6
	v_add_f32_e32 v6, v6, v6
	v_mul_f32_e32 v6, 0x3fb8aa3b, v6
	v_exp_f32_e32 v6, v6
	s_waitcnt vmcnt(6)
	v_sub_f32_e32 v157, v157, v150
	v_mul_f32_e32 v157, v157, v151
	v_fma_f32 v157, v138, v157, v139
	v_fma_f32 v7, v131, v157, v3
	v_mul_f32_e32 v3, 0x3d372713, v7
	v_mul_f32_e32 v3, v7, v3
	v_fma_f32 v3, v7, v3, v7
	v_add_f32_e32 v6, 1.0, v6
	v_mul_f32_e32 v3, 0x3f4c422a, v3
	v_rcp_f32_e32 v6, v6
	v_add_f32_e32 v3, v3, v3
	v_mul_f32_e32 v3, 0x3fb8aa3b, v3
	v_exp_f32_e32 v3, v3
	v_fma_f32 v6, v6, -2.0, 1.0
	v_mul_f32_e32 v2, 0.5, v2
	v_add_f32_e32 v6, 1.0, v6
	v_mul_f32_e32 v2, v2, v6
	v_add_f32_e32 v3, 1.0, v3
	v_rcp_f32_e32 v6, v3
	v_cvt_pk_bf16_f32 v8, v2, s0
	v_lshl_add_u64 v[2:3], v[16:17], 1, s[68:69]
	s_waitcnt vmcnt(5)
	v_sub_f32_e32 v158, v158, v152
	v_mul_f32_e32 v158, v158, v153
	v_fma_f32 v158, v138, v158, v139
	v_fma_f32 v4, v131, v158, v4
	global_store_short v[2:3], v8, off
	v_mul_f32_e32 v3, 0x3d372713, v4
	v_mul_f32_e32 v3, v4, v3
	v_fma_f32 v3, v4, v3, v4
	v_mul_f32_e32 v3, 0x3f4c422a, v3
	v_add_f32_e32 v3, v3, v3
	v_mul_f32_e32 v3, 0x3fb8aa3b, v3
	v_exp_f32_e32 v3, v3
	v_fma_f32 v2, v6, -2.0, 1.0
	v_mul_f32_e32 v6, 0.5, v7
	v_add_f32_e32 v2, 1.0, v2
	v_add_f32_e32 v3, 1.0, v3
	v_mul_f32_e32 v2, v6, v2
	v_rcp_f32_e32 v6, v3
	v_cvt_pk_bf16_f32 v7, v2, s0
	v_lshl_add_u64 v[2:3], v[18:19], 1, s[68:69]
	global_store_short v[2:3], v7, off
	v_fma_f32 v2, v6, -2.0, 1.0
	ds_read_b128 v[6:9], v130 offset:4352
	ds_read_b128 v[14:17], v130 offset:4480
	ds_read_b128 v[18:21], v130 offset:4544
	s_waitcnt lgkmcnt(2)
	v_mfma_f32_16x16x32_bf16 v[6:9], v[6:9], v[80:83], 0
	v_mul_f32_e32 v3, 0.5, v4
	v_add_f32_e32 v2, 1.0, v2
	s_waitcnt vmcnt(6)
	v_sub_f32_e32 v159, v159, v154
	v_mul_f32_e32 v159, v159, v155
	v_fma_f32 v159, v138, v159, v139
	v_fmac_f32_e32 v5, v131, v159
	v_mul_f32_e32 v2, v3, v2
	v_mul_f32_e32 v3, 0x3d372713, v5
	v_mfma_f32_16x16x32_bf16 v[6:9], v[10:13], v[84:87], v[6:9]
	v_mul_f32_e32 v3, v5, v3
	v_fma_f32 v3, v5, v3, v5
	v_mul_f32_e32 v3, 0x3f4c422a, v3
	v_add_f32_e32 v3, v3, v3
	s_waitcnt lgkmcnt(1)
	v_mfma_f32_16x16x32_bf16 v[6:9], v[14:17], v[88:91], v[6:9]
	v_mul_f32_e32 v3, 0x3fb8aa3b, v3
	v_exp_f32_e32 v3, v3
	v_cvt_pk_bf16_f32 v4, v2, s0
	s_waitcnt lgkmcnt(0)
	v_mfma_f32_16x16x32_bf16 v[6:9], v[18:21], v[92:95], v[6:9]
	v_mul_f32_e32 v5, 0.5, v5
	v_add_f32_e32 v2, 1.0, v3
	v_rcp_f32_e32 v10, v2
	v_lshl_add_u64 v[2:3], v[22:23], 1, s[68:69]
	global_store_short v[2:3], v4, off
	s_waitcnt vmcnt(6)
	s_nop 1
	v_sub_f32_e32 v160, v160, v244
	v_mul_f32_e32 v160, v160, v245
	v_fma_f32 v160, v138, v160, v139
	v_fma_f32 v4, v131, v160, v6
	v_mul_f32_e32 v3, 0x3d372713, v4
	v_mul_f32_e32 v3, v4, v3
	v_fma_f32 v3, v4, v3, v4
	v_mul_f32_e32 v3, 0x3f4c422a, v3
	v_add_f32_e32 v3, v3, v3
	v_mul_f32_e32 v3, 0x3fb8aa3b, v3
	v_exp_f32_e32 v3, v3
	v_fma_f32 v2, v10, -2.0, 1.0
	v_add_f32_e32 v2, 1.0, v2
	v_mul_f32_e32 v2, v5, v2
	v_add_f32_e32 v3, 1.0, v3
	v_rcp_f32_e32 v5, v3
	v_cvt_pk_bf16_f32 v6, v2, s0
	v_lshl_add_u64 v[2:3], v[24:25], 1, s[68:69]
	global_store_short v[2:3], v6, off
	v_fma_f32 v2, v5, -2.0, 1.0
	s_waitcnt vmcnt(6)
	v_sub_f32_e32 v161, v161, v246
	v_mul_f32_e32 v161, v161, v247
	v_fma_f32 v161, v138, v161, v139
	v_fma_f32 v5, v131, v161, v7
	v_mul_f32_e32 v3, 0x3d372713, v5
	v_mul_f32_e32 v3, v5, v3
	v_fma_f32 v3, v5, v3, v5
	v_mul_f32_e32 v3, 0x3f4c422a, v3
	v_add_f32_e32 v3, v3, v3
	v_mul_f32_e32 v3, 0x3fb8aa3b, v3
	v_exp_f32_e32 v3, v3
	v_mul_f32_e32 v4, 0.5, v4
	v_add_f32_e32 v2, 1.0, v2
	v_mul_f32_e32 v2, v4, v2
	v_add_f32_e32 v3, 1.0, v3
	v_rcp_f32_e32 v4, v3
	v_cvt_pk_bf16_f32 v6, v2, s0
	v_lshl_add_u64 v[2:3], v[26:27], 1, s[68:69]
	global_store_short v[2:3], v6, off
	v_fma_f32 v2, v4, -2.0, 1.0
	s_waitcnt vmcnt(6)
	v_sub_f32_e32 v162, v162, v248
	v_mul_f32_e32 v162, v162, v249
	v_fma_f32 v162, v138, v162, v139
	v_fma_f32 v4, v131, v162, v8
	v_mul_f32_e32 v3, 0x3d372713, v4
	v_mul_f32_e32 v3, v4, v3
	v_fma_f32 v3, v4, v3, v4
	v_mul_f32_e32 v3, 0x3f4c422a, v3
	v_add_f32_e32 v3, v3, v3
	v_mul_f32_e32 v3, 0x3fb8aa3b, v3
	v_exp_f32_e32 v3, v3
	v_mul_f32_e32 v5, 0.5, v5
	v_add_f32_e32 v2, 1.0, v2
	v_mul_f32_e32 v2, v5, v2
	v_add_f32_e32 v3, 1.0, v3
	v_rcp_f32_e32 v5, v3
	v_cvt_pk_bf16_f32 v6, v2, s0
	v_lshl_add_u64 v[2:3], v[28:29], 1, s[68:69]
	s_waitcnt vmcnt(5)
	v_sub_f32_e32 v163, v163, v250
	v_mul_f32_e32 v163, v163, v251
	v_fma_f32 v163, v138, v163, v139
	v_fmac_f32_e32 v9, v131, v163
	global_store_short v[2:3], v6, off
	v_mul_f32_e32 v3, 0x3d372713, v9
	v_mul_f32_e32 v3, v9, v3
	v_fma_f32 v3, v9, v3, v9
	v_mul_f32_e32 v3, 0x3f4c422a, v3
	v_add_f32_e32 v3, v3, v3
	v_mul_f32_e32 v3, 0x3fb8aa3b, v3
	v_exp_f32_e32 v3, v3
	v_fma_f32 v2, v5, -2.0, 1.0
	v_mul_f32_e32 v4, 0.5, v4
	v_add_f32_e32 v2, 1.0, v2
	v_add_f32_e32 v3, 1.0, v3
	v_mul_f32_e32 v2, v4, v2
	v_rcp_f32_e32 v4, v3
	v_cvt_pk_bf16_f32 v5, v2, s0
	v_lshl_add_u64 v[2:3], v[30:31], 1, s[68:69]
	global_store_short v[2:3], v5, off
	v_fma_f32 v2, v4, -2.0, 1.0
	v_mul_f32_e32 v3, 0.5, v9
	v_add_f32_e32 v2, 1.0, v2
	v_mul_f32_e32 v2, v3, v2
	v_mov_b64_e32 v[18:19], v[96:97]
	v_cvt_pk_bf16_f32 v4, v2, s0
	v_lshl_add_u64 v[2:3], v[32:33], 1, s[68:69]
	v_mov_b64_e32 v[20:21], v[98:99]
	global_store_short v[2:3], v4, off
	s_cbranch_scc1 .LBB0_1712

.LBB0_1736:
	s_or_b64 exec, exec, s[12:13]
	v_cvt_f32_u32_e32 v5, v3
	s_waitcnt vmcnt(0)
	v_readfirstlane_b32 s2, v4
	v_sub_u32_e32 v4, 0, v3
	v_rcp_iflag_f32_e32 v5, v5
	v_add_u32_e32 v6, s2, v2
	v_mul_f32_e32 v5, 0x4f7ffffe, v5
	v_cvt_u32_f32_e32 v5, v5
	v_mul_lo_u32 v2, v4, v5
	v_mul_hi_u32 v2, v5, v2
	v_add_u32_e32 v2, v5, v2
	v_mul_hi_u32 v2, v6, v2
	v_mul_lo_u32 v4, v2, v3
	v_sub_u32_e32 v4, v6, v4
	v_add_u32_e32 v5, 1, v2
	v_cmp_ge_u32_e32 vcc, v4, v3
	s_nop 1
	v_cndmask_b32_e32 v2, v2, v5, vcc
	v_sub_u32_e32 v5, v4, v3
	v_cndmask_b32_e32 v4, v4, v5, vcc
	v_add_u32_e32 v5, 1, v2
	v_cmp_ge_u32_e32 vcc, v4, v3
	v_add_u32_e32 v4, 1, v6
	s_nop 0
	v_cndmask_b32_e32 v2, v2, v5, vcc
	v_mul_lo_u32 v5, v3, v2
	v_add_u32_e32 v3, v5, v3
	v_cmp_ne_u32_e32 vcc, v4, v3
	s_and_saveexec_b64 s[2:3], vcc
	s_xor_b64 s[2:3], exec, s[2:3]
	s_cbranch_execz .LBB0_1750
	s_add_i32 s12, s33, 0x900
	s_mov_b32 s13, 0
	s_lshl_b64 s[12:13], s[12:13], 2
	s_add_u32 s24, s62, 0xf71d500
	s_addc_u32 s25, s63, 0
	s_waitcnt lgkmcnt(0)
	v_mov_b32_e32 v1, 0
	global_load_dword v3, v1, s[24:25] sc1
	s_waitcnt vmcnt(0)
	v_cmp_eq_u32_e32 vcc, v3, v2
	s_and_saveexec_b64 s[12:13], vcc
	s_cbranch_execz .LBB0_1749
	s_mov_b32 s38, 1
	s_mov_b64 s[26:27], 0
	s_branch .LBB0_1740

.LBB0_1806:
	s_or_b64 exec, exec, s[10:11]
	v_cvt_f32_u32_e32 v5, v3
	s_waitcnt vmcnt(0)
	v_readfirstlane_b32 s2, v4
	v_sub_u32_e32 v4, 0, v3
	v_rcp_iflag_f32_e32 v5, v5
	v_add_u32_e32 v6, s2, v2
	v_mul_f32_e32 v5, 0x4f7ffffe, v5
	v_cvt_u32_f32_e32 v5, v5
	v_mul_lo_u32 v2, v4, v5
	v_mul_hi_u32 v2, v5, v2
	v_add_u32_e32 v2, v5, v2
	v_mul_hi_u32 v2, v6, v2
	v_mul_lo_u32 v4, v2, v3
	v_sub_u32_e32 v4, v6, v4
	v_add_u32_e32 v5, 1, v2
	v_cmp_ge_u32_e32 vcc, v4, v3
	s_nop 1
	v_cndmask_b32_e32 v2, v2, v5, vcc
	v_sub_u32_e32 v5, v4, v3
	v_cndmask_b32_e32 v4, v4, v5, vcc
	v_add_u32_e32 v5, 1, v2
	v_cmp_ge_u32_e32 vcc, v4, v3
	v_add_u32_e32 v4, 1, v6
	s_nop 0
	v_cndmask_b32_e32 v2, v2, v5, vcc
	v_mul_lo_u32 v5, v3, v2
	v_add_u32_e32 v3, v5, v3
	v_cmp_ne_u32_e32 vcc, v4, v3
	s_and_saveexec_b64 s[2:3], vcc
	s_xor_b64 s[2:3], exec, s[2:3]
	s_cbranch_execz .LBB0_1820
	s_add_i32 s10, s33, 0x900
	s_mov_b32 s11, 0
	s_lshl_b64 s[10:11], s[10:11], 2
	s_add_u32 s12, s62, 0xf71d500
	s_addc_u32 s13, s63, 0
	s_waitcnt lgkmcnt(0)
	v_mov_b32_e32 v1, 0
	global_load_dword v3, v1, s[12:13] sc1
	s_waitcnt vmcnt(0)
	v_cmp_eq_u32_e32 vcc, v3, v2
	s_and_saveexec_b64 s[10:11], vcc
	s_cbranch_execz .LBB0_1819
	s_mov_b32 s34, 1
	s_mov_b64 s[22:23], 0
	s_branch .LBB0_1810

.LBB0_1870:
	s_or_b64 exec, exec, s[6:7]
	v_cvt_f32_u32_e32 v5, v3
	s_waitcnt vmcnt(0)
	v_readfirstlane_b32 s2, v4
	v_sub_u32_e32 v4, 0, v3
	v_rcp_iflag_f32_e32 v5, v5
	v_add_u32_e32 v6, s2, v2
	v_mul_f32_e32 v5, 0x4f7ffffe, v5
	v_cvt_u32_f32_e32 v5, v5
	v_mul_lo_u32 v2, v4, v5
	v_mul_hi_u32 v2, v5, v2
	v_add_u32_e32 v2, v5, v2
	v_mul_hi_u32 v2, v6, v2
	v_mul_lo_u32 v4, v2, v3
	v_sub_u32_e32 v4, v6, v4
	v_add_u32_e32 v5, 1, v2
	v_cmp_ge_u32_e32 vcc, v4, v3
	s_nop 1
	v_cndmask_b32_e32 v2, v2, v5, vcc
	v_sub_u32_e32 v5, v4, v3
	v_cndmask_b32_e32 v4, v4, v5, vcc
	v_add_u32_e32 v5, 1, v2
	v_cmp_ge_u32_e32 vcc, v4, v3
	v_add_u32_e32 v4, 1, v6
	s_nop 0
	v_cndmask_b32_e32 v2, v2, v5, vcc
	v_mul_lo_u32 v5, v3, v2
	v_add_u32_e32 v3, v5, v3
	v_cmp_ne_u32_e32 vcc, v4, v3
	s_and_saveexec_b64 s[2:3], vcc
	s_xor_b64 s[2:3], exec, s[2:3]
	s_cbranch_execz .LBB0_1884
	s_add_i32 s6, s28, 0x900
	s_mov_b32 s7, 0
	s_lshl_b64 s[6:7], s[6:7], 2
	s_add_u32 s8, s62, 0xf71d500
	s_addc_u32 s9, s63, 0
	s_waitcnt lgkmcnt(0)
	v_mov_b32_e32 v1, 0
	global_load_dword v3, v1, s[8:9] sc1
	s_waitcnt vmcnt(0)
	v_cmp_eq_u32_e32 vcc, v3, v2
	s_and_saveexec_b64 s[6:7], vcc
	s_cbranch_execz .LBB0_1883
	s_mov_b32 s29, 1
	s_mov_b64 s[10:11], 0
	s_branch .LBB0_1874

.LBB0_1948:
	s_or_b64 exec, exec, s[6:7]
	v_cvt_f32_u32_e32 v5, v3
	s_waitcnt vmcnt(0)
	v_readfirstlane_b32 s2, v4
	v_sub_u32_e32 v4, 0, v3
	v_rcp_iflag_f32_e32 v5, v5
	v_add_u32_e32 v6, s2, v2
	v_mul_f32_e32 v5, 0x4f7ffffe, v5
	v_cvt_u32_f32_e32 v5, v5
	v_mul_lo_u32 v2, v4, v5
	v_mul_hi_u32 v2, v5, v2
	v_add_u32_e32 v2, v5, v2
	v_mul_hi_u32 v2, v6, v2
	v_mul_lo_u32 v4, v2, v3
	v_sub_u32_e32 v4, v6, v4
	v_add_u32_e32 v5, 1, v2
	v_cmp_ge_u32_e32 vcc, v4, v3
	s_nop 1
	v_cndmask_b32_e32 v2, v2, v5, vcc
	v_sub_u32_e32 v5, v4, v3
	v_cndmask_b32_e32 v4, v4, v5, vcc
	v_add_u32_e32 v5, 1, v2
	v_cmp_ge_u32_e32 vcc, v4, v3
	v_add_u32_e32 v4, 1, v6
	s_nop 0
	v_cndmask_b32_e32 v2, v2, v5, vcc
	v_mul_lo_u32 v5, v3, v2
	v_add_u32_e32 v3, v5, v3
	v_cmp_ne_u32_e32 vcc, v4, v3
	s_and_saveexec_b64 s[2:3], vcc
	s_xor_b64 s[2:3], exec, s[2:3]
	s_cbranch_execz .LBB0_1962
	s_add_i32 s6, s24, 0x900
	s_mov_b32 s7, 0
	s_lshl_b64 s[6:7], s[6:7], 2
	s_add_u32 s8, s62, 0xf71d500
	s_addc_u32 s9, s63, 0
	s_waitcnt lgkmcnt(0)
	v_mov_b32_e32 v1, 0
	global_load_dword v3, v1, s[8:9] sc1
	s_waitcnt vmcnt(0)
	v_cmp_eq_u32_e32 vcc, v3, v2
	s_and_saveexec_b64 s[6:7], vcc
	s_cbranch_execz .LBB0_1961
	s_mov_b32 s25, 1
	s_mov_b64 s[10:11], 0
	s_branch .LBB0_1952

.LBB0_2018:
	s_or_b64 exec, exec, s[4:5]
	v_cvt_f32_u32_e32 v5, v3
	s_waitcnt vmcnt(0)
	v_readfirstlane_b32 s2, v4
	v_sub_u32_e32 v4, 0, v3
	v_rcp_iflag_f32_e32 v5, v5
	v_add_u32_e32 v6, s2, v2
	v_mul_f32_e32 v5, 0x4f7ffffe, v5
	v_cvt_u32_f32_e32 v5, v5
	v_mul_lo_u32 v2, v4, v5
	v_mul_hi_u32 v2, v5, v2
	v_add_u32_e32 v2, v5, v2
	v_mul_hi_u32 v2, v6, v2
	v_mul_lo_u32 v4, v2, v3
	v_sub_u32_e32 v4, v6, v4
	v_add_u32_e32 v5, 1, v2
	v_cmp_ge_u32_e32 vcc, v4, v3
	s_nop 1
	v_cndmask_b32_e32 v2, v2, v5, vcc
	v_sub_u32_e32 v5, v4, v3
	v_cndmask_b32_e32 v4, v4, v5, vcc
	v_add_u32_e32 v5, 1, v2
	v_cmp_ge_u32_e32 vcc, v4, v3
	v_add_u32_e32 v4, 1, v6
	s_nop 0
	v_cndmask_b32_e32 v2, v2, v5, vcc
	v_mul_lo_u32 v5, v3, v2
	v_add_u32_e32 v3, v5, v3
	v_cmp_ne_u32_e32 vcc, v4, v3
	s_and_saveexec_b64 s[2:3], vcc
	s_xor_b64 s[2:3], exec, s[2:3]
	s_cbranch_execz .LBB0_2032
	s_add_i32 s4, s20, 0x900
	s_mov_b32 s5, 0
	s_lshl_b64 s[4:5], s[4:5], 2
	s_add_u32 s6, s62, 0xf71d500
	s_addc_u32 s7, s63, 0
	s_waitcnt lgkmcnt(0)
	v_mov_b32_e32 v1, 0
	global_load_dword v3, v1, s[6:7] sc1
	s_waitcnt vmcnt(0)
	v_cmp_eq_u32_e32 vcc, v3, v2
	s_and_saveexec_b64 s[4:5], vcc
	s_cbranch_execz .LBB0_2031
	s_mov_b32 s21, 1
	s_mov_b64 s[8:9], 0
	s_branch .LBB0_2022
